# baseline (speedup 1.0000x reference)
; __device__ __forceinline__ void ph_out(const Params& p, int l, char* shm) {
;     ...
;     gemm_tile8(p.YMIX + (size_t)brow * DM, DM, W + (size_t)pn * 256 * DM, DM, DM, shm, [&](int r, int c, f32x4 v) {
;       const size_t o = (size_t)(brow + r) * DM + pn * 256 + c;
;       const f32x4 xo = *(const f32x4*)(xold + o);
;       *(f32x4*)(p.out + o) = xo + v;
;     });
.LBB0_46:
	v_add_u32_e32 v130, s8, v146
	v_lshrrev_b32_e32 v32, 2, v32
	v_ashrrev_i32_e32 v131, 31, v130
	s_lshl_b32 s6, s6, 8
	v_and_b32_e32 v32, 12, v32
	v_lshlrev_b64 v[132:133], 12, v[130:131]
	s_ashr_i32 s7, s6, 31
	v_lshl_or_b32 v32, s9, 5, v32
	v_lshl_add_u64 v[132:133], v[132:133], 0, s[6:7]
	v_or_b32_e32 v132, v132, v32
	v_lshlrev_b64 v[136:137], 2, v[132:133]
	v_lshl_add_u64 v[138:139], s[0:1], 0, v[136:137]
	global_load_dwordx4 v[132:135], v[138:139], off nt
	v_readlane_b32 s8, v246, 4
	v_readlane_b32 s20, v246, 16
	v_readlane_b32 s21, v246, 17
	v_readlane_b32 s14, v246, 10
	v_readlane_b32 s15, v246, 11
	v_lshl_add_u64 v[136:137], s[20:21], 0, v[136:137]
	v_readlane_b32 s15, v245, 24
	v_readlane_b32 s14, v245, 48
	v_readlane_b32 s9, v246, 5
	v_readlane_b32 s10, v246, 6
	v_readlane_b32 s11, v246, 7
	v_readlane_b32 s12, v246, 8
	v_readlane_b32 s13, v246, 9
	v_readlane_b32 s16, v246, 12
	v_readlane_b32 s17, v246, 13
	v_readlane_b32 s18, v246, 14
	v_readlane_b32 s19, v246, 15
	v_readlane_b32 s22, v246, 18
	v_readlane_b32 s23, v246, 19
	s_waitcnt vmcnt(0)
	v_pk_add_f32 v[128:129], v[128:129], v[134:135]
	v_pk_add_f32 v[126:127], v[126:127], v[132:133]
	global_store_dwordx4 v[136:137], v[126:129], off
	global_load_dwordx4 v[126:129], v[138:139], off offset:64 nt
	v_add_u32_e32 v132, 16, v130
	v_ashrrev_i32_e32 v133, 31, v132
	v_lshlrev_b64 v[132:133], 12, v[132:133]
	v_lshl_add_u64 v[132:133], v[132:133], 0, s[6:7]
	v_or_b32_e32 v132, v132, v32
	v_lshlrev_b64 v[132:133], 2, v[132:133]
	v_lshl_add_u64 v[134:135], s[0:1], 0, v[132:133]
	s_waitcnt vmcnt(0)
	v_pk_add_f32 v[124:125], v[124:125], v[128:129]
	v_pk_add_f32 v[122:123], v[122:123], v[126:127]
	global_store_dwordx4 v[136:137], v[122:125], off offset:64
	global_load_dwordx4 v[122:125], v[134:135], off nt
	v_lshl_add_u64 v[126:127], s[20:21], 0, v[132:133]
	s_waitcnt vmcnt(0)
	v_pk_add_f32 v[120:121], v[120:121], v[124:125]
	v_pk_add_f32 v[118:119], v[118:119], v[122:123]
	global_store_dwordx4 v[126:127], v[118:121], off
	global_load_dwordx4 v[118:121], v[134:135], off offset:64 nt
	v_add_u32_e32 v122, 32, v130
	v_ashrrev_i32_e32 v123, 31, v122
	v_lshlrev_b64 v[122:123], 12, v[122:123]
	v_lshl_add_u64 v[122:123], v[122:123], 0, s[6:7]
	v_or_b32_e32 v122, v122, v32
	v_lshlrev_b64 v[122:123], 2, v[122:123]
	v_lshl_add_u64 v[124:125], s[0:1], 0, v[122:123]
	s_waitcnt vmcnt(0)
	v_pk_add_f32 v[116:117], v[116:117], v[120:121]
	v_pk_add_f32 v[114:115], v[114:115], v[118:119]
	global_store_dwordx4 v[126:127], v[114:117], off offset:64
	global_load_dwordx4 v[114:117], v[124:125], off nt
	v_lshl_add_u64 v[118:119], s[20:21], 0, v[122:123]
	s_waitcnt vmcnt(0)
	v_pk_add_f32 v[112:113], v[112:113], v[116:117]
	v_pk_add_f32 v[110:111], v[110:111], v[114:115]
	global_store_dwordx4 v[118:119], v[110:113], off
	global_load_dwordx4 v[110:113], v[124:125], off offset:64 nt
	v_add_u32_e32 v114, 48, v130
	v_ashrrev_i32_e32 v115, 31, v114
	v_lshlrev_b64 v[114:115], 12, v[114:115]
	v_lshl_add_u64 v[114:115], v[114:115], 0, s[6:7]
	v_or_b32_e32 v114, v114, v32
	v_lshlrev_b64 v[114:115], 2, v[114:115]
	v_lshl_add_u64 v[116:117], s[0:1], 0, v[114:115]
	s_waitcnt vmcnt(0)
	v_pk_add_f32 v[108:109], v[108:109], v[112:113]
	v_pk_add_f32 v[106:107], v[106:107], v[110:111]
	global_store_dwordx4 v[118:119], v[106:109], off offset:64
	global_load_dwordx4 v[106:109], v[116:117], off nt
	v_lshl_add_u64 v[110:111], s[20:21], 0, v[114:115]
	s_waitcnt vmcnt(0)
	v_pk_add_f32 v[104:105], v[104:105], v[108:109]
	v_pk_add_f32 v[102:103], v[102:103], v[106:107]
	global_store_dwordx4 v[110:111], v[102:105], off
	global_load_dwordx4 v[102:105], v[116:117], off offset:64 nt
	s_waitcnt vmcnt(0)
	v_pk_add_f32 v[96:97], v[96:97], v[104:105]
	v_pk_add_f32 v[94:95], v[94:95], v[102:103]
	global_store_dwordx4 v[110:111], v[94:97], off offset:64
	global_load_dwordx4 v[94:97], v[138:139], off offset:512 nt
	s_waitcnt vmcnt(0)
	v_pk_add_f32 v[96:97], v[100:101], v[96:97]
	v_pk_add_f32 v[94:95], v[98:99], v[94:95]
	global_store_dwordx4 v[136:137], v[94:97], off offset:512
	global_load_dwordx4 v[94:97], v[138:139], off offset:576 nt
	s_waitcnt vmcnt(0)
	v_pk_add_f32 v[92:93], v[92:93], v[96:97]
	v_pk_add_f32 v[90:91], v[90:91], v[94:95]
	global_store_dwordx4 v[136:137], v[90:93], off offset:576
	global_load_dwordx4 v[90:93], v[134:135], off offset:512 nt
	s_waitcnt vmcnt(0)
	v_pk_add_f32 v[88:89], v[88:89], v[92:93]
	v_pk_add_f32 v[86:87], v[86:87], v[90:91]
	global_store_dwordx4 v[126:127], v[86:89], off offset:512
	global_load_dwordx4 v[86:89], v[134:135], off offset:576 nt
	s_waitcnt vmcnt(0)
	v_pk_add_f32 v[84:85], v[84:85], v[88:89]
	v_pk_add_f32 v[82:83], v[82:83], v[86:87]
	global_store_dwordx4 v[126:127], v[82:85], off offset:576
	global_load_dwordx4 v[82:85], v[124:125], off offset:512 nt
	s_waitcnt vmcnt(0)
	v_pk_add_f32 v[80:81], v[80:81], v[84:85]
	v_pk_add_f32 v[78:79], v[78:79], v[82:83]
	global_store_dwordx4 v[118:119], v[78:81], off offset:512
	global_load_dwordx4 v[78:81], v[124:125], off offset:576 nt
	s_waitcnt vmcnt(0)
; __device__ __forceinline__ void ph_out(const Params& p, int l, char* shm) {
;     ...
;     gemm_tile8(p.YMIX + (size_t)brow * DM, DM, W + (size_t)pn * 256 * DM, DM, DM, shm, [&](int r, int c, f32x4 v) {
;       const size_t o = (size_t)(brow + r) * DM + pn * 256 + c;
;       const f32x4 xo = *(const f32x4*)(xold + o);
;       *(f32x4*)(p.out + o) = xo + v;
;     });
	v_pk_add_f32 v[76:77], v[76:77], v[80:81]
	v_pk_add_f32 v[74:75], v[74:75], v[78:79]
	global_store_dwordx4 v[118:119], v[74:77], off offset:576
	global_load_dwordx4 v[74:77], v[116:117], off offset:512 nt
	s_waitcnt vmcnt(0)
	v_pk_add_f32 v[72:73], v[72:73], v[76:77]
	v_pk_add_f32 v[70:71], v[70:71], v[74:75]
	global_store_dwordx4 v[110:111], v[70:73], off offset:512
	global_load_dwordx4 v[70:73], v[116:117], off offset:576 nt
	v_add_u32_e32 v74, 0x80, v130
	v_ashrrev_i32_e32 v75, 31, v74
	v_lshlrev_b64 v[74:75], 12, v[74:75]
	v_lshl_add_u64 v[74:75], v[74:75], 0, s[6:7]
	v_or_b32_e32 v74, v74, v32
	v_lshlrev_b64 v[74:75], 2, v[74:75]
	v_lshl_add_u64 v[76:77], s[0:1], 0, v[74:75]
	s_waitcnt vmcnt(0)
	v_pk_add_f32 v[64:65], v[64:65], v[72:73]
	v_pk_add_f32 v[62:63], v[62:63], v[70:71]
	global_store_dwordx4 v[110:111], v[62:65], off offset:576
	global_load_dwordx4 v[62:65], v[76:77], off nt
	v_lshl_add_u64 v[70:71], s[20:21], 0, v[74:75]
	s_waitcnt vmcnt(0)
	v_pk_add_f32 v[64:65], v[68:69], v[64:65]
	v_pk_add_f32 v[62:63], v[66:67], v[62:63]
	global_store_dwordx4 v[70:71], v[62:65], off
	global_load_dwordx4 v[62:65], v[76:77], off offset:64 nt
	v_add_u32_e32 v66, 0x90, v130
	v_ashrrev_i32_e32 v67, 31, v66
	v_lshlrev_b64 v[66:67], 12, v[66:67]
	v_lshl_add_u64 v[66:67], v[66:67], 0, s[6:7]
	v_or_b32_e32 v66, v66, v32
	v_lshlrev_b64 v[66:67], 2, v[66:67]
	v_lshl_add_u64 v[68:69], s[0:1], 0, v[66:67]
	s_waitcnt vmcnt(0)
	v_pk_add_f32 v[60:61], v[60:61], v[64:65]
	v_pk_add_f32 v[58:59], v[58:59], v[62:63]
	global_store_dwordx4 v[70:71], v[58:61], off offset:64
	global_load_dwordx4 v[58:61], v[68:69], off nt
	v_lshl_add_u64 v[62:63], s[20:21], 0, v[66:67]
	s_waitcnt vmcnt(0)
	v_pk_add_f32 v[56:57], v[56:57], v[60:61]
	v_pk_add_f32 v[54:55], v[54:55], v[58:59]
	global_store_dwordx4 v[62:63], v[54:57], off
	global_load_dwordx4 v[54:57], v[68:69], off offset:64 nt
	v_add_u32_e32 v58, 0xa0, v130
	v_ashrrev_i32_e32 v59, 31, v58
	v_lshlrev_b64 v[58:59], 12, v[58:59]
	v_lshl_add_u64 v[58:59], v[58:59], 0, s[6:7]
	v_or_b32_e32 v58, v58, v32
	v_lshlrev_b64 v[58:59], 2, v[58:59]
	v_lshl_add_u64 v[60:61], s[0:1], 0, v[58:59]
	s_waitcnt vmcnt(0)
	v_pk_add_f32 v[52:53], v[52:53], v[56:57]
	v_pk_add_f32 v[50:51], v[50:51], v[54:55]
	global_store_dwordx4 v[62:63], v[50:53], off offset:64
	global_load_dwordx4 v[50:53], v[60:61], off nt
	v_lshl_add_u64 v[54:55], s[20:21], 0, v[58:59]
	s_waitcnt vmcnt(0)
	v_pk_add_f32 v[48:49], v[48:49], v[52:53]
	v_pk_add_f32 v[46:47], v[46:47], v[50:51]
	global_store_dwordx4 v[54:55], v[46:49], off
	global_load_dwordx4 v[46:49], v[60:61], off offset:64 nt
	v_add_u32_e32 v50, 0xb0, v130
	v_ashrrev_i32_e32 v51, 31, v50
	v_lshlrev_b64 v[50:51], 12, v[50:51]
	v_lshl_add_u64 v[50:51], v[50:51], 0, s[6:7]
	v_or_b32_e32 v50, v50, v32
	v_lshlrev_b64 v[50:51], 2, v[50:51]
	v_lshl_add_u64 v[52:53], s[0:1], 0, v[50:51]
	s_waitcnt vmcnt(0)
	v_pk_add_f32 v[44:45], v[44:45], v[48:49]
	v_pk_add_f32 v[42:43], v[42:43], v[46:47]
	global_store_dwordx4 v[54:55], v[42:45], off offset:64
	global_load_dwordx4 v[42:45], v[52:53], off nt
	v_lshl_add_u64 v[46:47], s[20:21], 0, v[50:51]
	s_waitcnt vmcnt(0)
	v_pk_add_f32 v[40:41], v[40:41], v[44:45]
	v_pk_add_f32 v[38:39], v[38:39], v[42:43]
	global_store_dwordx4 v[46:47], v[38:41], off
	global_load_dwordx4 v[38:41], v[52:53], off offset:64 nt
	s_waitcnt vmcnt(0)
	v_pk_add_f32 v[36:37], v[36:37], v[40:41]
	v_pk_add_f32 v[34:35], v[34:35], v[38:39]
	global_store_dwordx4 v[46:47], v[34:37], off offset:64
	global_load_dwordx4 v[34:37], v[76:77], off offset:512 nt
	s_waitcnt vmcnt(0)
	v_pk_add_f32 v[30:31], v[30:31], v[36:37]
	v_pk_add_f32 v[28:29], v[28:29], v[34:35]
	global_store_dwordx4 v[70:71], v[28:31], off offset:512
	global_load_dwordx4 v[28:31], v[76:77], off offset:576 nt
	s_waitcnt vmcnt(0)
	v_pk_add_f32 v[26:27], v[26:27], v[30:31]
	v_pk_add_f32 v[24:25], v[24:25], v[28:29]
	global_store_dwordx4 v[70:71], v[24:27], off offset:576
	global_load_dwordx4 v[24:27], v[68:69], off offset:512 nt
	s_waitcnt vmcnt(0)
	v_pk_add_f32 v[22:23], v[22:23], v[26:27]
	v_pk_add_f32 v[20:21], v[20:21], v[24:25]
	global_store_dwordx4 v[62:63], v[20:23], off offset:512
	global_load_dwordx4 v[20:23], v[68:69], off offset:576 nt
	s_waitcnt vmcnt(0)
	v_pk_add_f32 v[18:19], v[18:19], v[22:23]
	v_pk_add_f32 v[16:17], v[16:17], v[20:21]
	global_store_dwordx4 v[62:63], v[16:19], off offset:576
	global_load_dwordx4 v[16:19], v[60:61], off offset:512 nt
	s_waitcnt vmcnt(0)
	v_pk_add_f32 v[14:15], v[14:15], v[18:19]
	v_pk_add_f32 v[12:13], v[12:13], v[16:17]
	global_store_dwordx4 v[54:55], v[12:15], off offset:512
	global_load_dwordx4 v[12:15], v[60:61], off offset:576 nt
	s_waitcnt vmcnt(0)
	v_pk_add_f32 v[10:11], v[10:11], v[14:15]
	v_pk_add_f32 v[8:9], v[8:9], v[12:13]
	global_store_dwordx4 v[54:55], v[8:11], off offset:576
	global_load_dwordx4 v[8:11], v[52:53], off offset:512 nt
	s_waitcnt vmcnt(0)
	v_pk_add_f32 v[6:7], v[6:7], v[10:11]
	v_pk_add_f32 v[4:5], v[4:5], v[8:9]
	global_store_dwordx4 v[46:47], v[4:7], off offset:512
	global_load_dwordx4 v[4:7], v[52:53], off offset:576 nt
	s_waitcnt vmcnt(0)
	v_pk_add_f32 v[2:3], v[2:3], v[6:7]
	v_pk_add_f32 v[0:1], v[0:1], v[4:5]
	global_store_dwordx4 v[46:47], v[0:3], off offset:576

; __device__ __forceinline__ unsigned pack2(float a, float b) { const f32x2_t v = {a, b}; const bf16x2_t r = __builtin_convertvector(v, bf16x2_t); return __builtin_bit_cast(unsigned, r); }
; __device__ __forceinline__ void ph_proj(const Params& p, int l, char* shm) {
;     ...
;     const int act = ((pn >= 10 && pn < 18) || pn >= 51) ? 1 : ((pn >= 35 && pn < 51) ? 2 : 0);
;     gemm_tile8(p.H + (size_t)brow * DM, DM, W + (size_t)pn * 256 * DM, DM, DM, shm, [&](int r, int c, f32x4 v) {
;       if (pn == 34) {
;         *(f32x4*)(p.KW + (size_t)(brow + r) * 256 + c) = v;
;       } else {
;         float y[4];
; #pragma unroll
;         for (int j = 0; j < 4; ++j) {
;           float xv = v[j];
;           if (act == 1) xv = xv * __builtin_amdgcn_rcpf(1.f + __expf(-xv));
;           else if (act == 2) xv = 0.5f * xv * (1.f + erf_fast(xv * 0.70710678118654752f));
;           y[j] = xv;
;         }
;         *(uint2*)(p.P + (size_t)(brow + r) * NP + pn * 256 + c) = uint2{pack2(y[0], y[1]), pack2(y[2], y[3])};
.LBB0_966:
	s_add_i32 s0, s6, -10
	s_cmp_lt_u32 s0, 8
	s_cselect_b64 s[0:1], -1, 0
	s_cmp_gt_i32 s6, 50
	s_cselect_b64 s[10:11], -1, 0
	s_or_b64 s[0:1], s[10:11], s[0:1]
	s_cmp_gt_i32 s6, 34
	s_cselect_b32 s7, 2, 0
	s_and_b64 s[0:1], s[0:1], exec
	v_lshrrev_b32_e32 v32, 2, v32
	s_cselect_b32 s7, 1, s7
	v_and_b32_e32 v32, 12, v32
	s_cmp_lg_u32 s6, 34
	v_readlane_b32 s16, v245, 25
	v_lshl_or_b32 v134, s9, 5, v32
	s_cselect_b64 s[10:11], -1, 0
	s_cmp_eq_u32 s6, 34
	s_mov_b64 s[0:1], -1
	v_readlane_b32 s15, v245, 24
	v_readlane_b32 s17, v245, 26
	v_readlane_b32 s18, v245, 27
	v_readlane_b32 s19, v245, 28
	v_readlane_b32 s20, v245, 29
	v_readlane_b32 s21, v245, 30
	v_readlane_b32 s22, v245, 31
	v_readlane_b32 s23, v245, 32
	v_readlane_b32 s24, v245, 33
	v_readlane_b32 s25, v245, 34
	v_readlane_b32 s26, v245, 35
	v_readlane_b32 s27, v245, 36
	v_readlane_b32 s28, v245, 37
	v_readlane_b32 s29, v245, 38
	v_readlane_b32 s30, v245, 39
	v_readlane_b32 s31, v245, 40
	v_readlane_b32 s14, v245, 48
	s_cbranch_scc1 .Lpj_f32
	v_add_u32_e32 v135, s8, v146
	v_mov_b32_e32 v137, v33
	v_mov_b32_e32 v139, v33
	s_lshl_b32 s0, s6, 9
	s_add_u32 s0, s26, s0
	s_addc_u32 s1, s27, 0
	s_movk_i32 s9, 0x7600
	v_lshlrev_b32_e32 v136, 1, v134
	v_and_b32_e32 v138, 16, v204
	v_lshrrev_b32_e32 v139, 1, v138
	v_add3_u32 v136, v136, v138, v139
	v_mov_b32_e32 v139, v33
	v_mov_b32_e32 v138, v135
	v_mov_b64_e32 v[160:161], s[0:1]
	v_mad_i64_i32 v[160:161], s[10:11], v138, s9, v[160:161]
	v_lshl_add_u64 v[160:161], v[160:161], 0, v[136:137]
	v_add_u32_e32 v138, 16, v135
	v_mov_b64_e32 v[162:163], s[0:1]
	v_mad_i64_i32 v[162:163], s[10:11], v138, s9, v[162:163]
	v_lshl_add_u64 v[162:163], v[162:163], 0, v[136:137]
	v_add_u32_e32 v138, 32, v135
	v_mov_b64_e32 v[164:165], s[0:1]
	v_mad_i64_i32 v[164:165], s[10:11], v138, s9, v[164:165]
	v_lshl_add_u64 v[164:165], v[164:165], 0, v[136:137]
	v_add_u32_e32 v138, 48, v135
	v_mov_b64_e32 v[166:167], s[0:1]
	v_mad_i64_i32 v[166:167], s[10:11], v138, s9, v[166:167]
	v_lshl_add_u64 v[166:167], v[166:167], 0, v[136:137]
	v_add_u32_e32 v138, 0x80, v135
	v_mov_b64_e32 v[168:169], s[0:1]
	v_mad_i64_i32 v[168:169], s[10:11], v138, s9, v[168:169]
	v_lshl_add_u64 v[168:169], v[168:169], 0, v[136:137]
	v_add_u32_e32 v138, 0x90, v135
	v_mov_b64_e32 v[170:171], s[0:1]
	v_mad_i64_i32 v[170:171], s[10:11], v138, s9, v[170:171]
	v_lshl_add_u64 v[170:171], v[170:171], 0, v[136:137]
	v_add_u32_e32 v138, 0xa0, v135
	v_mov_b64_e32 v[172:173], s[0:1]
	v_mad_i64_i32 v[172:173], s[10:11], v138, s9, v[172:173]
	v_lshl_add_u64 v[172:173], v[172:173], 0, v[136:137]
	v_add_u32_e32 v138, 0xb0, v135
	v_mov_b64_e32 v[174:175], s[0:1]
	v_mad_i64_i32 v[174:175], s[10:11], v138, s9, v[174:175]
	v_lshl_add_u64 v[174:175], v[174:175], 0, v[136:137]
	s_cmp_eq_u32 s7, 1
	s_cbranch_scc1 .Lpj_silu
	s_cmp_eq_u32 s7, 2
	s_cbranch_scc1 .Lpj_gelu
	v_cvt_pk_bf16_f32 v140, v126, v127
	v_cvt_pk_bf16_f32 v141, v128, v129
	v_cvt_pk_bf16_f32 v142, v122, v123
	v_cvt_pk_bf16_f32 v143, v124, v125
	v_cvt_pk_bf16_f32 v144, v118, v119
	v_cvt_pk_bf16_f32 v145, v120, v121
	v_cvt_pk_bf16_f32 v146, v114, v115
	v_cvt_pk_bf16_f32 v147, v116, v117
	s_nop 1
	v_permlane16_swap_b32_e32 v140, v142
	v_permlane16_swap_b32_e32 v141, v143
	global_store_dwordx4 v[160:161], v[140:143], off nt
	v_cvt_pk_bf16_f32 v148, v110, v111
	v_cvt_pk_bf16_f32 v149, v112, v113
	v_cvt_pk_bf16_f32 v150, v106, v107
	v_cvt_pk_bf16_f32 v151, v108, v109
	s_nop 1
	v_permlane16_swap_b32_e32 v144, v146
	v_permlane16_swap_b32_e32 v145, v147
	global_store_dwordx4 v[162:163], v[144:147], off nt
	v_cvt_pk_bf16_f32 v140, v102, v103
	v_cvt_pk_bf16_f32 v141, v104, v105
	v_cvt_pk_bf16_f32 v142, v98, v99
	v_cvt_pk_bf16_f32 v143, v100, v101
	s_nop 1
	v_permlane16_swap_b32_e32 v148, v150
	v_permlane16_swap_b32_e32 v149, v151
	global_store_dwordx4 v[164:165], v[148:151], off nt
	v_cvt_pk_bf16_f32 v144, v94, v95
	v_cvt_pk_bf16_f32 v145, v96, v97
	v_cvt_pk_bf16_f32 v146, v90, v91
	v_cvt_pk_bf16_f32 v147, v92, v93
	s_nop 1
	v_permlane16_swap_b32_e32 v140, v142
	v_permlane16_swap_b32_e32 v141, v143
	global_store_dwordx4 v[166:167], v[140:143], off nt
	v_cvt_pk_bf16_f32 v148, v86, v87
	v_cvt_pk_bf16_f32 v149, v88, v89
	v_cvt_pk_bf16_f32 v150, v82, v83
	v_cvt_pk_bf16_f32 v151, v84, v85
	s_nop 1
	v_permlane16_swap_b32_e32 v144, v146
	v_permlane16_swap_b32_e32 v145, v147
	global_store_dwordx4 v[160:161], v[144:147], off offset:256 nt
	v_cvt_pk_bf16_f32 v140, v78, v79
	v_cvt_pk_bf16_f32 v141, v80, v81
	v_cvt_pk_bf16_f32 v142, v74, v75
	v_cvt_pk_bf16_f32 v143, v76, v77
	s_nop 1
	v_permlane16_swap_b32_e32 v148, v150
	v_permlane16_swap_b32_e32 v149, v151
	global_store_dwordx4 v[162:163], v[148:151], off offset:256 nt
	v_cvt_pk_bf16_f32 v144, v70, v71
	v_cvt_pk_bf16_f32 v145, v72, v73
	v_cvt_pk_bf16_f32 v146, v66, v67
	v_cvt_pk_bf16_f32 v147, v68, v69
	s_nop 1
	v_permlane16_swap_b32_e32 v140, v142
	v_permlane16_swap_b32_e32 v141, v143
	global_store_dwordx4 v[164:165], v[140:143], off offset:256 nt
	v_cvt_pk_bf16_f32 v148, v62, v63
	v_cvt_pk_bf16_f32 v149, v64, v65
	v_cvt_pk_bf16_f32 v150, v58, v59
	v_cvt_pk_bf16_f32 v151, v60, v61
	s_nop 1
	v_permlane16_swap_b32_e32 v144, v146
	v_permlane16_swap_b32_e32 v145, v147
	global_store_dwordx4 v[166:167], v[144:147], off offset:256 nt
	v_cvt_pk_bf16_f32 v140, v54, v55
	v_cvt_pk_bf16_f32 v141, v56, v57
	v_cvt_pk_bf16_f32 v142, v50, v51
	v_cvt_pk_bf16_f32 v143, v52, v53
	s_nop 1
	v_permlane16_swap_b32_e32 v148, v150
	v_permlane16_swap_b32_e32 v149, v151
	global_store_dwordx4 v[168:169], v[148:151], off nt
	v_cvt_pk_bf16_f32 v144, v46, v47
	v_cvt_pk_bf16_f32 v145, v48, v49
	v_cvt_pk_bf16_f32 v146, v42, v43
; __device__ __forceinline__ unsigned pack2(float a, float b) { const f32x2_t v = {a, b}; const bf16x2_t r = __builtin_convertvector(v, bf16x2_t); return __builtin_bit_cast(unsigned, r); }
; __device__ __forceinline__ void ph_proj(const Params& p, int l, char* shm) {
;     ...
;           float xv = v[j];
;           if (act == 1) xv = xv * __builtin_amdgcn_rcpf(1.f + __expf(-xv));
;           else if (act == 2) xv = 0.5f * xv * (1.f + erf_fast(xv * 0.70710678118654752f));
;           y[j] = xv;
;         }
;         *(uint2*)(p.P + (size_t)(brow + r) * NP + pn * 256 + c) = uint2{pack2(y[0], y[1]), pack2(y[2], y[3])};
	v_cvt_pk_bf16_f32 v147, v44, v45
	s_nop 1
	v_permlane16_swap_b32_e32 v140, v142
	v_permlane16_swap_b32_e32 v141, v143
	global_store_dwordx4 v[170:171], v[140:143], off nt
	v_cvt_pk_bf16_f32 v148, v38, v39
	v_cvt_pk_bf16_f32 v149, v40, v41
	v_cvt_pk_bf16_f32 v150, v34, v35
	v_cvt_pk_bf16_f32 v151, v36, v37
	s_nop 1
	v_permlane16_swap_b32_e32 v144, v146
	v_permlane16_swap_b32_e32 v145, v147
	global_store_dwordx4 v[172:173], v[144:147], off nt
	v_cvt_pk_bf16_f32 v140, v28, v29
	v_cvt_pk_bf16_f32 v141, v30, v31
	v_cvt_pk_bf16_f32 v142, v24, v25
	v_cvt_pk_bf16_f32 v143, v26, v27
	s_nop 1
	v_permlane16_swap_b32_e32 v148, v150
	v_permlane16_swap_b32_e32 v149, v151
	global_store_dwordx4 v[174:175], v[148:151], off nt
	v_cvt_pk_bf16_f32 v144, v20, v21
	v_cvt_pk_bf16_f32 v145, v22, v23
	v_cvt_pk_bf16_f32 v146, v16, v17
	v_cvt_pk_bf16_f32 v147, v18, v19
	s_nop 1
	v_permlane16_swap_b32_e32 v140, v142
	v_permlane16_swap_b32_e32 v141, v143
	global_store_dwordx4 v[168:169], v[140:143], off offset:256 nt
	v_cvt_pk_bf16_f32 v148, v12, v13
	v_cvt_pk_bf16_f32 v149, v14, v15
	v_cvt_pk_bf16_f32 v150, v8, v9
	v_cvt_pk_bf16_f32 v151, v10, v11
	s_nop 1
	v_permlane16_swap_b32_e32 v144, v146
	v_permlane16_swap_b32_e32 v145, v147
	global_store_dwordx4 v[170:171], v[144:147], off offset:256 nt
	v_cvt_pk_bf16_f32 v140, v4, v5
	v_cvt_pk_bf16_f32 v141, v6, v7
	v_cvt_pk_bf16_f32 v142, v0, v1
	v_cvt_pk_bf16_f32 v143, v2, v3
	s_nop 1
	v_permlane16_swap_b32_e32 v148, v150
	v_permlane16_swap_b32_e32 v149, v151
	global_store_dwordx4 v[172:173], v[148:151], off offset:256 nt
	s_nop 1
	v_permlane16_swap_b32_e32 v140, v142
	v_permlane16_swap_b32_e32 v141, v143
	global_store_dwordx4 v[174:175], v[140:143], off offset:256 nt
	s_branch .LBB0_958
.Lpj_silu:
	v_mul_f32_e32 v176, 0xbfb8aa3b, v126
	v_mul_f32_e32 v177, 0xbfb8aa3b, v127
	v_mul_f32_e32 v178, 0xbfb8aa3b, v128
	v_mul_f32_e32 v179, 0xbfb8aa3b, v129
	v_exp_f32_e32 v176, v176
	v_exp_f32_e32 v177, v177
	v_exp_f32_e32 v178, v178
	v_exp_f32_e32 v179, v179
	v_add_f32_e32 v176, 1.0, v176
	v_add_f32_e32 v177, 1.0, v177
	v_add_f32_e32 v178, 1.0, v178
	v_add_f32_e32 v179, 1.0, v179
	v_rcp_f32_e32 v176, v176
	v_rcp_f32_e32 v177, v177
	v_rcp_f32_e32 v178, v178
	v_rcp_f32_e32 v179, v179
	v_mul_f32_e32 v176, v126, v176
	v_mul_f32_e32 v177, v127, v177
	v_mul_f32_e32 v178, v128, v178
	v_mul_f32_e32 v179, v129, v179
	v_cvt_pk_bf16_f32 v140, v176, v177
	v_cvt_pk_bf16_f32 v141, v178, v179
	v_mul_f32_e32 v176, 0xbfb8aa3b, v122
	v_mul_f32_e32 v177, 0xbfb8aa3b, v123
	v_mul_f32_e32 v178, 0xbfb8aa3b, v124
	v_mul_f32_e32 v179, 0xbfb8aa3b, v125
	v_exp_f32_e32 v176, v176
	v_exp_f32_e32 v177, v177
	v_exp_f32_e32 v178, v178
	v_exp_f32_e32 v179, v179
	v_add_f32_e32 v176, 1.0, v176
	v_add_f32_e32 v177, 1.0, v177
	v_add_f32_e32 v178, 1.0, v178
	v_add_f32_e32 v179, 1.0, v179
	v_rcp_f32_e32 v176, v176
	v_rcp_f32_e32 v177, v177
	v_rcp_f32_e32 v178, v178
	v_rcp_f32_e32 v179, v179
	v_mul_f32_e32 v176, v122, v176
	v_mul_f32_e32 v177, v123, v177
	v_mul_f32_e32 v178, v124, v178
	v_mul_f32_e32 v179, v125, v179
	v_cvt_pk_bf16_f32 v142, v176, v177
	v_cvt_pk_bf16_f32 v143, v178, v179
	v_mul_f32_e32 v176, 0xbfb8aa3b, v118
	v_mul_f32_e32 v177, 0xbfb8aa3b, v119
	v_mul_f32_e32 v178, 0xbfb8aa3b, v120
	v_mul_f32_e32 v179, 0xbfb8aa3b, v121
	v_exp_f32_e32 v176, v176
	v_exp_f32_e32 v177, v177
	v_exp_f32_e32 v178, v178
	v_exp_f32_e32 v179, v179
	v_add_f32_e32 v176, 1.0, v176
	v_add_f32_e32 v177, 1.0, v177
	v_add_f32_e32 v178, 1.0, v178
	v_add_f32_e32 v179, 1.0, v179
	v_rcp_f32_e32 v176, v176
	v_rcp_f32_e32 v177, v177
	v_rcp_f32_e32 v178, v178
	v_rcp_f32_e32 v179, v179
	v_mul_f32_e32 v176, v118, v176
	v_mul_f32_e32 v177, v119, v177
	v_mul_f32_e32 v178, v120, v178
	v_mul_f32_e32 v179, v121, v179
	v_cvt_pk_bf16_f32 v144, v176, v177
	v_cvt_pk_bf16_f32 v145, v178, v179
	v_mul_f32_e32 v176, 0xbfb8aa3b, v114
	v_mul_f32_e32 v177, 0xbfb8aa3b, v115
	v_mul_f32_e32 v178, 0xbfb8aa3b, v116
	v_mul_f32_e32 v179, 0xbfb8aa3b, v117
	v_exp_f32_e32 v176, v176
	v_exp_f32_e32 v177, v177
	v_exp_f32_e32 v178, v178
	v_exp_f32_e32 v179, v179
	v_add_f32_e32 v176, 1.0, v176
	v_add_f32_e32 v177, 1.0, v177
	v_add_f32_e32 v178, 1.0, v178
	v_add_f32_e32 v179, 1.0, v179
	v_rcp_f32_e32 v176, v176
	v_rcp_f32_e32 v177, v177
	v_rcp_f32_e32 v178, v178
	v_rcp_f32_e32 v179, v179
	v_mul_f32_e32 v176, v114, v176
	v_mul_f32_e32 v177, v115, v177
	v_mul_f32_e32 v178, v116, v178
	v_mul_f32_e32 v179, v117, v179
	v_cvt_pk_bf16_f32 v146, v176, v177
	v_cvt_pk_bf16_f32 v147, v178, v179
	s_nop 1
	v_permlane16_swap_b32_e32 v140, v142
	v_permlane16_swap_b32_e32 v141, v143
	global_store_dwordx4 v[160:161], v[140:143], off nt
	v_mul_f32_e32 v176, 0xbfb8aa3b, v110
	v_mul_f32_e32 v177, 0xbfb8aa3b, v111
	v_mul_f32_e32 v178, 0xbfb8aa3b, v112
	v_mul_f32_e32 v179, 0xbfb8aa3b, v113
	v_exp_f32_e32 v176, v176
	v_exp_f32_e32 v177, v177
	v_exp_f32_e32 v178, v178
	v_exp_f32_e32 v179, v179
	v_add_f32_e32 v176, 1.0, v176
	v_add_f32_e32 v177, 1.0, v177
	v_add_f32_e32 v178, 1.0, v178
	v_add_f32_e32 v179, 1.0, v179
	v_rcp_f32_e32 v176, v176
	v_rcp_f32_e32 v177, v177
	v_rcp_f32_e32 v178, v178
	v_rcp_f32_e32 v179, v179
	v_mul_f32_e32 v176, v110, v176
	v_mul_f32_e32 v177, v111, v177
	v_mul_f32_e32 v178, v112, v178
	v_mul_f32_e32 v179, v113, v179
	v_cvt_pk_bf16_f32 v148, v176, v177
	v_cvt_pk_bf16_f32 v149, v178, v179
	v_mul_f32_e32 v176, 0xbfb8aa3b, v106
	v_mul_f32_e32 v177, 0xbfb8aa3b, v107
	v_mul_f32_e32 v178, 0xbfb8aa3b, v108
	v_mul_f32_e32 v179, 0xbfb8aa3b, v109
	v_exp_f32_e32 v176, v176
	v_exp_f32_e32 v177, v177
	v_exp_f32_e32 v178, v178
	v_exp_f32_e32 v179, v179
	v_add_f32_e32 v176, 1.0, v176
	v_add_f32_e32 v177, 1.0, v177
	v_add_f32_e32 v178, 1.0, v178
; __device__ __forceinline__ unsigned pack2(float a, float b) { const f32x2_t v = {a, b}; const bf16x2_t r = __builtin_convertvector(v, bf16x2_t); return __builtin_bit_cast(unsigned, r); }
; __device__ __forceinline__ void ph_proj(const Params& p, int l, char* shm) {
;     ...
;           if (act == 1) xv = xv * __builtin_amdgcn_rcpf(1.f + __expf(-xv));
;           else if (act == 2) xv = 0.5f * xv * (1.f + erf_fast(xv * 0.70710678118654752f));
;           y[j] = xv;
;         }
;         *(uint2*)(p.P + (size_t)(brow + r) * NP + pn * 256 + c) = uint2{pack2(y[0], y[1]), pack2(y[2], y[3])};
	v_add_f32_e32 v179, 1.0, v179
	v_rcp_f32_e32 v176, v176
	v_rcp_f32_e32 v177, v177
	v_rcp_f32_e32 v178, v178
	v_rcp_f32_e32 v179, v179
	v_mul_f32_e32 v176, v106, v176
	v_mul_f32_e32 v177, v107, v177
	v_mul_f32_e32 v178, v108, v178
	v_mul_f32_e32 v179, v109, v179
	v_cvt_pk_bf16_f32 v150, v176, v177
	v_cvt_pk_bf16_f32 v151, v178, v179
	s_nop 1
	v_permlane16_swap_b32_e32 v144, v146
	v_permlane16_swap_b32_e32 v145, v147
	global_store_dwordx4 v[162:163], v[144:147], off nt
	v_mul_f32_e32 v176, 0xbfb8aa3b, v102
	v_mul_f32_e32 v177, 0xbfb8aa3b, v103
	v_mul_f32_e32 v178, 0xbfb8aa3b, v104
	v_mul_f32_e32 v179, 0xbfb8aa3b, v105
	v_exp_f32_e32 v176, v176
	v_exp_f32_e32 v177, v177
	v_exp_f32_e32 v178, v178
	v_exp_f32_e32 v179, v179
	v_add_f32_e32 v176, 1.0, v176
	v_add_f32_e32 v177, 1.0, v177
	v_add_f32_e32 v178, 1.0, v178
	v_add_f32_e32 v179, 1.0, v179
	v_rcp_f32_e32 v176, v176
	v_rcp_f32_e32 v177, v177
	v_rcp_f32_e32 v178, v178
	v_rcp_f32_e32 v179, v179
	v_mul_f32_e32 v176, v102, v176
	v_mul_f32_e32 v177, v103, v177
	v_mul_f32_e32 v178, v104, v178
	v_mul_f32_e32 v179, v105, v179
	v_cvt_pk_bf16_f32 v140, v176, v177
	v_cvt_pk_bf16_f32 v141, v178, v179
	v_mul_f32_e32 v176, 0xbfb8aa3b, v98
	v_mul_f32_e32 v177, 0xbfb8aa3b, v99
	v_mul_f32_e32 v178, 0xbfb8aa3b, v100
	v_mul_f32_e32 v179, 0xbfb8aa3b, v101
	v_exp_f32_e32 v176, v176
	v_exp_f32_e32 v177, v177
	v_exp_f32_e32 v178, v178
	v_exp_f32_e32 v179, v179
	v_add_f32_e32 v176, 1.0, v176
	v_add_f32_e32 v177, 1.0, v177
	v_add_f32_e32 v178, 1.0, v178
	v_add_f32_e32 v179, 1.0, v179
	v_rcp_f32_e32 v176, v176
	v_rcp_f32_e32 v177, v177
	v_rcp_f32_e32 v178, v178
	v_rcp_f32_e32 v179, v179
	v_mul_f32_e32 v176, v98, v176
	v_mul_f32_e32 v177, v99, v177
	v_mul_f32_e32 v178, v100, v178
	v_mul_f32_e32 v179, v101, v179
	v_cvt_pk_bf16_f32 v142, v176, v177
	v_cvt_pk_bf16_f32 v143, v178, v179
	s_nop 1
	v_permlane16_swap_b32_e32 v148, v150
	v_permlane16_swap_b32_e32 v149, v151
	global_store_dwordx4 v[164:165], v[148:151], off nt
	v_mul_f32_e32 v176, 0xbfb8aa3b, v94
	v_mul_f32_e32 v177, 0xbfb8aa3b, v95
	v_mul_f32_e32 v178, 0xbfb8aa3b, v96
	v_mul_f32_e32 v179, 0xbfb8aa3b, v97
	v_exp_f32_e32 v176, v176
	v_exp_f32_e32 v177, v177
	v_exp_f32_e32 v178, v178
	v_exp_f32_e32 v179, v179
	v_add_f32_e32 v176, 1.0, v176
	v_add_f32_e32 v177, 1.0, v177
	v_add_f32_e32 v178, 1.0, v178
	v_add_f32_e32 v179, 1.0, v179
	v_rcp_f32_e32 v176, v176
	v_rcp_f32_e32 v177, v177
	v_rcp_f32_e32 v178, v178
	v_rcp_f32_e32 v179, v179
	v_mul_f32_e32 v176, v94, v176
	v_mul_f32_e32 v177, v95, v177
	v_mul_f32_e32 v178, v96, v178
	v_mul_f32_e32 v179, v97, v179
	v_cvt_pk_bf16_f32 v144, v176, v177
	v_cvt_pk_bf16_f32 v145, v178, v179
	v_mul_f32_e32 v176, 0xbfb8aa3b, v90
	v_mul_f32_e32 v177, 0xbfb8aa3b, v91
	v_mul_f32_e32 v178, 0xbfb8aa3b, v92
	v_mul_f32_e32 v179, 0xbfb8aa3b, v93
	v_exp_f32_e32 v176, v176
	v_exp_f32_e32 v177, v177
	v_exp_f32_e32 v178, v178
	v_exp_f32_e32 v179, v179
	v_add_f32_e32 v176, 1.0, v176
	v_add_f32_e32 v177, 1.0, v177
	v_add_f32_e32 v178, 1.0, v178
	v_add_f32_e32 v179, 1.0, v179
	v_rcp_f32_e32 v176, v176
	v_rcp_f32_e32 v177, v177
	v_rcp_f32_e32 v178, v178
	v_rcp_f32_e32 v179, v179
	v_mul_f32_e32 v176, v90, v176
	v_mul_f32_e32 v177, v91, v177
	v_mul_f32_e32 v178, v92, v178
	v_mul_f32_e32 v179, v93, v179
	v_cvt_pk_bf16_f32 v146, v176, v177
	v_cvt_pk_bf16_f32 v147, v178, v179
	s_nop 1
	v_permlane16_swap_b32_e32 v140, v142
	v_permlane16_swap_b32_e32 v141, v143
	global_store_dwordx4 v[166:167], v[140:143], off nt
	v_mul_f32_e32 v176, 0xbfb8aa3b, v86
	v_mul_f32_e32 v177, 0xbfb8aa3b, v87
	v_mul_f32_e32 v178, 0xbfb8aa3b, v88
	v_mul_f32_e32 v179, 0xbfb8aa3b, v89
	v_exp_f32_e32 v176, v176
	v_exp_f32_e32 v177, v177
	v_exp_f32_e32 v178, v178
	v_exp_f32_e32 v179, v179
	v_add_f32_e32 v176, 1.0, v176
	v_add_f32_e32 v177, 1.0, v177
	v_add_f32_e32 v178, 1.0, v178
	v_add_f32_e32 v179, 1.0, v179
	v_rcp_f32_e32 v176, v176
	v_rcp_f32_e32 v177, v177
	v_rcp_f32_e32 v178, v178
	v_rcp_f32_e32 v179, v179
	v_mul_f32_e32 v176, v86, v176
	v_mul_f32_e32 v177, v87, v177
	v_mul_f32_e32 v178, v88, v178
	v_mul_f32_e32 v179, v89, v179
	v_cvt_pk_bf16_f32 v148, v176, v177
	v_cvt_pk_bf16_f32 v149, v178, v179
	v_mul_f32_e32 v176, 0xbfb8aa3b, v82
	v_mul_f32_e32 v177, 0xbfb8aa3b, v83
	v_mul_f32_e32 v178, 0xbfb8aa3b, v84
	v_mul_f32_e32 v179, 0xbfb8aa3b, v85
	v_exp_f32_e32 v176, v176
	v_exp_f32_e32 v177, v177
	v_exp_f32_e32 v178, v178
	v_exp_f32_e32 v179, v179
	v_add_f32_e32 v176, 1.0, v176
	v_add_f32_e32 v177, 1.0, v177
	v_add_f32_e32 v178, 1.0, v178
	v_add_f32_e32 v179, 1.0, v179
	v_rcp_f32_e32 v176, v176
	v_rcp_f32_e32 v177, v177
	v_rcp_f32_e32 v178, v178
	v_rcp_f32_e32 v179, v179
	v_mul_f32_e32 v176, v82, v176
	v_mul_f32_e32 v177, v83, v177
	v_mul_f32_e32 v178, v84, v178
	v_mul_f32_e32 v179, v85, v179
	v_cvt_pk_bf16_f32 v150, v176, v177
	v_cvt_pk_bf16_f32 v151, v178, v179
	s_nop 1
	v_permlane16_swap_b32_e32 v144, v146
	v_permlane16_swap_b32_e32 v145, v147
	global_store_dwordx4 v[160:161], v[144:147], off offset:256 nt
	v_mul_f32_e32 v176, 0xbfb8aa3b, v78
	v_mul_f32_e32 v177, 0xbfb8aa3b, v79
	v_mul_f32_e32 v178, 0xbfb8aa3b, v80
	v_mul_f32_e32 v179, 0xbfb8aa3b, v81
	v_exp_f32_e32 v176, v176
	v_exp_f32_e32 v177, v177
	v_exp_f32_e32 v178, v178
	v_exp_f32_e32 v179, v179
	v_add_f32_e32 v176, 1.0, v176
	v_add_f32_e32 v177, 1.0, v177
	v_add_f32_e32 v178, 1.0, v178
	v_add_f32_e32 v179, 1.0, v179
	v_rcp_f32_e32 v176, v176
	v_rcp_f32_e32 v177, v177
	v_rcp_f32_e32 v178, v178
	v_rcp_f32_e32 v179, v179
	v_mul_f32_e32 v176, v78, v176
	v_mul_f32_e32 v177, v79, v177
	v_mul_f32_e32 v178, v80, v178
	v_mul_f32_e32 v179, v81, v179
	v_cvt_pk_bf16_f32 v140, v176, v177
	v_cvt_pk_bf16_f32 v141, v178, v179
; __device__ __forceinline__ unsigned pack2(float a, float b) { const f32x2_t v = {a, b}; const bf16x2_t r = __builtin_convertvector(v, bf16x2_t); return __builtin_bit_cast(unsigned, r); }
; __device__ __forceinline__ void ph_proj(const Params& p, int l, char* shm) {
;     ...
;           if (act == 1) xv = xv * __builtin_amdgcn_rcpf(1.f + __expf(-xv));
;           else if (act == 2) xv = 0.5f * xv * (1.f + erf_fast(xv * 0.70710678118654752f));
;           y[j] = xv;
;         }
;         *(uint2*)(p.P + (size_t)(brow + r) * NP + pn * 256 + c) = uint2{pack2(y[0], y[1]), pack2(y[2], y[3])};
	v_mul_f32_e32 v176, 0xbfb8aa3b, v74
	v_mul_f32_e32 v177, 0xbfb8aa3b, v75
	v_mul_f32_e32 v178, 0xbfb8aa3b, v76
	v_mul_f32_e32 v179, 0xbfb8aa3b, v77
	v_exp_f32_e32 v176, v176
	v_exp_f32_e32 v177, v177
	v_exp_f32_e32 v178, v178
	v_exp_f32_e32 v179, v179
	v_add_f32_e32 v176, 1.0, v176
	v_add_f32_e32 v177, 1.0, v177
	v_add_f32_e32 v178, 1.0, v178
	v_add_f32_e32 v179, 1.0, v179
	v_rcp_f32_e32 v176, v176
	v_rcp_f32_e32 v177, v177
	v_rcp_f32_e32 v178, v178
	v_rcp_f32_e32 v179, v179
	v_mul_f32_e32 v176, v74, v176
	v_mul_f32_e32 v177, v75, v177
	v_mul_f32_e32 v178, v76, v178
	v_mul_f32_e32 v179, v77, v179
	v_cvt_pk_bf16_f32 v142, v176, v177
	v_cvt_pk_bf16_f32 v143, v178, v179
	s_nop 1
	v_permlane16_swap_b32_e32 v148, v150
	v_permlane16_swap_b32_e32 v149, v151
	global_store_dwordx4 v[162:163], v[148:151], off offset:256 nt
	v_mul_f32_e32 v176, 0xbfb8aa3b, v70
	v_mul_f32_e32 v177, 0xbfb8aa3b, v71
	v_mul_f32_e32 v178, 0xbfb8aa3b, v72
	v_mul_f32_e32 v179, 0xbfb8aa3b, v73
	v_exp_f32_e32 v176, v176
	v_exp_f32_e32 v177, v177
	v_exp_f32_e32 v178, v178
	v_exp_f32_e32 v179, v179
	v_add_f32_e32 v176, 1.0, v176
	v_add_f32_e32 v177, 1.0, v177
	v_add_f32_e32 v178, 1.0, v178
	v_add_f32_e32 v179, 1.0, v179
	v_rcp_f32_e32 v176, v176
	v_rcp_f32_e32 v177, v177
	v_rcp_f32_e32 v178, v178
	v_rcp_f32_e32 v179, v179
	v_mul_f32_e32 v176, v70, v176
	v_mul_f32_e32 v177, v71, v177
	v_mul_f32_e32 v178, v72, v178
	v_mul_f32_e32 v179, v73, v179
	v_cvt_pk_bf16_f32 v144, v176, v177
	v_cvt_pk_bf16_f32 v145, v178, v179
	v_mul_f32_e32 v176, 0xbfb8aa3b, v66
	v_mul_f32_e32 v177, 0xbfb8aa3b, v67
	v_mul_f32_e32 v178, 0xbfb8aa3b, v68
	v_mul_f32_e32 v179, 0xbfb8aa3b, v69
	v_exp_f32_e32 v176, v176
	v_exp_f32_e32 v177, v177
	v_exp_f32_e32 v178, v178
	v_exp_f32_e32 v179, v179
	v_add_f32_e32 v176, 1.0, v176
	v_add_f32_e32 v177, 1.0, v177
	v_add_f32_e32 v178, 1.0, v178
	v_add_f32_e32 v179, 1.0, v179
	v_rcp_f32_e32 v176, v176
	v_rcp_f32_e32 v177, v177
	v_rcp_f32_e32 v178, v178
	v_rcp_f32_e32 v179, v179
	v_mul_f32_e32 v176, v66, v176
	v_mul_f32_e32 v177, v67, v177
	v_mul_f32_e32 v178, v68, v178
	v_mul_f32_e32 v179, v69, v179
	v_cvt_pk_bf16_f32 v146, v176, v177
	v_cvt_pk_bf16_f32 v147, v178, v179
	s_nop 1
	v_permlane16_swap_b32_e32 v140, v142
	v_permlane16_swap_b32_e32 v141, v143
	global_store_dwordx4 v[164:165], v[140:143], off offset:256 nt
	v_mul_f32_e32 v176, 0xbfb8aa3b, v62
	v_mul_f32_e32 v177, 0xbfb8aa3b, v63
	v_mul_f32_e32 v178, 0xbfb8aa3b, v64
	v_mul_f32_e32 v179, 0xbfb8aa3b, v65
	v_exp_f32_e32 v176, v176
	v_exp_f32_e32 v177, v177
	v_exp_f32_e32 v178, v178
	v_exp_f32_e32 v179, v179
	v_add_f32_e32 v176, 1.0, v176
	v_add_f32_e32 v177, 1.0, v177
	v_add_f32_e32 v178, 1.0, v178
	v_add_f32_e32 v179, 1.0, v179
	v_rcp_f32_e32 v176, v176
	v_rcp_f32_e32 v177, v177
	v_rcp_f32_e32 v178, v178
	v_rcp_f32_e32 v179, v179
	v_mul_f32_e32 v176, v62, v176
	v_mul_f32_e32 v177, v63, v177
	v_mul_f32_e32 v178, v64, v178
	v_mul_f32_e32 v179, v65, v179
	v_cvt_pk_bf16_f32 v148, v176, v177
	v_cvt_pk_bf16_f32 v149, v178, v179
	v_mul_f32_e32 v176, 0xbfb8aa3b, v58
	v_mul_f32_e32 v177, 0xbfb8aa3b, v59
	v_mul_f32_e32 v178, 0xbfb8aa3b, v60
	v_mul_f32_e32 v179, 0xbfb8aa3b, v61
	v_exp_f32_e32 v176, v176
	v_exp_f32_e32 v177, v177
	v_exp_f32_e32 v178, v178
	v_exp_f32_e32 v179, v179
	v_add_f32_e32 v176, 1.0, v176
	v_add_f32_e32 v177, 1.0, v177
	v_add_f32_e32 v178, 1.0, v178
	v_add_f32_e32 v179, 1.0, v179
	v_rcp_f32_e32 v176, v176
	v_rcp_f32_e32 v177, v177
	v_rcp_f32_e32 v178, v178
	v_rcp_f32_e32 v179, v179
	v_mul_f32_e32 v176, v58, v176
	v_mul_f32_e32 v177, v59, v177
	v_mul_f32_e32 v178, v60, v178
	v_mul_f32_e32 v179, v61, v179
	v_cvt_pk_bf16_f32 v150, v176, v177
	v_cvt_pk_bf16_f32 v151, v178, v179
	s_nop 1
	v_permlane16_swap_b32_e32 v144, v146
	v_permlane16_swap_b32_e32 v145, v147
	global_store_dwordx4 v[166:167], v[144:147], off offset:256 nt
	v_mul_f32_e32 v176, 0xbfb8aa3b, v54
	v_mul_f32_e32 v177, 0xbfb8aa3b, v55
	v_mul_f32_e32 v178, 0xbfb8aa3b, v56
	v_mul_f32_e32 v179, 0xbfb8aa3b, v57
	v_exp_f32_e32 v176, v176
	v_exp_f32_e32 v177, v177
	v_exp_f32_e32 v178, v178
	v_exp_f32_e32 v179, v179
	v_add_f32_e32 v176, 1.0, v176
	v_add_f32_e32 v177, 1.0, v177
	v_add_f32_e32 v178, 1.0, v178
	v_add_f32_e32 v179, 1.0, v179
	v_rcp_f32_e32 v176, v176
	v_rcp_f32_e32 v177, v177
	v_rcp_f32_e32 v178, v178
	v_rcp_f32_e32 v179, v179
	v_mul_f32_e32 v176, v54, v176
	v_mul_f32_e32 v177, v55, v177
	v_mul_f32_e32 v178, v56, v178
	v_mul_f32_e32 v179, v57, v179
	v_cvt_pk_bf16_f32 v140, v176, v177
	v_cvt_pk_bf16_f32 v141, v178, v179
	v_mul_f32_e32 v176, 0xbfb8aa3b, v50
	v_mul_f32_e32 v177, 0xbfb8aa3b, v51
	v_mul_f32_e32 v178, 0xbfb8aa3b, v52
	v_mul_f32_e32 v179, 0xbfb8aa3b, v53
	v_exp_f32_e32 v176, v176
	v_exp_f32_e32 v177, v177
	v_exp_f32_e32 v178, v178
	v_exp_f32_e32 v179, v179
	v_add_f32_e32 v176, 1.0, v176
	v_add_f32_e32 v177, 1.0, v177
	v_add_f32_e32 v178, 1.0, v178
	v_add_f32_e32 v179, 1.0, v179
	v_rcp_f32_e32 v176, v176
	v_rcp_f32_e32 v177, v177
	v_rcp_f32_e32 v178, v178
	v_rcp_f32_e32 v179, v179
	v_mul_f32_e32 v176, v50, v176
	v_mul_f32_e32 v177, v51, v177
	v_mul_f32_e32 v178, v52, v178
	v_mul_f32_e32 v179, v53, v179
	v_cvt_pk_bf16_f32 v142, v176, v177
	v_cvt_pk_bf16_f32 v143, v178, v179
	s_nop 1
	v_permlane16_swap_b32_e32 v148, v150
	v_permlane16_swap_b32_e32 v149, v151
	global_store_dwordx4 v[168:169], v[148:151], off nt
	v_mul_f32_e32 v176, 0xbfb8aa3b, v46
	v_mul_f32_e32 v177, 0xbfb8aa3b, v47
	v_mul_f32_e32 v178, 0xbfb8aa3b, v48
	v_mul_f32_e32 v179, 0xbfb8aa3b, v49
	v_exp_f32_e32 v176, v176
	v_exp_f32_e32 v177, v177
	v_exp_f32_e32 v178, v178
	v_exp_f32_e32 v179, v179
	v_add_f32_e32 v176, 1.0, v176
	v_add_f32_e32 v177, 1.0, v177
; __device__ __forceinline__ unsigned pack2(float a, float b) { const f32x2_t v = {a, b}; const bf16x2_t r = __builtin_convertvector(v, bf16x2_t); return __builtin_bit_cast(unsigned, r); }
; __device__ __forceinline__ void ph_proj(const Params& p, int l, char* shm) {
;     ...
;           if (act == 1) xv = xv * __builtin_amdgcn_rcpf(1.f + __expf(-xv));
;           else if (act == 2) xv = 0.5f * xv * (1.f + erf_fast(xv * 0.70710678118654752f));
;           y[j] = xv;
;         }
;         *(uint2*)(p.P + (size_t)(brow + r) * NP + pn * 256 + c) = uint2{pack2(y[0], y[1]), pack2(y[2], y[3])};
	v_add_f32_e32 v178, 1.0, v178
	v_add_f32_e32 v179, 1.0, v179
	v_rcp_f32_e32 v176, v176
	v_rcp_f32_e32 v177, v177
	v_rcp_f32_e32 v178, v178
	v_rcp_f32_e32 v179, v179
	v_mul_f32_e32 v176, v46, v176
	v_mul_f32_e32 v177, v47, v177
	v_mul_f32_e32 v178, v48, v178
	v_mul_f32_e32 v179, v49, v179
	v_cvt_pk_bf16_f32 v144, v176, v177
	v_cvt_pk_bf16_f32 v145, v178, v179
	v_mul_f32_e32 v176, 0xbfb8aa3b, v42
	v_mul_f32_e32 v177, 0xbfb8aa3b, v43
	v_mul_f32_e32 v178, 0xbfb8aa3b, v44
	v_mul_f32_e32 v179, 0xbfb8aa3b, v45
	v_exp_f32_e32 v176, v176
	v_exp_f32_e32 v177, v177
	v_exp_f32_e32 v178, v178
	v_exp_f32_e32 v179, v179
	v_add_f32_e32 v176, 1.0, v176
	v_add_f32_e32 v177, 1.0, v177
	v_add_f32_e32 v178, 1.0, v178
	v_add_f32_e32 v179, 1.0, v179
	v_rcp_f32_e32 v176, v176
	v_rcp_f32_e32 v177, v177
	v_rcp_f32_e32 v178, v178
	v_rcp_f32_e32 v179, v179
	v_mul_f32_e32 v176, v42, v176
	v_mul_f32_e32 v177, v43, v177
	v_mul_f32_e32 v178, v44, v178
	v_mul_f32_e32 v179, v45, v179
	v_cvt_pk_bf16_f32 v146, v176, v177
	v_cvt_pk_bf16_f32 v147, v178, v179
	s_nop 1
	v_permlane16_swap_b32_e32 v140, v142
	v_permlane16_swap_b32_e32 v141, v143
	global_store_dwordx4 v[170:171], v[140:143], off nt
	v_mul_f32_e32 v176, 0xbfb8aa3b, v38
	v_mul_f32_e32 v177, 0xbfb8aa3b, v39
	v_mul_f32_e32 v178, 0xbfb8aa3b, v40
	v_mul_f32_e32 v179, 0xbfb8aa3b, v41
	v_exp_f32_e32 v176, v176
	v_exp_f32_e32 v177, v177
	v_exp_f32_e32 v178, v178
	v_exp_f32_e32 v179, v179
	v_add_f32_e32 v176, 1.0, v176
	v_add_f32_e32 v177, 1.0, v177
	v_add_f32_e32 v178, 1.0, v178
	v_add_f32_e32 v179, 1.0, v179
	v_rcp_f32_e32 v176, v176
	v_rcp_f32_e32 v177, v177
	v_rcp_f32_e32 v178, v178
	v_rcp_f32_e32 v179, v179
	v_mul_f32_e32 v176, v38, v176
	v_mul_f32_e32 v177, v39, v177
	v_mul_f32_e32 v178, v40, v178
	v_mul_f32_e32 v179, v41, v179
	v_cvt_pk_bf16_f32 v148, v176, v177
	v_cvt_pk_bf16_f32 v149, v178, v179
	v_mul_f32_e32 v176, 0xbfb8aa3b, v34
	v_mul_f32_e32 v177, 0xbfb8aa3b, v35
	v_mul_f32_e32 v178, 0xbfb8aa3b, v36
	v_mul_f32_e32 v179, 0xbfb8aa3b, v37
	v_exp_f32_e32 v176, v176
	v_exp_f32_e32 v177, v177
	v_exp_f32_e32 v178, v178
	v_exp_f32_e32 v179, v179
	v_add_f32_e32 v176, 1.0, v176
	v_add_f32_e32 v177, 1.0, v177
	v_add_f32_e32 v178, 1.0, v178
	v_add_f32_e32 v179, 1.0, v179
	v_rcp_f32_e32 v176, v176
	v_rcp_f32_e32 v177, v177
	v_rcp_f32_e32 v178, v178
	v_rcp_f32_e32 v179, v179
	v_mul_f32_e32 v176, v34, v176
	v_mul_f32_e32 v177, v35, v177
	v_mul_f32_e32 v178, v36, v178
	v_mul_f32_e32 v179, v37, v179
	v_cvt_pk_bf16_f32 v150, v176, v177
	v_cvt_pk_bf16_f32 v151, v178, v179
	s_nop 1
	v_permlane16_swap_b32_e32 v144, v146
	v_permlane16_swap_b32_e32 v145, v147
	global_store_dwordx4 v[172:173], v[144:147], off nt
	v_mul_f32_e32 v176, 0xbfb8aa3b, v28
	v_mul_f32_e32 v177, 0xbfb8aa3b, v29
	v_mul_f32_e32 v178, 0xbfb8aa3b, v30
	v_mul_f32_e32 v179, 0xbfb8aa3b, v31
	v_exp_f32_e32 v176, v176
	v_exp_f32_e32 v177, v177
	v_exp_f32_e32 v178, v178
	v_exp_f32_e32 v179, v179
	v_add_f32_e32 v176, 1.0, v176
	v_add_f32_e32 v177, 1.0, v177
	v_add_f32_e32 v178, 1.0, v178
	v_add_f32_e32 v179, 1.0, v179
	v_rcp_f32_e32 v176, v176
	v_rcp_f32_e32 v177, v177
	v_rcp_f32_e32 v178, v178
	v_rcp_f32_e32 v179, v179
	v_mul_f32_e32 v176, v28, v176
	v_mul_f32_e32 v177, v29, v177
	v_mul_f32_e32 v178, v30, v178
	v_mul_f32_e32 v179, v31, v179
	v_cvt_pk_bf16_f32 v140, v176, v177
	v_cvt_pk_bf16_f32 v141, v178, v179
	v_mul_f32_e32 v176, 0xbfb8aa3b, v24
	v_mul_f32_e32 v177, 0xbfb8aa3b, v25
	v_mul_f32_e32 v178, 0xbfb8aa3b, v26
	v_mul_f32_e32 v179, 0xbfb8aa3b, v27
	v_exp_f32_e32 v176, v176
	v_exp_f32_e32 v177, v177
	v_exp_f32_e32 v178, v178
	v_exp_f32_e32 v179, v179
	v_add_f32_e32 v176, 1.0, v176
	v_add_f32_e32 v177, 1.0, v177
	v_add_f32_e32 v178, 1.0, v178
	v_add_f32_e32 v179, 1.0, v179
	v_rcp_f32_e32 v176, v176
	v_rcp_f32_e32 v177, v177
	v_rcp_f32_e32 v178, v178
	v_rcp_f32_e32 v179, v179
	v_mul_f32_e32 v176, v24, v176
	v_mul_f32_e32 v177, v25, v177
	v_mul_f32_e32 v178, v26, v178
	v_mul_f32_e32 v179, v27, v179
	v_cvt_pk_bf16_f32 v142, v176, v177
	v_cvt_pk_bf16_f32 v143, v178, v179
	s_nop 1
	v_permlane16_swap_b32_e32 v148, v150
	v_permlane16_swap_b32_e32 v149, v151
	global_store_dwordx4 v[174:175], v[148:151], off nt
	v_mul_f32_e32 v176, 0xbfb8aa3b, v20
	v_mul_f32_e32 v177, 0xbfb8aa3b, v21
	v_mul_f32_e32 v178, 0xbfb8aa3b, v22
	v_mul_f32_e32 v179, 0xbfb8aa3b, v23
	v_exp_f32_e32 v176, v176
	v_exp_f32_e32 v177, v177
	v_exp_f32_e32 v178, v178
	v_exp_f32_e32 v179, v179
	v_add_f32_e32 v176, 1.0, v176
	v_add_f32_e32 v177, 1.0, v177
	v_add_f32_e32 v178, 1.0, v178
	v_add_f32_e32 v179, 1.0, v179
	v_rcp_f32_e32 v176, v176
	v_rcp_f32_e32 v177, v177
	v_rcp_f32_e32 v178, v178
	v_rcp_f32_e32 v179, v179
	v_mul_f32_e32 v176, v20, v176
	v_mul_f32_e32 v177, v21, v177
	v_mul_f32_e32 v178, v22, v178
	v_mul_f32_e32 v179, v23, v179
	v_cvt_pk_bf16_f32 v144, v176, v177
	v_cvt_pk_bf16_f32 v145, v178, v179
	v_mul_f32_e32 v176, 0xbfb8aa3b, v16
	v_mul_f32_e32 v177, 0xbfb8aa3b, v17
	v_mul_f32_e32 v178, 0xbfb8aa3b, v18
	v_mul_f32_e32 v179, 0xbfb8aa3b, v19
	v_exp_f32_e32 v176, v176
	v_exp_f32_e32 v177, v177
	v_exp_f32_e32 v178, v178
	v_exp_f32_e32 v179, v179
	v_add_f32_e32 v176, 1.0, v176
	v_add_f32_e32 v177, 1.0, v177
	v_add_f32_e32 v178, 1.0, v178
	v_add_f32_e32 v179, 1.0, v179
	v_rcp_f32_e32 v176, v176
	v_rcp_f32_e32 v177, v177
	v_rcp_f32_e32 v178, v178
	v_rcp_f32_e32 v179, v179
	v_mul_f32_e32 v176, v16, v176
	v_mul_f32_e32 v177, v17, v177
	v_mul_f32_e32 v178, v18, v178
	v_mul_f32_e32 v179, v19, v179
	v_cvt_pk_bf16_f32 v146, v176, v177
	v_cvt_pk_bf16_f32 v147, v178, v179
	s_nop 1
	v_permlane16_swap_b32_e32 v140, v142
	v_permlane16_swap_b32_e32 v141, v143
	global_store_dwordx4 v[168:169], v[140:143], off offset:256 nt
; __device__ __forceinline__ unsigned pack2(float a, float b) { const f32x2_t v = {a, b}; const bf16x2_t r = __builtin_convertvector(v, bf16x2_t); return __builtin_bit_cast(unsigned, r); }
; __device__ __forceinline__ float erf_fast(float x) {
;   const float ax = fabsf(x);
;   const float t = __builtin_amdgcn_rcpf(fmaf(0.3275911f, ax, 1.f));
;   float y = fmaf(1.061405429f, t, -1.453152027f);
;   y = fmaf(y, t, 1.421413741f);
;   y = fmaf(y, t, -0.284496736f);
;   y = fmaf(y, t, 0.254829592f);
;   y = 1.f - y * t * __expf(-ax * ax);
;   return copysignf(y, x);
; }
; __device__ __forceinline__ void ph_proj(const Params& p, int l, char* shm) {
;     ...
;           if (act == 1) xv = xv * __builtin_amdgcn_rcpf(1.f + __expf(-xv));
;           else if (act == 2) xv = 0.5f * xv * (1.f + erf_fast(xv * 0.70710678118654752f));
;           y[j] = xv;
;         }
;         *(uint2*)(p.P + (size_t)(brow + r) * NP + pn * 256 + c) = uint2{pack2(y[0], y[1]), pack2(y[2], y[3])};
	v_mul_f32_e32 v176, 0xbfb8aa3b, v12
	v_mul_f32_e32 v177, 0xbfb8aa3b, v13
	v_mul_f32_e32 v178, 0xbfb8aa3b, v14
	v_mul_f32_e32 v179, 0xbfb8aa3b, v15
	v_exp_f32_e32 v176, v176
	v_exp_f32_e32 v177, v177
	v_exp_f32_e32 v178, v178
	v_exp_f32_e32 v179, v179
	v_add_f32_e32 v176, 1.0, v176
	v_add_f32_e32 v177, 1.0, v177
	v_add_f32_e32 v178, 1.0, v178
	v_add_f32_e32 v179, 1.0, v179
	v_rcp_f32_e32 v176, v176
	v_rcp_f32_e32 v177, v177
	v_rcp_f32_e32 v178, v178
	v_rcp_f32_e32 v179, v179
	v_mul_f32_e32 v176, v12, v176
	v_mul_f32_e32 v177, v13, v177
	v_mul_f32_e32 v178, v14, v178
	v_mul_f32_e32 v179, v15, v179
	v_cvt_pk_bf16_f32 v148, v176, v177
	v_cvt_pk_bf16_f32 v149, v178, v179
	v_mul_f32_e32 v176, 0xbfb8aa3b, v8
	v_mul_f32_e32 v177, 0xbfb8aa3b, v9
	v_mul_f32_e32 v178, 0xbfb8aa3b, v10
	v_mul_f32_e32 v179, 0xbfb8aa3b, v11
	v_exp_f32_e32 v176, v176
	v_exp_f32_e32 v177, v177
	v_exp_f32_e32 v178, v178
	v_exp_f32_e32 v179, v179
	v_add_f32_e32 v176, 1.0, v176
	v_add_f32_e32 v177, 1.0, v177
	v_add_f32_e32 v178, 1.0, v178
	v_add_f32_e32 v179, 1.0, v179
	v_rcp_f32_e32 v176, v176
	v_rcp_f32_e32 v177, v177
	v_rcp_f32_e32 v178, v178
	v_rcp_f32_e32 v179, v179
	v_mul_f32_e32 v176, v8, v176
	v_mul_f32_e32 v177, v9, v177
	v_mul_f32_e32 v178, v10, v178
	v_mul_f32_e32 v179, v11, v179
	v_cvt_pk_bf16_f32 v150, v176, v177
	v_cvt_pk_bf16_f32 v151, v178, v179
	s_nop 1
	v_permlane16_swap_b32_e32 v144, v146
	v_permlane16_swap_b32_e32 v145, v147
	global_store_dwordx4 v[170:171], v[144:147], off offset:256 nt
	v_mul_f32_e32 v176, 0xbfb8aa3b, v4
	v_mul_f32_e32 v177, 0xbfb8aa3b, v5
	v_mul_f32_e32 v178, 0xbfb8aa3b, v6
	v_mul_f32_e32 v179, 0xbfb8aa3b, v7
	v_exp_f32_e32 v176, v176
	v_exp_f32_e32 v177, v177
	v_exp_f32_e32 v178, v178
	v_exp_f32_e32 v179, v179
	v_add_f32_e32 v176, 1.0, v176
	v_add_f32_e32 v177, 1.0, v177
	v_add_f32_e32 v178, 1.0, v178
	v_add_f32_e32 v179, 1.0, v179
	v_rcp_f32_e32 v176, v176
	v_rcp_f32_e32 v177, v177
	v_rcp_f32_e32 v178, v178
	v_rcp_f32_e32 v179, v179
	v_mul_f32_e32 v176, v4, v176
	v_mul_f32_e32 v177, v5, v177
	v_mul_f32_e32 v178, v6, v178
	v_mul_f32_e32 v179, v7, v179
	v_cvt_pk_bf16_f32 v140, v176, v177
	v_cvt_pk_bf16_f32 v141, v178, v179
	v_mul_f32_e32 v176, 0xbfb8aa3b, v0
	v_mul_f32_e32 v177, 0xbfb8aa3b, v1
	v_mul_f32_e32 v178, 0xbfb8aa3b, v2
	v_mul_f32_e32 v179, 0xbfb8aa3b, v3
	v_exp_f32_e32 v176, v176
	v_exp_f32_e32 v177, v177
	v_exp_f32_e32 v178, v178
	v_exp_f32_e32 v179, v179
	v_add_f32_e32 v176, 1.0, v176
	v_add_f32_e32 v177, 1.0, v177
	v_add_f32_e32 v178, 1.0, v178
	v_add_f32_e32 v179, 1.0, v179
	v_rcp_f32_e32 v176, v176
	v_rcp_f32_e32 v177, v177
	v_rcp_f32_e32 v178, v178
	v_rcp_f32_e32 v179, v179
	v_mul_f32_e32 v176, v0, v176
	v_mul_f32_e32 v177, v1, v177
	v_mul_f32_e32 v178, v2, v178
	v_mul_f32_e32 v179, v3, v179
	v_cvt_pk_bf16_f32 v142, v176, v177
	v_cvt_pk_bf16_f32 v143, v178, v179
	s_nop 1
	v_permlane16_swap_b32_e32 v148, v150
	v_permlane16_swap_b32_e32 v149, v151
	global_store_dwordx4 v[172:173], v[148:151], off offset:256 nt
	s_nop 1
	v_permlane16_swap_b32_e32 v140, v142
	v_permlane16_swap_b32_e32 v141, v143
	global_store_dwordx4 v[174:175], v[140:143], off offset:256 nt
	s_branch .LBB0_958
.Lpj_gelu:
	s_mov_b32 s9, 0x3ea7ba05
	s_brev_b32 s10, -2
	v_mul_f32_e32 v176, 0x3f3504f3, v126
	v_mul_f32_e32 v177, 0x3f3504f3, v127
	v_mul_f32_e32 v178, 0x3f3504f3, v128
	v_mul_f32_e32 v179, 0x3f3504f3, v129
	v_fma_f32 v180, |v176|, s9, 1.0
	v_fma_f32 v181, |v177|, s9, 1.0
	v_fma_f32 v182, |v178|, s9, 1.0
	v_fma_f32 v183, |v179|, s9, 1.0
	v_rcp_f32_e32 v180, v180
	v_rcp_f32_e32 v181, v181
	v_rcp_f32_e32 v182, v182
	v_rcp_f32_e32 v183, v183
	v_mul_f32_e32 v188, 0.5, v126
	v_mul_f32_e32 v189, 0.5, v127
	v_mul_f32_e32 v190, 0.5, v128
	v_mul_f32_e32 v191, 0.5, v129
	v_fmamk_f32 v184, v180, 0x3f87dc22, v206
	v_fmamk_f32 v185, v181, 0x3f87dc22, v206
	v_fmamk_f32 v186, v182, 0x3f87dc22, v206
	v_fmamk_f32 v187, v183, 0x3f87dc22, v206
	v_fmaak_f32 v184, v184, v180, 0x3fb5f0e3
	v_fmaak_f32 v185, v185, v181, 0x3fb5f0e3
	v_fmaak_f32 v186, v186, v182, 0x3fb5f0e3
	v_fmaak_f32 v187, v187, v183, 0x3fb5f0e3
	v_fmaak_f32 v184, v184, v180, 0xbe91a98e
	v_fmaak_f32 v185, v185, v181, 0xbe91a98e
	v_fmaak_f32 v186, v186, v182, 0xbe91a98e
	v_fmaak_f32 v187, v187, v183, 0xbe91a98e
	v_fmaak_f32 v184, v184, v180, 0x3e827906
	v_fmaak_f32 v185, v185, v181, 0x3e827906
	v_fmaak_f32 v186, v186, v182, 0x3e827906
	v_fmaak_f32 v187, v187, v183, 0x3e827906
	v_mul_f32_e32 v180, v180, v184
	v_mul_f32_e32 v181, v181, v185
	v_mul_f32_e32 v182, v182, v186
	v_mul_f32_e32 v183, v183, v187
	v_mul_f32_e64 v184, |v176|, |v176|
	v_mul_f32_e64 v185, |v177|, |v177|
	v_mul_f32_e64 v186, |v178|, |v178|
	v_mul_f32_e64 v187, |v179|, |v179|
	v_mul_f32_e32 v184, 0xbfb8aa3b, v184
	v_mul_f32_e32 v185, 0xbfb8aa3b, v185
	v_mul_f32_e32 v186, 0xbfb8aa3b, v186
	v_mul_f32_e32 v187, 0xbfb8aa3b, v187
	v_exp_f32_e32 v184, v184
	v_exp_f32_e32 v185, v185
	v_exp_f32_e32 v186, v186
	v_exp_f32_e32 v187, v187
	v_fma_f32 v180, -v184, v180, 1.0
	v_fma_f32 v181, -v185, v181, 1.0
	v_fma_f32 v182, -v186, v182, 1.0
	v_fma_f32 v183, -v187, v183, 1.0
	v_bfi_b32 v176, s10, v180, v176
	v_bfi_b32 v177, s10, v181, v177
	v_bfi_b32 v178, s10, v182, v178
	v_bfi_b32 v179, s10, v183, v179
	v_add_f32_e32 v176, 1.0, v176
	v_add_f32_e32 v177, 1.0, v177
	v_add_f32_e32 v178, 1.0, v178
	v_add_f32_e32 v179, 1.0, v179
	v_mul_f32_e32 v188, v188, v176
	v_mul_f32_e32 v189, v189, v177
	v_mul_f32_e32 v190, v190, v178
	v_mul_f32_e32 v191, v191, v179
	v_cvt_pk_bf16_f32 v140, v188, v189
	v_cvt_pk_bf16_f32 v141, v190, v191
	v_mul_f32_e32 v176, 0x3f3504f3, v122
	v_mul_f32_e32 v177, 0x3f3504f3, v123
	v_mul_f32_e32 v178, 0x3f3504f3, v124
; __device__ __forceinline__ float erf_fast(float x) {
;   const float ax = fabsf(x);
;   const float t = __builtin_amdgcn_rcpf(fmaf(0.3275911f, ax, 1.f));
;   float y = fmaf(1.061405429f, t, -1.453152027f);
;   y = fmaf(y, t, 1.421413741f);
;   y = fmaf(y, t, -0.284496736f);
;   y = fmaf(y, t, 0.254829592f);
;   y = 1.f - y * t * __expf(-ax * ax);
;   return copysignf(y, x);
; }
; __device__ __forceinline__ void ph_proj(const Params& p, int l, char* shm) {
;     ...
;           else if (act == 2) xv = 0.5f * xv * (1.f + erf_fast(xv * 0.70710678118654752f));
	v_mul_f32_e32 v179, 0x3f3504f3, v125
	v_fma_f32 v180, |v176|, s9, 1.0
	v_fma_f32 v181, |v177|, s9, 1.0
	v_fma_f32 v182, |v178|, s9, 1.0
	v_fma_f32 v183, |v179|, s9, 1.0
	v_rcp_f32_e32 v180, v180
	v_rcp_f32_e32 v181, v181
	v_rcp_f32_e32 v182, v182
	v_rcp_f32_e32 v183, v183
	v_mul_f32_e32 v188, 0.5, v122
	v_mul_f32_e32 v189, 0.5, v123
	v_mul_f32_e32 v190, 0.5, v124
	v_mul_f32_e32 v191, 0.5, v125
	v_fmamk_f32 v184, v180, 0x3f87dc22, v206
	v_fmamk_f32 v185, v181, 0x3f87dc22, v206
	v_fmamk_f32 v186, v182, 0x3f87dc22, v206
	v_fmamk_f32 v187, v183, 0x3f87dc22, v206
	v_fmaak_f32 v184, v184, v180, 0x3fb5f0e3
	v_fmaak_f32 v185, v185, v181, 0x3fb5f0e3
	v_fmaak_f32 v186, v186, v182, 0x3fb5f0e3
	v_fmaak_f32 v187, v187, v183, 0x3fb5f0e3
	v_fmaak_f32 v184, v184, v180, 0xbe91a98e
	v_fmaak_f32 v185, v185, v181, 0xbe91a98e
	v_fmaak_f32 v186, v186, v182, 0xbe91a98e
	v_fmaak_f32 v187, v187, v183, 0xbe91a98e
	v_fmaak_f32 v184, v184, v180, 0x3e827906
	v_fmaak_f32 v185, v185, v181, 0x3e827906
	v_fmaak_f32 v186, v186, v182, 0x3e827906
	v_fmaak_f32 v187, v187, v183, 0x3e827906
	v_mul_f32_e32 v180, v180, v184
	v_mul_f32_e32 v181, v181, v185
	v_mul_f32_e32 v182, v182, v186
	v_mul_f32_e32 v183, v183, v187
	v_mul_f32_e64 v184, |v176|, |v176|
	v_mul_f32_e64 v185, |v177|, |v177|
	v_mul_f32_e64 v186, |v178|, |v178|
	v_mul_f32_e64 v187, |v179|, |v179|
	v_mul_f32_e32 v184, 0xbfb8aa3b, v184
	v_mul_f32_e32 v185, 0xbfb8aa3b, v185
	v_mul_f32_e32 v186, 0xbfb8aa3b, v186
	v_mul_f32_e32 v187, 0xbfb8aa3b, v187
	v_exp_f32_e32 v184, v184
	v_exp_f32_e32 v185, v185
	v_exp_f32_e32 v186, v186
	v_exp_f32_e32 v187, v187
	v_fma_f32 v180, -v184, v180, 1.0
	v_fma_f32 v181, -v185, v181, 1.0
	v_fma_f32 v182, -v186, v182, 1.0
	v_fma_f32 v183, -v187, v183, 1.0
	v_bfi_b32 v176, s10, v180, v176
	v_bfi_b32 v177, s10, v181, v177
	v_bfi_b32 v178, s10, v182, v178
	v_bfi_b32 v179, s10, v183, v179
	v_add_f32_e32 v176, 1.0, v176
	v_add_f32_e32 v177, 1.0, v177
	v_add_f32_e32 v178, 1.0, v178
	v_add_f32_e32 v179, 1.0, v179
	v_mul_f32_e32 v188, v188, v176
	v_mul_f32_e32 v189, v189, v177
	v_mul_f32_e32 v190, v190, v178
	v_mul_f32_e32 v191, v191, v179
	v_cvt_pk_bf16_f32 v142, v188, v189
	v_cvt_pk_bf16_f32 v143, v190, v191
	v_mul_f32_e32 v176, 0x3f3504f3, v118
	v_mul_f32_e32 v177, 0x3f3504f3, v119
	v_mul_f32_e32 v178, 0x3f3504f3, v120
	v_mul_f32_e32 v179, 0x3f3504f3, v121
	v_fma_f32 v180, |v176|, s9, 1.0
	v_fma_f32 v181, |v177|, s9, 1.0
	v_fma_f32 v182, |v178|, s9, 1.0
	v_fma_f32 v183, |v179|, s9, 1.0
	v_rcp_f32_e32 v180, v180
	v_rcp_f32_e32 v181, v181
	v_rcp_f32_e32 v182, v182
	v_rcp_f32_e32 v183, v183
	v_mul_f32_e32 v188, 0.5, v118
	v_mul_f32_e32 v189, 0.5, v119
	v_mul_f32_e32 v190, 0.5, v120
	v_mul_f32_e32 v191, 0.5, v121
	v_fmamk_f32 v184, v180, 0x3f87dc22, v206
	v_fmamk_f32 v185, v181, 0x3f87dc22, v206
	v_fmamk_f32 v186, v182, 0x3f87dc22, v206
	v_fmamk_f32 v187, v183, 0x3f87dc22, v206
	v_fmaak_f32 v184, v184, v180, 0x3fb5f0e3
	v_fmaak_f32 v185, v185, v181, 0x3fb5f0e3
	v_fmaak_f32 v186, v186, v182, 0x3fb5f0e3
	v_fmaak_f32 v187, v187, v183, 0x3fb5f0e3
	v_fmaak_f32 v184, v184, v180, 0xbe91a98e
	v_fmaak_f32 v185, v185, v181, 0xbe91a98e
	v_fmaak_f32 v186, v186, v182, 0xbe91a98e
	v_fmaak_f32 v187, v187, v183, 0xbe91a98e
	v_fmaak_f32 v184, v184, v180, 0x3e827906
	v_fmaak_f32 v185, v185, v181, 0x3e827906
	v_fmaak_f32 v186, v186, v182, 0x3e827906
	v_fmaak_f32 v187, v187, v183, 0x3e827906
	v_mul_f32_e32 v180, v180, v184
	v_mul_f32_e32 v181, v181, v185
	v_mul_f32_e32 v182, v182, v186
	v_mul_f32_e32 v183, v183, v187
	v_mul_f32_e64 v184, |v176|, |v176|
	v_mul_f32_e64 v185, |v177|, |v177|
	v_mul_f32_e64 v186, |v178|, |v178|
	v_mul_f32_e64 v187, |v179|, |v179|
	v_mul_f32_e32 v184, 0xbfb8aa3b, v184
	v_mul_f32_e32 v185, 0xbfb8aa3b, v185
	v_mul_f32_e32 v186, 0xbfb8aa3b, v186
	v_mul_f32_e32 v187, 0xbfb8aa3b, v187
	v_exp_f32_e32 v184, v184
	v_exp_f32_e32 v185, v185
	v_exp_f32_e32 v186, v186
	v_exp_f32_e32 v187, v187
	v_fma_f32 v180, -v184, v180, 1.0
	v_fma_f32 v181, -v185, v181, 1.0
	v_fma_f32 v182, -v186, v182, 1.0
	v_fma_f32 v183, -v187, v183, 1.0
	v_bfi_b32 v176, s10, v180, v176
	v_bfi_b32 v177, s10, v181, v177
	v_bfi_b32 v178, s10, v182, v178
	v_bfi_b32 v179, s10, v183, v179
	v_add_f32_e32 v176, 1.0, v176
	v_add_f32_e32 v177, 1.0, v177
	v_add_f32_e32 v178, 1.0, v178
	v_add_f32_e32 v179, 1.0, v179
	v_mul_f32_e32 v188, v188, v176
	v_mul_f32_e32 v189, v189, v177
	v_mul_f32_e32 v190, v190, v178
	v_mul_f32_e32 v191, v191, v179
	v_cvt_pk_bf16_f32 v144, v188, v189
	v_cvt_pk_bf16_f32 v145, v190, v191
	v_mul_f32_e32 v176, 0x3f3504f3, v114
	v_mul_f32_e32 v177, 0x3f3504f3, v115
	v_mul_f32_e32 v178, 0x3f3504f3, v116
	v_mul_f32_e32 v179, 0x3f3504f3, v117
	v_fma_f32 v180, |v176|, s9, 1.0
	v_fma_f32 v181, |v177|, s9, 1.0
	v_fma_f32 v182, |v178|, s9, 1.0
	v_fma_f32 v183, |v179|, s9, 1.0
	v_rcp_f32_e32 v180, v180
	v_rcp_f32_e32 v181, v181
	v_rcp_f32_e32 v182, v182
	v_rcp_f32_e32 v183, v183
	v_mul_f32_e32 v188, 0.5, v114
	v_mul_f32_e32 v189, 0.5, v115
	v_mul_f32_e32 v190, 0.5, v116
	v_mul_f32_e32 v191, 0.5, v117
	v_fmamk_f32 v184, v180, 0x3f87dc22, v206
	v_fmamk_f32 v185, v181, 0x3f87dc22, v206
	v_fmamk_f32 v186, v182, 0x3f87dc22, v206
	v_fmamk_f32 v187, v183, 0x3f87dc22, v206
	v_fmaak_f32 v184, v184, v180, 0x3fb5f0e3
	v_fmaak_f32 v185, v185, v181, 0x3fb5f0e3
	v_fmaak_f32 v186, v186, v182, 0x3fb5f0e3
	v_fmaak_f32 v187, v187, v183, 0x3fb5f0e3
	v_fmaak_f32 v184, v184, v180, 0xbe91a98e
	v_fmaak_f32 v185, v185, v181, 0xbe91a98e
	v_fmaak_f32 v186, v186, v182, 0xbe91a98e
	v_fmaak_f32 v187, v187, v183, 0xbe91a98e
	v_fmaak_f32 v184, v184, v180, 0x3e827906
	v_fmaak_f32 v185, v185, v181, 0x3e827906
	v_fmaak_f32 v186, v186, v182, 0x3e827906
; __device__ __forceinline__ unsigned pack2(float a, float b) { const f32x2_t v = {a, b}; const bf16x2_t r = __builtin_convertvector(v, bf16x2_t); return __builtin_bit_cast(unsigned, r); }
; __device__ __forceinline__ float erf_fast(float x) {
;   const float ax = fabsf(x);
;   const float t = __builtin_amdgcn_rcpf(fmaf(0.3275911f, ax, 1.f));
;   float y = fmaf(1.061405429f, t, -1.453152027f);
;   y = fmaf(y, t, 1.421413741f);
;   y = fmaf(y, t, -0.284496736f);
;   y = fmaf(y, t, 0.254829592f);
;   y = 1.f - y * t * __expf(-ax * ax);
;   return copysignf(y, x);
; }
; __device__ __forceinline__ void ph_proj(const Params& p, int l, char* shm) {
;     ...
;           else if (act == 2) xv = 0.5f * xv * (1.f + erf_fast(xv * 0.70710678118654752f));
;           y[j] = xv;
;         }
;         *(uint2*)(p.P + (size_t)(brow + r) * NP + pn * 256 + c) = uint2{pack2(y[0], y[1]), pack2(y[2], y[3])};
	v_fmaak_f32 v187, v187, v183, 0x3e827906
	v_mul_f32_e32 v180, v180, v184
	v_mul_f32_e32 v181, v181, v185
	v_mul_f32_e32 v182, v182, v186
	v_mul_f32_e32 v183, v183, v187
	v_mul_f32_e64 v184, |v176|, |v176|
	v_mul_f32_e64 v185, |v177|, |v177|
	v_mul_f32_e64 v186, |v178|, |v178|
	v_mul_f32_e64 v187, |v179|, |v179|
	v_mul_f32_e32 v184, 0xbfb8aa3b, v184
	v_mul_f32_e32 v185, 0xbfb8aa3b, v185
	v_mul_f32_e32 v186, 0xbfb8aa3b, v186
	v_mul_f32_e32 v187, 0xbfb8aa3b, v187
	v_exp_f32_e32 v184, v184
	v_exp_f32_e32 v185, v185
	v_exp_f32_e32 v186, v186
	v_exp_f32_e32 v187, v187
	v_fma_f32 v180, -v184, v180, 1.0
	v_fma_f32 v181, -v185, v181, 1.0
	v_fma_f32 v182, -v186, v182, 1.0
	v_fma_f32 v183, -v187, v183, 1.0
	v_bfi_b32 v176, s10, v180, v176
	v_bfi_b32 v177, s10, v181, v177
	v_bfi_b32 v178, s10, v182, v178
	v_bfi_b32 v179, s10, v183, v179
	v_add_f32_e32 v176, 1.0, v176
	v_add_f32_e32 v177, 1.0, v177
	v_add_f32_e32 v178, 1.0, v178
	v_add_f32_e32 v179, 1.0, v179
	v_mul_f32_e32 v188, v188, v176
	v_mul_f32_e32 v189, v189, v177
	v_mul_f32_e32 v190, v190, v178
	v_mul_f32_e32 v191, v191, v179
	v_cvt_pk_bf16_f32 v146, v188, v189
	v_cvt_pk_bf16_f32 v147, v190, v191
	s_nop 1
	v_permlane16_swap_b32_e32 v140, v142
	v_permlane16_swap_b32_e32 v141, v143
	global_store_dwordx4 v[160:161], v[140:143], off nt
	v_mul_f32_e32 v176, 0x3f3504f3, v110
	v_mul_f32_e32 v177, 0x3f3504f3, v111
	v_mul_f32_e32 v178, 0x3f3504f3, v112
	v_mul_f32_e32 v179, 0x3f3504f3, v113
	v_fma_f32 v180, |v176|, s9, 1.0
	v_fma_f32 v181, |v177|, s9, 1.0
	v_fma_f32 v182, |v178|, s9, 1.0
	v_fma_f32 v183, |v179|, s9, 1.0
	v_rcp_f32_e32 v180, v180
	v_rcp_f32_e32 v181, v181
	v_rcp_f32_e32 v182, v182
	v_rcp_f32_e32 v183, v183
	v_mul_f32_e32 v188, 0.5, v110
	v_mul_f32_e32 v189, 0.5, v111
	v_mul_f32_e32 v190, 0.5, v112
	v_mul_f32_e32 v191, 0.5, v113
	v_fmamk_f32 v184, v180, 0x3f87dc22, v206
	v_fmamk_f32 v185, v181, 0x3f87dc22, v206
	v_fmamk_f32 v186, v182, 0x3f87dc22, v206
	v_fmamk_f32 v187, v183, 0x3f87dc22, v206
	v_fmaak_f32 v184, v184, v180, 0x3fb5f0e3
	v_fmaak_f32 v185, v185, v181, 0x3fb5f0e3
	v_fmaak_f32 v186, v186, v182, 0x3fb5f0e3
	v_fmaak_f32 v187, v187, v183, 0x3fb5f0e3
	v_fmaak_f32 v184, v184, v180, 0xbe91a98e
	v_fmaak_f32 v185, v185, v181, 0xbe91a98e
	v_fmaak_f32 v186, v186, v182, 0xbe91a98e
	v_fmaak_f32 v187, v187, v183, 0xbe91a98e
	v_fmaak_f32 v184, v184, v180, 0x3e827906
	v_fmaak_f32 v185, v185, v181, 0x3e827906
	v_fmaak_f32 v186, v186, v182, 0x3e827906
	v_fmaak_f32 v187, v187, v183, 0x3e827906
	v_mul_f32_e32 v180, v180, v184
	v_mul_f32_e32 v181, v181, v185
	v_mul_f32_e32 v182, v182, v186
	v_mul_f32_e32 v183, v183, v187
	v_mul_f32_e64 v184, |v176|, |v176|
	v_mul_f32_e64 v185, |v177|, |v177|
	v_mul_f32_e64 v186, |v178|, |v178|
	v_mul_f32_e64 v187, |v179|, |v179|
	v_mul_f32_e32 v184, 0xbfb8aa3b, v184
	v_mul_f32_e32 v185, 0xbfb8aa3b, v185
	v_mul_f32_e32 v186, 0xbfb8aa3b, v186
	v_mul_f32_e32 v187, 0xbfb8aa3b, v187
	v_exp_f32_e32 v184, v184
	v_exp_f32_e32 v185, v185
	v_exp_f32_e32 v186, v186
	v_exp_f32_e32 v187, v187
	v_fma_f32 v180, -v184, v180, 1.0
	v_fma_f32 v181, -v185, v181, 1.0
	v_fma_f32 v182, -v186, v182, 1.0
	v_fma_f32 v183, -v187, v183, 1.0
	v_bfi_b32 v176, s10, v180, v176
	v_bfi_b32 v177, s10, v181, v177
	v_bfi_b32 v178, s10, v182, v178
	v_bfi_b32 v179, s10, v183, v179
	v_add_f32_e32 v176, 1.0, v176
	v_add_f32_e32 v177, 1.0, v177
	v_add_f32_e32 v178, 1.0, v178
	v_add_f32_e32 v179, 1.0, v179
	v_mul_f32_e32 v188, v188, v176
	v_mul_f32_e32 v189, v189, v177
	v_mul_f32_e32 v190, v190, v178
	v_mul_f32_e32 v191, v191, v179
	v_cvt_pk_bf16_f32 v148, v188, v189
	v_cvt_pk_bf16_f32 v149, v190, v191
	v_mul_f32_e32 v176, 0x3f3504f3, v106
	v_mul_f32_e32 v177, 0x3f3504f3, v107
	v_mul_f32_e32 v178, 0x3f3504f3, v108
	v_mul_f32_e32 v179, 0x3f3504f3, v109
	v_fma_f32 v180, |v176|, s9, 1.0
	v_fma_f32 v181, |v177|, s9, 1.0
	v_fma_f32 v182, |v178|, s9, 1.0
	v_fma_f32 v183, |v179|, s9, 1.0
	v_rcp_f32_e32 v180, v180
	v_rcp_f32_e32 v181, v181
	v_rcp_f32_e32 v182, v182
	v_rcp_f32_e32 v183, v183
	v_mul_f32_e32 v188, 0.5, v106
	v_mul_f32_e32 v189, 0.5, v107
	v_mul_f32_e32 v190, 0.5, v108
	v_mul_f32_e32 v191, 0.5, v109
	v_fmamk_f32 v184, v180, 0x3f87dc22, v206
	v_fmamk_f32 v185, v181, 0x3f87dc22, v206
	v_fmamk_f32 v186, v182, 0x3f87dc22, v206
	v_fmamk_f32 v187, v183, 0x3f87dc22, v206
	v_fmaak_f32 v184, v184, v180, 0x3fb5f0e3
	v_fmaak_f32 v185, v185, v181, 0x3fb5f0e3
	v_fmaak_f32 v186, v186, v182, 0x3fb5f0e3
	v_fmaak_f32 v187, v187, v183, 0x3fb5f0e3
	v_fmaak_f32 v184, v184, v180, 0xbe91a98e
	v_fmaak_f32 v185, v185, v181, 0xbe91a98e
	v_fmaak_f32 v186, v186, v182, 0xbe91a98e
	v_fmaak_f32 v187, v187, v183, 0xbe91a98e
	v_fmaak_f32 v184, v184, v180, 0x3e827906
	v_fmaak_f32 v185, v185, v181, 0x3e827906
	v_fmaak_f32 v186, v186, v182, 0x3e827906
	v_fmaak_f32 v187, v187, v183, 0x3e827906
	v_mul_f32_e32 v180, v180, v184
	v_mul_f32_e32 v181, v181, v185
	v_mul_f32_e32 v182, v182, v186
	v_mul_f32_e32 v183, v183, v187
	v_mul_f32_e64 v184, |v176|, |v176|
	v_mul_f32_e64 v185, |v177|, |v177|
	v_mul_f32_e64 v186, |v178|, |v178|
	v_mul_f32_e64 v187, |v179|, |v179|
	v_mul_f32_e32 v184, 0xbfb8aa3b, v184
	v_mul_f32_e32 v185, 0xbfb8aa3b, v185
	v_mul_f32_e32 v186, 0xbfb8aa3b, v186
	v_mul_f32_e32 v187, 0xbfb8aa3b, v187
	v_exp_f32_e32 v184, v184
	v_exp_f32_e32 v185, v185
	v_exp_f32_e32 v186, v186
	v_exp_f32_e32 v187, v187
	v_fma_f32 v180, -v184, v180, 1.0
	v_fma_f32 v181, -v185, v181, 1.0
	v_fma_f32 v182, -v186, v182, 1.0
	v_fma_f32 v183, -v187, v183, 1.0
	v_bfi_b32 v176, s10, v180, v176
	v_bfi_b32 v177, s10, v181, v177
	v_bfi_b32 v178, s10, v182, v178
	v_bfi_b32 v179, s10, v183, v179
	v_add_f32_e32 v176, 1.0, v176
	v_add_f32_e32 v177, 1.0, v177
; __device__ __forceinline__ unsigned pack2(float a, float b) { const f32x2_t v = {a, b}; const bf16x2_t r = __builtin_convertvector(v, bf16x2_t); return __builtin_bit_cast(unsigned, r); }
; __device__ __forceinline__ float erf_fast(float x) {
;   const float ax = fabsf(x);
;   const float t = __builtin_amdgcn_rcpf(fmaf(0.3275911f, ax, 1.f));
;   float y = fmaf(1.061405429f, t, -1.453152027f);
;   y = fmaf(y, t, 1.421413741f);
;   y = fmaf(y, t, -0.284496736f);
;   y = fmaf(y, t, 0.254829592f);
;   y = 1.f - y * t * __expf(-ax * ax);
;   return copysignf(y, x);
; }
; __device__ __forceinline__ void ph_proj(const Params& p, int l, char* shm) {
;     ...
;     gemm_tile8(p.H + (size_t)brow * DM, DM, W + (size_t)pn * 256 * DM, DM, DM, shm, [&](int r, int c, f32x4 v) {
;       if (pn == 34) {
;         *(f32x4*)(p.KW + (size_t)(brow + r) * 256 + c) = v;
;       } else {
;         float y[4];
; #pragma unroll
;         for (int j = 0; j < 4; ++j) {
;           float xv = v[j];
;           if (act == 1) xv = xv * __builtin_amdgcn_rcpf(1.f + __expf(-xv));
;           else if (act == 2) xv = 0.5f * xv * (1.f + erf_fast(xv * 0.70710678118654752f));
;           y[j] = xv;
;         }
;         *(uint2*)(p.P + (size_t)(brow + r) * NP + pn * 256 + c) = uint2{pack2(y[0], y[1]), pack2(y[2], y[3])};
;       }
;     });
	v_add_f32_e32 v178, 1.0, v178
	v_add_f32_e32 v179, 1.0, v179
	v_mul_f32_e32 v188, v188, v176
	v_mul_f32_e32 v189, v189, v177
	v_mul_f32_e32 v190, v190, v178
	v_mul_f32_e32 v191, v191, v179
	v_cvt_pk_bf16_f32 v150, v188, v189
	v_cvt_pk_bf16_f32 v151, v190, v191
	s_nop 1
	v_permlane16_swap_b32_e32 v144, v146
	v_permlane16_swap_b32_e32 v145, v147
	global_store_dwordx4 v[162:163], v[144:147], off nt
	v_mul_f32_e32 v176, 0x3f3504f3, v102
	v_mul_f32_e32 v177, 0x3f3504f3, v103
	v_mul_f32_e32 v178, 0x3f3504f3, v104
	v_mul_f32_e32 v179, 0x3f3504f3, v105
	v_fma_f32 v180, |v176|, s9, 1.0
	v_fma_f32 v181, |v177|, s9, 1.0
	v_fma_f32 v182, |v178|, s9, 1.0
	v_fma_f32 v183, |v179|, s9, 1.0
	v_rcp_f32_e32 v180, v180
	v_rcp_f32_e32 v181, v181
	v_rcp_f32_e32 v182, v182
	v_rcp_f32_e32 v183, v183
	v_mul_f32_e32 v188, 0.5, v102
	v_mul_f32_e32 v189, 0.5, v103
	v_mul_f32_e32 v190, 0.5, v104
	v_mul_f32_e32 v191, 0.5, v105
	v_fmamk_f32 v184, v180, 0x3f87dc22, v206
	v_fmamk_f32 v185, v181, 0x3f87dc22, v206
	v_fmamk_f32 v186, v182, 0x3f87dc22, v206
	v_fmamk_f32 v187, v183, 0x3f87dc22, v206
	v_fmaak_f32 v184, v184, v180, 0x3fb5f0e3
	v_fmaak_f32 v185, v185, v181, 0x3fb5f0e3
	v_fmaak_f32 v186, v186, v182, 0x3fb5f0e3
	v_fmaak_f32 v187, v187, v183, 0x3fb5f0e3
	v_fmaak_f32 v184, v184, v180, 0xbe91a98e
	v_fmaak_f32 v185, v185, v181, 0xbe91a98e
	v_fmaak_f32 v186, v186, v182, 0xbe91a98e
	v_fmaak_f32 v187, v187, v183, 0xbe91a98e
	v_fmaak_f32 v184, v184, v180, 0x3e827906
	v_fmaak_f32 v185, v185, v181, 0x3e827906
	v_fmaak_f32 v186, v186, v182, 0x3e827906
	v_fmaak_f32 v187, v187, v183, 0x3e827906
	v_mul_f32_e32 v180, v180, v184
	v_mul_f32_e32 v181, v181, v185
	v_mul_f32_e32 v182, v182, v186
	v_mul_f32_e32 v183, v183, v187
	v_mul_f32_e64 v184, |v176|, |v176|
	v_mul_f32_e64 v185, |v177|, |v177|
	v_mul_f32_e64 v186, |v178|, |v178|
	v_mul_f32_e64 v187, |v179|, |v179|
	v_mul_f32_e32 v184, 0xbfb8aa3b, v184
	v_mul_f32_e32 v185, 0xbfb8aa3b, v185
	v_mul_f32_e32 v186, 0xbfb8aa3b, v186
	v_mul_f32_e32 v187, 0xbfb8aa3b, v187
	v_exp_f32_e32 v184, v184
	v_exp_f32_e32 v185, v185
	v_exp_f32_e32 v186, v186
	v_exp_f32_e32 v187, v187
	v_fma_f32 v180, -v184, v180, 1.0
	v_fma_f32 v181, -v185, v181, 1.0
	v_fma_f32 v182, -v186, v182, 1.0
	v_fma_f32 v183, -v187, v183, 1.0
	v_bfi_b32 v176, s10, v180, v176
	v_bfi_b32 v177, s10, v181, v177
	v_bfi_b32 v178, s10, v182, v178
	v_bfi_b32 v179, s10, v183, v179
	v_add_f32_e32 v176, 1.0, v176
	v_add_f32_e32 v177, 1.0, v177
	v_add_f32_e32 v178, 1.0, v178
	v_add_f32_e32 v179, 1.0, v179
	v_mul_f32_e32 v188, v188, v176
	v_mul_f32_e32 v189, v189, v177
	v_mul_f32_e32 v190, v190, v178
	v_mul_f32_e32 v191, v191, v179
	v_cvt_pk_bf16_f32 v140, v188, v189
	v_cvt_pk_bf16_f32 v141, v190, v191
	v_mul_f32_e32 v176, 0x3f3504f3, v98
	v_mul_f32_e32 v177, 0x3f3504f3, v99
	v_mul_f32_e32 v178, 0x3f3504f3, v100
	v_mul_f32_e32 v179, 0x3f3504f3, v101
	v_fma_f32 v180, |v176|, s9, 1.0
	v_fma_f32 v181, |v177|, s9, 1.0
	v_fma_f32 v182, |v178|, s9, 1.0
	v_fma_f32 v183, |v179|, s9, 1.0
	v_rcp_f32_e32 v180, v180
	v_rcp_f32_e32 v181, v181
	v_rcp_f32_e32 v182, v182
	v_rcp_f32_e32 v183, v183
	v_mul_f32_e32 v188, 0.5, v98
	v_mul_f32_e32 v189, 0.5, v99
	v_mul_f32_e32 v190, 0.5, v100
	v_mul_f32_e32 v191, 0.5, v101
	v_fmamk_f32 v184, v180, 0x3f87dc22, v206
	v_fmamk_f32 v185, v181, 0x3f87dc22, v206
	v_fmamk_f32 v186, v182, 0x3f87dc22, v206
	v_fmamk_f32 v187, v183, 0x3f87dc22, v206
	v_fmaak_f32 v184, v184, v180, 0x3fb5f0e3
	v_fmaak_f32 v185, v185, v181, 0x3fb5f0e3
	v_fmaak_f32 v186, v186, v182, 0x3fb5f0e3
	v_fmaak_f32 v187, v187, v183, 0x3fb5f0e3
	v_fmaak_f32 v184, v184, v180, 0xbe91a98e
	v_fmaak_f32 v185, v185, v181, 0xbe91a98e
	v_fmaak_f32 v186, v186, v182, 0xbe91a98e
	v_fmaak_f32 v187, v187, v183, 0xbe91a98e
	v_fmaak_f32 v184, v184, v180, 0x3e827906
	v_fmaak_f32 v185, v185, v181, 0x3e827906
	v_fmaak_f32 v186, v186, v182, 0x3e827906
	v_fmaak_f32 v187, v187, v183, 0x3e827906
	v_mul_f32_e32 v180, v180, v184
	v_mul_f32_e32 v181, v181, v185
	v_mul_f32_e32 v182, v182, v186
	v_mul_f32_e32 v183, v183, v187
	v_mul_f32_e64 v184, |v176|, |v176|
	v_mul_f32_e64 v185, |v177|, |v177|
	v_mul_f32_e64 v186, |v178|, |v178|
	v_mul_f32_e64 v187, |v179|, |v179|
	v_mul_f32_e32 v184, 0xbfb8aa3b, v184
	v_mul_f32_e32 v185, 0xbfb8aa3b, v185
	v_mul_f32_e32 v186, 0xbfb8aa3b, v186
	v_mul_f32_e32 v187, 0xbfb8aa3b, v187
	v_exp_f32_e32 v184, v184
	v_exp_f32_e32 v185, v185
	v_exp_f32_e32 v186, v186
	v_exp_f32_e32 v187, v187
	v_fma_f32 v180, -v184, v180, 1.0
	v_fma_f32 v181, -v185, v181, 1.0
	v_fma_f32 v182, -v186, v182, 1.0
	v_fma_f32 v183, -v187, v183, 1.0
	v_bfi_b32 v176, s10, v180, v176
	v_bfi_b32 v177, s10, v181, v177
	v_bfi_b32 v178, s10, v182, v178
	v_bfi_b32 v179, s10, v183, v179
	v_add_f32_e32 v176, 1.0, v176
	v_add_f32_e32 v177, 1.0, v177
	v_add_f32_e32 v178, 1.0, v178
	v_add_f32_e32 v179, 1.0, v179
	v_mul_f32_e32 v188, v188, v176
	v_mul_f32_e32 v189, v189, v177
	v_mul_f32_e32 v190, v190, v178
	v_mul_f32_e32 v191, v191, v179
	v_cvt_pk_bf16_f32 v142, v188, v189
	v_cvt_pk_bf16_f32 v143, v190, v191
	s_nop 1
	v_permlane16_swap_b32_e32 v148, v150
	v_permlane16_swap_b32_e32 v149, v151
	global_store_dwordx4 v[164:165], v[148:151], off nt
	v_mul_f32_e32 v176, 0x3f3504f3, v94
	v_mul_f32_e32 v177, 0x3f3504f3, v95
	v_mul_f32_e32 v178, 0x3f3504f3, v96
	v_mul_f32_e32 v179, 0x3f3504f3, v97
	v_fma_f32 v180, |v176|, s9, 1.0
	v_fma_f32 v181, |v177|, s9, 1.0
	v_fma_f32 v182, |v178|, s9, 1.0
	v_fma_f32 v183, |v179|, s9, 1.0
	v_rcp_f32_e32 v180, v180
	v_rcp_f32_e32 v181, v181
	v_rcp_f32_e32 v182, v182
	v_rcp_f32_e32 v183, v183
	v_mul_f32_e32 v188, 0.5, v94
	v_mul_f32_e32 v189, 0.5, v95
	v_mul_f32_e32 v190, 0.5, v96
	v_mul_f32_e32 v191, 0.5, v97
; __device__ __forceinline__ unsigned pack2(float a, float b) { const f32x2_t v = {a, b}; const bf16x2_t r = __builtin_convertvector(v, bf16x2_t); return __builtin_bit_cast(unsigned, r); }
; __device__ __forceinline__ float erf_fast(float x) {
;   const float ax = fabsf(x);
;   const float t = __builtin_amdgcn_rcpf(fmaf(0.3275911f, ax, 1.f));
;   float y = fmaf(1.061405429f, t, -1.453152027f);
;   y = fmaf(y, t, 1.421413741f);
;   y = fmaf(y, t, -0.284496736f);
;   y = fmaf(y, t, 0.254829592f);
;   y = 1.f - y * t * __expf(-ax * ax);
;   return copysignf(y, x);
; }
; __device__ __forceinline__ void ph_proj(const Params& p, int l, char* shm) {
;     ...
;     gemm_tile8(p.H + (size_t)brow * DM, DM, W + (size_t)pn * 256 * DM, DM, DM, shm, [&](int r, int c, f32x4 v) {
;       if (pn == 34) {
;         *(f32x4*)(p.KW + (size_t)(brow + r) * 256 + c) = v;
;       } else {
;         float y[4];
; #pragma unroll
;         for (int j = 0; j < 4; ++j) {
;           float xv = v[j];
;           if (act == 1) xv = xv * __builtin_amdgcn_rcpf(1.f + __expf(-xv));
;           else if (act == 2) xv = 0.5f * xv * (1.f + erf_fast(xv * 0.70710678118654752f));
;           y[j] = xv;
;         }
;         *(uint2*)(p.P + (size_t)(brow + r) * NP + pn * 256 + c) = uint2{pack2(y[0], y[1]), pack2(y[2], y[3])};
;       }
;     });
	v_fmamk_f32 v184, v180, 0x3f87dc22, v206
	v_fmamk_f32 v185, v181, 0x3f87dc22, v206
	v_fmamk_f32 v186, v182, 0x3f87dc22, v206
	v_fmamk_f32 v187, v183, 0x3f87dc22, v206
	v_fmaak_f32 v184, v184, v180, 0x3fb5f0e3
	v_fmaak_f32 v185, v185, v181, 0x3fb5f0e3
	v_fmaak_f32 v186, v186, v182, 0x3fb5f0e3
	v_fmaak_f32 v187, v187, v183, 0x3fb5f0e3
	v_fmaak_f32 v184, v184, v180, 0xbe91a98e
	v_fmaak_f32 v185, v185, v181, 0xbe91a98e
	v_fmaak_f32 v186, v186, v182, 0xbe91a98e
	v_fmaak_f32 v187, v187, v183, 0xbe91a98e
	v_fmaak_f32 v184, v184, v180, 0x3e827906
	v_fmaak_f32 v185, v185, v181, 0x3e827906
	v_fmaak_f32 v186, v186, v182, 0x3e827906
	v_fmaak_f32 v187, v187, v183, 0x3e827906
	v_mul_f32_e32 v180, v180, v184
	v_mul_f32_e32 v181, v181, v185
	v_mul_f32_e32 v182, v182, v186
	v_mul_f32_e32 v183, v183, v187
	v_mul_f32_e64 v184, |v176|, |v176|
	v_mul_f32_e64 v185, |v177|, |v177|
	v_mul_f32_e64 v186, |v178|, |v178|
	v_mul_f32_e64 v187, |v179|, |v179|
	v_mul_f32_e32 v184, 0xbfb8aa3b, v184
	v_mul_f32_e32 v185, 0xbfb8aa3b, v185
	v_mul_f32_e32 v186, 0xbfb8aa3b, v186
	v_mul_f32_e32 v187, 0xbfb8aa3b, v187
	v_exp_f32_e32 v184, v184
	v_exp_f32_e32 v185, v185
	v_exp_f32_e32 v186, v186
	v_exp_f32_e32 v187, v187
	v_fma_f32 v180, -v184, v180, 1.0
	v_fma_f32 v181, -v185, v181, 1.0
	v_fma_f32 v182, -v186, v182, 1.0
	v_fma_f32 v183, -v187, v183, 1.0
	v_bfi_b32 v176, s10, v180, v176
	v_bfi_b32 v177, s10, v181, v177
	v_bfi_b32 v178, s10, v182, v178
	v_bfi_b32 v179, s10, v183, v179
	v_add_f32_e32 v176, 1.0, v176
	v_add_f32_e32 v177, 1.0, v177
	v_add_f32_e32 v178, 1.0, v178
	v_add_f32_e32 v179, 1.0, v179
	v_mul_f32_e32 v188, v188, v176
	v_mul_f32_e32 v189, v189, v177
	v_mul_f32_e32 v190, v190, v178
	v_mul_f32_e32 v191, v191, v179
	v_cvt_pk_bf16_f32 v144, v188, v189
	v_cvt_pk_bf16_f32 v145, v190, v191
	v_mul_f32_e32 v176, 0x3f3504f3, v90
	v_mul_f32_e32 v177, 0x3f3504f3, v91
	v_mul_f32_e32 v178, 0x3f3504f3, v92
	v_mul_f32_e32 v179, 0x3f3504f3, v93
	v_fma_f32 v180, |v176|, s9, 1.0
	v_fma_f32 v181, |v177|, s9, 1.0
	v_fma_f32 v182, |v178|, s9, 1.0
	v_fma_f32 v183, |v179|, s9, 1.0
	v_rcp_f32_e32 v180, v180
	v_rcp_f32_e32 v181, v181
	v_rcp_f32_e32 v182, v182
	v_rcp_f32_e32 v183, v183
	v_mul_f32_e32 v188, 0.5, v90
	v_mul_f32_e32 v189, 0.5, v91
	v_mul_f32_e32 v190, 0.5, v92
	v_mul_f32_e32 v191, 0.5, v93
	v_fmamk_f32 v184, v180, 0x3f87dc22, v206
	v_fmamk_f32 v185, v181, 0x3f87dc22, v206
	v_fmamk_f32 v186, v182, 0x3f87dc22, v206
	v_fmamk_f32 v187, v183, 0x3f87dc22, v206
	v_fmaak_f32 v184, v184, v180, 0x3fb5f0e3
	v_fmaak_f32 v185, v185, v181, 0x3fb5f0e3
	v_fmaak_f32 v186, v186, v182, 0x3fb5f0e3
	v_fmaak_f32 v187, v187, v183, 0x3fb5f0e3
	v_fmaak_f32 v184, v184, v180, 0xbe91a98e
	v_fmaak_f32 v185, v185, v181, 0xbe91a98e
	v_fmaak_f32 v186, v186, v182, 0xbe91a98e
	v_fmaak_f32 v187, v187, v183, 0xbe91a98e
	v_fmaak_f32 v184, v184, v180, 0x3e827906
	v_fmaak_f32 v185, v185, v181, 0x3e827906
	v_fmaak_f32 v186, v186, v182, 0x3e827906
	v_fmaak_f32 v187, v187, v183, 0x3e827906
	v_mul_f32_e32 v180, v180, v184
	v_mul_f32_e32 v181, v181, v185
	v_mul_f32_e32 v182, v182, v186
	v_mul_f32_e32 v183, v183, v187
	v_mul_f32_e64 v184, |v176|, |v176|
	v_mul_f32_e64 v185, |v177|, |v177|
	v_mul_f32_e64 v186, |v178|, |v178|
	v_mul_f32_e64 v187, |v179|, |v179|
	v_mul_f32_e32 v184, 0xbfb8aa3b, v184
	v_mul_f32_e32 v185, 0xbfb8aa3b, v185
	v_mul_f32_e32 v186, 0xbfb8aa3b, v186
	v_mul_f32_e32 v187, 0xbfb8aa3b, v187
	v_exp_f32_e32 v184, v184
	v_exp_f32_e32 v185, v185
	v_exp_f32_e32 v186, v186
	v_exp_f32_e32 v187, v187
	v_fma_f32 v180, -v184, v180, 1.0
	v_fma_f32 v181, -v185, v181, 1.0
	v_fma_f32 v182, -v186, v182, 1.0
	v_fma_f32 v183, -v187, v183, 1.0
	v_bfi_b32 v176, s10, v180, v176
	v_bfi_b32 v177, s10, v181, v177
	v_bfi_b32 v178, s10, v182, v178
	v_bfi_b32 v179, s10, v183, v179
	v_add_f32_e32 v176, 1.0, v176
	v_add_f32_e32 v177, 1.0, v177
	v_add_f32_e32 v178, 1.0, v178
	v_add_f32_e32 v179, 1.0, v179
	v_mul_f32_e32 v188, v188, v176
	v_mul_f32_e32 v189, v189, v177
	v_mul_f32_e32 v190, v190, v178
	v_mul_f32_e32 v191, v191, v179
	v_cvt_pk_bf16_f32 v146, v188, v189
	v_cvt_pk_bf16_f32 v147, v190, v191
	s_nop 1
	v_permlane16_swap_b32_e32 v140, v142
	v_permlane16_swap_b32_e32 v141, v143
	global_store_dwordx4 v[166:167], v[140:143], off nt
	v_mul_f32_e32 v176, 0x3f3504f3, v86
	v_mul_f32_e32 v177, 0x3f3504f3, v87
	v_mul_f32_e32 v178, 0x3f3504f3, v88
	v_mul_f32_e32 v179, 0x3f3504f3, v89
	v_fma_f32 v180, |v176|, s9, 1.0
	v_fma_f32 v181, |v177|, s9, 1.0
	v_fma_f32 v182, |v178|, s9, 1.0
	v_fma_f32 v183, |v179|, s9, 1.0
	v_rcp_f32_e32 v180, v180
	v_rcp_f32_e32 v181, v181
	v_rcp_f32_e32 v182, v182
	v_rcp_f32_e32 v183, v183
	v_mul_f32_e32 v188, 0.5, v86
	v_mul_f32_e32 v189, 0.5, v87
	v_mul_f32_e32 v190, 0.5, v88
	v_mul_f32_e32 v191, 0.5, v89
	v_fmamk_f32 v184, v180, 0x3f87dc22, v206
	v_fmamk_f32 v185, v181, 0x3f87dc22, v206
	v_fmamk_f32 v186, v182, 0x3f87dc22, v206
	v_fmamk_f32 v187, v183, 0x3f87dc22, v206
	v_fmaak_f32 v184, v184, v180, 0x3fb5f0e3
	v_fmaak_f32 v185, v185, v181, 0x3fb5f0e3
	v_fmaak_f32 v186, v186, v182, 0x3fb5f0e3
	v_fmaak_f32 v187, v187, v183, 0x3fb5f0e3
	v_fmaak_f32 v184, v184, v180, 0xbe91a98e
	v_fmaak_f32 v185, v185, v181, 0xbe91a98e
	v_fmaak_f32 v186, v186, v182, 0xbe91a98e
	v_fmaak_f32 v187, v187, v183, 0xbe91a98e
	v_fmaak_f32 v184, v184, v180, 0x3e827906
	v_fmaak_f32 v185, v185, v181, 0x3e827906
	v_fmaak_f32 v186, v186, v182, 0x3e827906
	v_fmaak_f32 v187, v187, v183, 0x3e827906
	v_mul_f32_e32 v180, v180, v184
	v_mul_f32_e32 v181, v181, v185
	v_mul_f32_e32 v182, v182, v186
	v_mul_f32_e32 v183, v183, v187
	v_mul_f32_e64 v184, |v176|, |v176|
	v_mul_f32_e64 v185, |v177|, |v177|
	v_mul_f32_e64 v186, |v178|, |v178|
; __device__ __forceinline__ unsigned pack2(float a, float b) { const f32x2_t v = {a, b}; const bf16x2_t r = __builtin_convertvector(v, bf16x2_t); return __builtin_bit_cast(unsigned, r); }
; __device__ __forceinline__ float erf_fast(float x) {
;   const float ax = fabsf(x);
;   const float t = __builtin_amdgcn_rcpf(fmaf(0.3275911f, ax, 1.f));
;   float y = fmaf(1.061405429f, t, -1.453152027f);
;   y = fmaf(y, t, 1.421413741f);
;   y = fmaf(y, t, -0.284496736f);
;   y = fmaf(y, t, 0.254829592f);
;   y = 1.f - y * t * __expf(-ax * ax);
;   return copysignf(y, x);
; }
; __device__ __forceinline__ void ph_proj(const Params& p, int l, char* shm) {
;     ...
;     gemm_tile8(p.H + (size_t)brow * DM, DM, W + (size_t)pn * 256 * DM, DM, DM, shm, [&](int r, int c, f32x4 v) {
;       if (pn == 34) {
;         *(f32x4*)(p.KW + (size_t)(brow + r) * 256 + c) = v;
;       } else {
;         float y[4];
; #pragma unroll
;         for (int j = 0; j < 4; ++j) {
;           float xv = v[j];
;           if (act == 1) xv = xv * __builtin_amdgcn_rcpf(1.f + __expf(-xv));
;           else if (act == 2) xv = 0.5f * xv * (1.f + erf_fast(xv * 0.70710678118654752f));
;           y[j] = xv;
;         }
;         *(uint2*)(p.P + (size_t)(brow + r) * NP + pn * 256 + c) = uint2{pack2(y[0], y[1]), pack2(y[2], y[3])};
;       }
;     });
	v_mul_f32_e64 v187, |v179|, |v179|
	v_mul_f32_e32 v184, 0xbfb8aa3b, v184
	v_mul_f32_e32 v185, 0xbfb8aa3b, v185
	v_mul_f32_e32 v186, 0xbfb8aa3b, v186
	v_mul_f32_e32 v187, 0xbfb8aa3b, v187
	v_exp_f32_e32 v184, v184
	v_exp_f32_e32 v185, v185
	v_exp_f32_e32 v186, v186
	v_exp_f32_e32 v187, v187
	v_fma_f32 v180, -v184, v180, 1.0
	v_fma_f32 v181, -v185, v181, 1.0
	v_fma_f32 v182, -v186, v182, 1.0
	v_fma_f32 v183, -v187, v183, 1.0
	v_bfi_b32 v176, s10, v180, v176
	v_bfi_b32 v177, s10, v181, v177
	v_bfi_b32 v178, s10, v182, v178
	v_bfi_b32 v179, s10, v183, v179
	v_add_f32_e32 v176, 1.0, v176
	v_add_f32_e32 v177, 1.0, v177
	v_add_f32_e32 v178, 1.0, v178
	v_add_f32_e32 v179, 1.0, v179
	v_mul_f32_e32 v188, v188, v176
	v_mul_f32_e32 v189, v189, v177
	v_mul_f32_e32 v190, v190, v178
	v_mul_f32_e32 v191, v191, v179
	v_cvt_pk_bf16_f32 v148, v188, v189
	v_cvt_pk_bf16_f32 v149, v190, v191
	v_mul_f32_e32 v176, 0x3f3504f3, v82
	v_mul_f32_e32 v177, 0x3f3504f3, v83
	v_mul_f32_e32 v178, 0x3f3504f3, v84
	v_mul_f32_e32 v179, 0x3f3504f3, v85
	v_fma_f32 v180, |v176|, s9, 1.0
	v_fma_f32 v181, |v177|, s9, 1.0
	v_fma_f32 v182, |v178|, s9, 1.0
	v_fma_f32 v183, |v179|, s9, 1.0
	v_rcp_f32_e32 v180, v180
	v_rcp_f32_e32 v181, v181
	v_rcp_f32_e32 v182, v182
	v_rcp_f32_e32 v183, v183
	v_mul_f32_e32 v188, 0.5, v82
	v_mul_f32_e32 v189, 0.5, v83
	v_mul_f32_e32 v190, 0.5, v84
	v_mul_f32_e32 v191, 0.5, v85
	v_fmamk_f32 v184, v180, 0x3f87dc22, v206
	v_fmamk_f32 v185, v181, 0x3f87dc22, v206
	v_fmamk_f32 v186, v182, 0x3f87dc22, v206
	v_fmamk_f32 v187, v183, 0x3f87dc22, v206
	v_fmaak_f32 v184, v184, v180, 0x3fb5f0e3
	v_fmaak_f32 v185, v185, v181, 0x3fb5f0e3
	v_fmaak_f32 v186, v186, v182, 0x3fb5f0e3
	v_fmaak_f32 v187, v187, v183, 0x3fb5f0e3
	v_fmaak_f32 v184, v184, v180, 0xbe91a98e
	v_fmaak_f32 v185, v185, v181, 0xbe91a98e
	v_fmaak_f32 v186, v186, v182, 0xbe91a98e
	v_fmaak_f32 v187, v187, v183, 0xbe91a98e
	v_fmaak_f32 v184, v184, v180, 0x3e827906
	v_fmaak_f32 v185, v185, v181, 0x3e827906
	v_fmaak_f32 v186, v186, v182, 0x3e827906
	v_fmaak_f32 v187, v187, v183, 0x3e827906
	v_mul_f32_e32 v180, v180, v184
	v_mul_f32_e32 v181, v181, v185
	v_mul_f32_e32 v182, v182, v186
	v_mul_f32_e32 v183, v183, v187
	v_mul_f32_e64 v184, |v176|, |v176|
	v_mul_f32_e64 v185, |v177|, |v177|
	v_mul_f32_e64 v186, |v178|, |v178|
	v_mul_f32_e64 v187, |v179|, |v179|
	v_mul_f32_e32 v184, 0xbfb8aa3b, v184
	v_mul_f32_e32 v185, 0xbfb8aa3b, v185
	v_mul_f32_e32 v186, 0xbfb8aa3b, v186
	v_mul_f32_e32 v187, 0xbfb8aa3b, v187
	v_exp_f32_e32 v184, v184
	v_exp_f32_e32 v185, v185
	v_exp_f32_e32 v186, v186
	v_exp_f32_e32 v187, v187
	v_fma_f32 v180, -v184, v180, 1.0
	v_fma_f32 v181, -v185, v181, 1.0
	v_fma_f32 v182, -v186, v182, 1.0
	v_fma_f32 v183, -v187, v183, 1.0
	v_bfi_b32 v176, s10, v180, v176
	v_bfi_b32 v177, s10, v181, v177
	v_bfi_b32 v178, s10, v182, v178
	v_bfi_b32 v179, s10, v183, v179
	v_add_f32_e32 v176, 1.0, v176
	v_add_f32_e32 v177, 1.0, v177
	v_add_f32_e32 v178, 1.0, v178
	v_add_f32_e32 v179, 1.0, v179
	v_mul_f32_e32 v188, v188, v176
	v_mul_f32_e32 v189, v189, v177
	v_mul_f32_e32 v190, v190, v178
	v_mul_f32_e32 v191, v191, v179
	v_cvt_pk_bf16_f32 v150, v188, v189
	v_cvt_pk_bf16_f32 v151, v190, v191
	s_nop 1
	v_permlane16_swap_b32_e32 v144, v146
	v_permlane16_swap_b32_e32 v145, v147
	global_store_dwordx4 v[160:161], v[144:147], off offset:256 nt
	v_mul_f32_e32 v176, 0x3f3504f3, v78
	v_mul_f32_e32 v177, 0x3f3504f3, v79
	v_mul_f32_e32 v178, 0x3f3504f3, v80
	v_mul_f32_e32 v179, 0x3f3504f3, v81
	v_fma_f32 v180, |v176|, s9, 1.0
	v_fma_f32 v181, |v177|, s9, 1.0
	v_fma_f32 v182, |v178|, s9, 1.0
	v_fma_f32 v183, |v179|, s9, 1.0
	v_rcp_f32_e32 v180, v180
	v_rcp_f32_e32 v181, v181
	v_rcp_f32_e32 v182, v182
	v_rcp_f32_e32 v183, v183
	v_mul_f32_e32 v188, 0.5, v78
	v_mul_f32_e32 v189, 0.5, v79
	v_mul_f32_e32 v190, 0.5, v80
	v_mul_f32_e32 v191, 0.5, v81
	v_fmamk_f32 v184, v180, 0x3f87dc22, v206
	v_fmamk_f32 v185, v181, 0x3f87dc22, v206
	v_fmamk_f32 v186, v182, 0x3f87dc22, v206
	v_fmamk_f32 v187, v183, 0x3f87dc22, v206
	v_fmaak_f32 v184, v184, v180, 0x3fb5f0e3
	v_fmaak_f32 v185, v185, v181, 0x3fb5f0e3
	v_fmaak_f32 v186, v186, v182, 0x3fb5f0e3
	v_fmaak_f32 v187, v187, v183, 0x3fb5f0e3
	v_fmaak_f32 v184, v184, v180, 0xbe91a98e
	v_fmaak_f32 v185, v185, v181, 0xbe91a98e
	v_fmaak_f32 v186, v186, v182, 0xbe91a98e
	v_fmaak_f32 v187, v187, v183, 0xbe91a98e
	v_fmaak_f32 v184, v184, v180, 0x3e827906
	v_fmaak_f32 v185, v185, v181, 0x3e827906
	v_fmaak_f32 v186, v186, v182, 0x3e827906
	v_fmaak_f32 v187, v187, v183, 0x3e827906
	v_mul_f32_e32 v180, v180, v184
	v_mul_f32_e32 v181, v181, v185
	v_mul_f32_e32 v182, v182, v186
	v_mul_f32_e32 v183, v183, v187
	v_mul_f32_e64 v184, |v176|, |v176|
	v_mul_f32_e64 v185, |v177|, |v177|
	v_mul_f32_e64 v186, |v178|, |v178|
	v_mul_f32_e64 v187, |v179|, |v179|
	v_mul_f32_e32 v184, 0xbfb8aa3b, v184
	v_mul_f32_e32 v185, 0xbfb8aa3b, v185
	v_mul_f32_e32 v186, 0xbfb8aa3b, v186
	v_mul_f32_e32 v187, 0xbfb8aa3b, v187
	v_exp_f32_e32 v184, v184
	v_exp_f32_e32 v185, v185
	v_exp_f32_e32 v186, v186
	v_exp_f32_e32 v187, v187
	v_fma_f32 v180, -v184, v180, 1.0
	v_fma_f32 v181, -v185, v181, 1.0
	v_fma_f32 v182, -v186, v182, 1.0
	v_fma_f32 v183, -v187, v183, 1.0
	v_bfi_b32 v176, s10, v180, v176
	v_bfi_b32 v177, s10, v181, v177
	v_bfi_b32 v178, s10, v182, v178
	v_bfi_b32 v179, s10, v183, v179
	v_add_f32_e32 v176, 1.0, v176
	v_add_f32_e32 v177, 1.0, v177
	v_add_f32_e32 v178, 1.0, v178
	v_add_f32_e32 v179, 1.0, v179
	v_mul_f32_e32 v188, v188, v176
	v_mul_f32_e32 v189, v189, v177
	v_mul_f32_e32 v190, v190, v178
	v_mul_f32_e32 v191, v191, v179
	v_cvt_pk_bf16_f32 v140, v188, v189
	v_cvt_pk_bf16_f32 v141, v190, v191
; __device__ __forceinline__ unsigned pack2(float a, float b) { const f32x2_t v = {a, b}; const bf16x2_t r = __builtin_convertvector(v, bf16x2_t); return __builtin_bit_cast(unsigned, r); }
; __device__ __forceinline__ float erf_fast(float x) {
;   const float ax = fabsf(x);
;   const float t = __builtin_amdgcn_rcpf(fmaf(0.3275911f, ax, 1.f));
;   float y = fmaf(1.061405429f, t, -1.453152027f);
;   y = fmaf(y, t, 1.421413741f);
;   y = fmaf(y, t, -0.284496736f);
;   y = fmaf(y, t, 0.254829592f);
;   y = 1.f - y * t * __expf(-ax * ax);
;   return copysignf(y, x);
; }
; __device__ __forceinline__ void ph_proj(const Params& p, int l, char* shm) {
;     ...
;     gemm_tile8(p.H + (size_t)brow * DM, DM, W + (size_t)pn * 256 * DM, DM, DM, shm, [&](int r, int c, f32x4 v) {
;       if (pn == 34) {
;         *(f32x4*)(p.KW + (size_t)(brow + r) * 256 + c) = v;
;       } else {
;         float y[4];
; #pragma unroll
;         for (int j = 0; j < 4; ++j) {
;           float xv = v[j];
;           if (act == 1) xv = xv * __builtin_amdgcn_rcpf(1.f + __expf(-xv));
;           else if (act == 2) xv = 0.5f * xv * (1.f + erf_fast(xv * 0.70710678118654752f));
;           y[j] = xv;
;         }
;         *(uint2*)(p.P + (size_t)(brow + r) * NP + pn * 256 + c) = uint2{pack2(y[0], y[1]), pack2(y[2], y[3])};
;       }
;     });
	v_mul_f32_e32 v176, 0x3f3504f3, v74
	v_mul_f32_e32 v177, 0x3f3504f3, v75
	v_mul_f32_e32 v178, 0x3f3504f3, v76
	v_mul_f32_e32 v179, 0x3f3504f3, v77
	v_fma_f32 v180, |v176|, s9, 1.0
	v_fma_f32 v181, |v177|, s9, 1.0
	v_fma_f32 v182, |v178|, s9, 1.0
	v_fma_f32 v183, |v179|, s9, 1.0
	v_rcp_f32_e32 v180, v180
	v_rcp_f32_e32 v181, v181
	v_rcp_f32_e32 v182, v182
	v_rcp_f32_e32 v183, v183
	v_mul_f32_e32 v188, 0.5, v74
	v_mul_f32_e32 v189, 0.5, v75
	v_mul_f32_e32 v190, 0.5, v76
	v_mul_f32_e32 v191, 0.5, v77
	v_fmamk_f32 v184, v180, 0x3f87dc22, v206
	v_fmamk_f32 v185, v181, 0x3f87dc22, v206
	v_fmamk_f32 v186, v182, 0x3f87dc22, v206
	v_fmamk_f32 v187, v183, 0x3f87dc22, v206
	v_fmaak_f32 v184, v184, v180, 0x3fb5f0e3
	v_fmaak_f32 v185, v185, v181, 0x3fb5f0e3
	v_fmaak_f32 v186, v186, v182, 0x3fb5f0e3
	v_fmaak_f32 v187, v187, v183, 0x3fb5f0e3
	v_fmaak_f32 v184, v184, v180, 0xbe91a98e
	v_fmaak_f32 v185, v185, v181, 0xbe91a98e
	v_fmaak_f32 v186, v186, v182, 0xbe91a98e
	v_fmaak_f32 v187, v187, v183, 0xbe91a98e
	v_fmaak_f32 v184, v184, v180, 0x3e827906
	v_fmaak_f32 v185, v185, v181, 0x3e827906
	v_fmaak_f32 v186, v186, v182, 0x3e827906
	v_fmaak_f32 v187, v187, v183, 0x3e827906
	v_mul_f32_e32 v180, v180, v184
	v_mul_f32_e32 v181, v181, v185
	v_mul_f32_e32 v182, v182, v186
	v_mul_f32_e32 v183, v183, v187
	v_mul_f32_e64 v184, |v176|, |v176|
	v_mul_f32_e64 v185, |v177|, |v177|
	v_mul_f32_e64 v186, |v178|, |v178|
	v_mul_f32_e64 v187, |v179|, |v179|
	v_mul_f32_e32 v184, 0xbfb8aa3b, v184
	v_mul_f32_e32 v185, 0xbfb8aa3b, v185
	v_mul_f32_e32 v186, 0xbfb8aa3b, v186
	v_mul_f32_e32 v187, 0xbfb8aa3b, v187
	v_exp_f32_e32 v184, v184
	v_exp_f32_e32 v185, v185
	v_exp_f32_e32 v186, v186
	v_exp_f32_e32 v187, v187
	v_fma_f32 v180, -v184, v180, 1.0
	v_fma_f32 v181, -v185, v181, 1.0
	v_fma_f32 v182, -v186, v182, 1.0
	v_fma_f32 v183, -v187, v183, 1.0
	v_bfi_b32 v176, s10, v180, v176
	v_bfi_b32 v177, s10, v181, v177
	v_bfi_b32 v178, s10, v182, v178
	v_bfi_b32 v179, s10, v183, v179
	v_add_f32_e32 v176, 1.0, v176
	v_add_f32_e32 v177, 1.0, v177
	v_add_f32_e32 v178, 1.0, v178
	v_add_f32_e32 v179, 1.0, v179
	v_mul_f32_e32 v188, v188, v176
	v_mul_f32_e32 v189, v189, v177
	v_mul_f32_e32 v190, v190, v178
	v_mul_f32_e32 v191, v191, v179
	v_cvt_pk_bf16_f32 v142, v188, v189
	v_cvt_pk_bf16_f32 v143, v190, v191
	s_nop 1
	v_permlane16_swap_b32_e32 v148, v150
	v_permlane16_swap_b32_e32 v149, v151
	global_store_dwordx4 v[162:163], v[148:151], off offset:256 nt
	v_mul_f32_e32 v176, 0x3f3504f3, v70
	v_mul_f32_e32 v177, 0x3f3504f3, v71
	v_mul_f32_e32 v178, 0x3f3504f3, v72
	v_mul_f32_e32 v179, 0x3f3504f3, v73
	v_fma_f32 v180, |v176|, s9, 1.0
	v_fma_f32 v181, |v177|, s9, 1.0
	v_fma_f32 v182, |v178|, s9, 1.0
	v_fma_f32 v183, |v179|, s9, 1.0
	v_rcp_f32_e32 v180, v180
	v_rcp_f32_e32 v181, v181
	v_rcp_f32_e32 v182, v182
	v_rcp_f32_e32 v183, v183
	v_mul_f32_e32 v188, 0.5, v70
	v_mul_f32_e32 v189, 0.5, v71
	v_mul_f32_e32 v190, 0.5, v72
	v_mul_f32_e32 v191, 0.5, v73
	v_fmamk_f32 v184, v180, 0x3f87dc22, v206
	v_fmamk_f32 v185, v181, 0x3f87dc22, v206
	v_fmamk_f32 v186, v182, 0x3f87dc22, v206
	v_fmamk_f32 v187, v183, 0x3f87dc22, v206
	v_fmaak_f32 v184, v184, v180, 0x3fb5f0e3
	v_fmaak_f32 v185, v185, v181, 0x3fb5f0e3
	v_fmaak_f32 v186, v186, v182, 0x3fb5f0e3
	v_fmaak_f32 v187, v187, v183, 0x3fb5f0e3
	v_fmaak_f32 v184, v184, v180, 0xbe91a98e
	v_fmaak_f32 v185, v185, v181, 0xbe91a98e
	v_fmaak_f32 v186, v186, v182, 0xbe91a98e
	v_fmaak_f32 v187, v187, v183, 0xbe91a98e
	v_fmaak_f32 v184, v184, v180, 0x3e827906
	v_fmaak_f32 v185, v185, v181, 0x3e827906
	v_fmaak_f32 v186, v186, v182, 0x3e827906
	v_fmaak_f32 v187, v187, v183, 0x3e827906
	v_mul_f32_e32 v180, v180, v184
	v_mul_f32_e32 v181, v181, v185
	v_mul_f32_e32 v182, v182, v186
	v_mul_f32_e32 v183, v183, v187
	v_mul_f32_e64 v184, |v176|, |v176|
	v_mul_f32_e64 v185, |v177|, |v177|
	v_mul_f32_e64 v186, |v178|, |v178|
	v_mul_f32_e64 v187, |v179|, |v179|
	v_mul_f32_e32 v184, 0xbfb8aa3b, v184
	v_mul_f32_e32 v185, 0xbfb8aa3b, v185
	v_mul_f32_e32 v186, 0xbfb8aa3b, v186
	v_mul_f32_e32 v187, 0xbfb8aa3b, v187
	v_exp_f32_e32 v184, v184
	v_exp_f32_e32 v185, v185
	v_exp_f32_e32 v186, v186
	v_exp_f32_e32 v187, v187
	v_fma_f32 v180, -v184, v180, 1.0
	v_fma_f32 v181, -v185, v181, 1.0
	v_fma_f32 v182, -v186, v182, 1.0
	v_fma_f32 v183, -v187, v183, 1.0
	v_bfi_b32 v176, s10, v180, v176
	v_bfi_b32 v177, s10, v181, v177
	v_bfi_b32 v178, s10, v182, v178
	v_bfi_b32 v179, s10, v183, v179
	v_add_f32_e32 v176, 1.0, v176
	v_add_f32_e32 v177, 1.0, v177
	v_add_f32_e32 v178, 1.0, v178
	v_add_f32_e32 v179, 1.0, v179
	v_mul_f32_e32 v188, v188, v176
	v_mul_f32_e32 v189, v189, v177
	v_mul_f32_e32 v190, v190, v178
	v_mul_f32_e32 v191, v191, v179
	v_cvt_pk_bf16_f32 v144, v188, v189
	v_cvt_pk_bf16_f32 v145, v190, v191
	v_mul_f32_e32 v176, 0x3f3504f3, v66
	v_mul_f32_e32 v177, 0x3f3504f3, v67
	v_mul_f32_e32 v178, 0x3f3504f3, v68
	v_mul_f32_e32 v179, 0x3f3504f3, v69
	v_fma_f32 v180, |v176|, s9, 1.0
	v_fma_f32 v181, |v177|, s9, 1.0
	v_fma_f32 v182, |v178|, s9, 1.0
	v_fma_f32 v183, |v179|, s9, 1.0
	v_rcp_f32_e32 v180, v180
	v_rcp_f32_e32 v181, v181
	v_rcp_f32_e32 v182, v182
	v_rcp_f32_e32 v183, v183
	v_mul_f32_e32 v188, 0.5, v66
	v_mul_f32_e32 v189, 0.5, v67
	v_mul_f32_e32 v190, 0.5, v68
	v_mul_f32_e32 v191, 0.5, v69
	v_fmamk_f32 v184, v180, 0x3f87dc22, v206
	v_fmamk_f32 v185, v181, 0x3f87dc22, v206
	v_fmamk_f32 v186, v182, 0x3f87dc22, v206
	v_fmamk_f32 v187, v183, 0x3f87dc22, v206
	v_fmaak_f32 v184, v184, v180, 0x3fb5f0e3
	v_fmaak_f32 v185, v185, v181, 0x3fb5f0e3
	v_fmaak_f32 v186, v186, v182, 0x3fb5f0e3
	v_fmaak_f32 v187, v187, v183, 0x3fb5f0e3
	v_fmaak_f32 v184, v184, v180, 0xbe91a98e
; __device__ __forceinline__ unsigned pack2(float a, float b) { const f32x2_t v = {a, b}; const bf16x2_t r = __builtin_convertvector(v, bf16x2_t); return __builtin_bit_cast(unsigned, r); }
; __device__ __forceinline__ float erf_fast(float x) {
;   const float ax = fabsf(x);
;   const float t = __builtin_amdgcn_rcpf(fmaf(0.3275911f, ax, 1.f));
;   float y = fmaf(1.061405429f, t, -1.453152027f);
;   y = fmaf(y, t, 1.421413741f);
;   y = fmaf(y, t, -0.284496736f);
;   y = fmaf(y, t, 0.254829592f);
;   y = 1.f - y * t * __expf(-ax * ax);
;   return copysignf(y, x);
; }
; __device__ __forceinline__ void ph_proj(const Params& p, int l, char* shm) {
;     ...
;     gemm_tile8(p.H + (size_t)brow * DM, DM, W + (size_t)pn * 256 * DM, DM, DM, shm, [&](int r, int c, f32x4 v) {
;       if (pn == 34) {
;         *(f32x4*)(p.KW + (size_t)(brow + r) * 256 + c) = v;
;       } else {
;         float y[4];
; #pragma unroll
;         for (int j = 0; j < 4; ++j) {
;           float xv = v[j];
;           if (act == 1) xv = xv * __builtin_amdgcn_rcpf(1.f + __expf(-xv));
;           else if (act == 2) xv = 0.5f * xv * (1.f + erf_fast(xv * 0.70710678118654752f));
;           y[j] = xv;
;         }
;         *(uint2*)(p.P + (size_t)(brow + r) * NP + pn * 256 + c) = uint2{pack2(y[0], y[1]), pack2(y[2], y[3])};
;       }
;     });
	v_fmaak_f32 v185, v185, v181, 0xbe91a98e
	v_fmaak_f32 v186, v186, v182, 0xbe91a98e
	v_fmaak_f32 v187, v187, v183, 0xbe91a98e
	v_fmaak_f32 v184, v184, v180, 0x3e827906
	v_fmaak_f32 v185, v185, v181, 0x3e827906
	v_fmaak_f32 v186, v186, v182, 0x3e827906
	v_fmaak_f32 v187, v187, v183, 0x3e827906
	v_mul_f32_e32 v180, v180, v184
	v_mul_f32_e32 v181, v181, v185
	v_mul_f32_e32 v182, v182, v186
	v_mul_f32_e32 v183, v183, v187
	v_mul_f32_e64 v184, |v176|, |v176|
	v_mul_f32_e64 v185, |v177|, |v177|
	v_mul_f32_e64 v186, |v178|, |v178|
	v_mul_f32_e64 v187, |v179|, |v179|
	v_mul_f32_e32 v184, 0xbfb8aa3b, v184
	v_mul_f32_e32 v185, 0xbfb8aa3b, v185
	v_mul_f32_e32 v186, 0xbfb8aa3b, v186
	v_mul_f32_e32 v187, 0xbfb8aa3b, v187
	v_exp_f32_e32 v184, v184
	v_exp_f32_e32 v185, v185
	v_exp_f32_e32 v186, v186
	v_exp_f32_e32 v187, v187
	v_fma_f32 v180, -v184, v180, 1.0
	v_fma_f32 v181, -v185, v181, 1.0
	v_fma_f32 v182, -v186, v182, 1.0
	v_fma_f32 v183, -v187, v183, 1.0
	v_bfi_b32 v176, s10, v180, v176
	v_bfi_b32 v177, s10, v181, v177
	v_bfi_b32 v178, s10, v182, v178
	v_bfi_b32 v179, s10, v183, v179
	v_add_f32_e32 v176, 1.0, v176
	v_add_f32_e32 v177, 1.0, v177
	v_add_f32_e32 v178, 1.0, v178
	v_add_f32_e32 v179, 1.0, v179
	v_mul_f32_e32 v188, v188, v176
	v_mul_f32_e32 v189, v189, v177
	v_mul_f32_e32 v190, v190, v178
	v_mul_f32_e32 v191, v191, v179
	v_cvt_pk_bf16_f32 v146, v188, v189
	v_cvt_pk_bf16_f32 v147, v190, v191
	s_nop 1
	v_permlane16_swap_b32_e32 v140, v142
	v_permlane16_swap_b32_e32 v141, v143
	global_store_dwordx4 v[164:165], v[140:143], off offset:256 nt
	v_mul_f32_e32 v176, 0x3f3504f3, v62
	v_mul_f32_e32 v177, 0x3f3504f3, v63
	v_mul_f32_e32 v178, 0x3f3504f3, v64
	v_mul_f32_e32 v179, 0x3f3504f3, v65
	v_fma_f32 v180, |v176|, s9, 1.0
	v_fma_f32 v181, |v177|, s9, 1.0
	v_fma_f32 v182, |v178|, s9, 1.0
	v_fma_f32 v183, |v179|, s9, 1.0
	v_rcp_f32_e32 v180, v180
	v_rcp_f32_e32 v181, v181
	v_rcp_f32_e32 v182, v182
	v_rcp_f32_e32 v183, v183
	v_mul_f32_e32 v188, 0.5, v62
	v_mul_f32_e32 v189, 0.5, v63
	v_mul_f32_e32 v190, 0.5, v64
	v_mul_f32_e32 v191, 0.5, v65
	v_fmamk_f32 v184, v180, 0x3f87dc22, v206
	v_fmamk_f32 v185, v181, 0x3f87dc22, v206
	v_fmamk_f32 v186, v182, 0x3f87dc22, v206
	v_fmamk_f32 v187, v183, 0x3f87dc22, v206
	v_fmaak_f32 v184, v184, v180, 0x3fb5f0e3
	v_fmaak_f32 v185, v185, v181, 0x3fb5f0e3
	v_fmaak_f32 v186, v186, v182, 0x3fb5f0e3
	v_fmaak_f32 v187, v187, v183, 0x3fb5f0e3
	v_fmaak_f32 v184, v184, v180, 0xbe91a98e
	v_fmaak_f32 v185, v185, v181, 0xbe91a98e
	v_fmaak_f32 v186, v186, v182, 0xbe91a98e
	v_fmaak_f32 v187, v187, v183, 0xbe91a98e
	v_fmaak_f32 v184, v184, v180, 0x3e827906
	v_fmaak_f32 v185, v185, v181, 0x3e827906
	v_fmaak_f32 v186, v186, v182, 0x3e827906
	v_fmaak_f32 v187, v187, v183, 0x3e827906
	v_mul_f32_e32 v180, v180, v184
	v_mul_f32_e32 v181, v181, v185
	v_mul_f32_e32 v182, v182, v186
	v_mul_f32_e32 v183, v183, v187
	v_mul_f32_e64 v184, |v176|, |v176|
	v_mul_f32_e64 v185, |v177|, |v177|
	v_mul_f32_e64 v186, |v178|, |v178|
	v_mul_f32_e64 v187, |v179|, |v179|
	v_mul_f32_e32 v184, 0xbfb8aa3b, v184
	v_mul_f32_e32 v185, 0xbfb8aa3b, v185
	v_mul_f32_e32 v186, 0xbfb8aa3b, v186
	v_mul_f32_e32 v187, 0xbfb8aa3b, v187
	v_exp_f32_e32 v184, v184
	v_exp_f32_e32 v185, v185
	v_exp_f32_e32 v186, v186
	v_exp_f32_e32 v187, v187
	v_fma_f32 v180, -v184, v180, 1.0
	v_fma_f32 v181, -v185, v181, 1.0
	v_fma_f32 v182, -v186, v182, 1.0
	v_fma_f32 v183, -v187, v183, 1.0
	v_bfi_b32 v176, s10, v180, v176
	v_bfi_b32 v177, s10, v181, v177
	v_bfi_b32 v178, s10, v182, v178
	v_bfi_b32 v179, s10, v183, v179
	v_add_f32_e32 v176, 1.0, v176
	v_add_f32_e32 v177, 1.0, v177
	v_add_f32_e32 v178, 1.0, v178
	v_add_f32_e32 v179, 1.0, v179
	v_mul_f32_e32 v188, v188, v176
	v_mul_f32_e32 v189, v189, v177
	v_mul_f32_e32 v190, v190, v178
	v_mul_f32_e32 v191, v191, v179
	v_cvt_pk_bf16_f32 v148, v188, v189
	v_cvt_pk_bf16_f32 v149, v190, v191
	v_mul_f32_e32 v176, 0x3f3504f3, v58
	v_mul_f32_e32 v177, 0x3f3504f3, v59
	v_mul_f32_e32 v178, 0x3f3504f3, v60
	v_mul_f32_e32 v179, 0x3f3504f3, v61
	v_fma_f32 v180, |v176|, s9, 1.0
	v_fma_f32 v181, |v177|, s9, 1.0
	v_fma_f32 v182, |v178|, s9, 1.0
	v_fma_f32 v183, |v179|, s9, 1.0
	v_rcp_f32_e32 v180, v180
	v_rcp_f32_e32 v181, v181
	v_rcp_f32_e32 v182, v182
	v_rcp_f32_e32 v183, v183
	v_mul_f32_e32 v188, 0.5, v58
	v_mul_f32_e32 v189, 0.5, v59
	v_mul_f32_e32 v190, 0.5, v60
	v_mul_f32_e32 v191, 0.5, v61
	v_fmamk_f32 v184, v180, 0x3f87dc22, v206
	v_fmamk_f32 v185, v181, 0x3f87dc22, v206
	v_fmamk_f32 v186, v182, 0x3f87dc22, v206
	v_fmamk_f32 v187, v183, 0x3f87dc22, v206
	v_fmaak_f32 v184, v184, v180, 0x3fb5f0e3
	v_fmaak_f32 v185, v185, v181, 0x3fb5f0e3
	v_fmaak_f32 v186, v186, v182, 0x3fb5f0e3
	v_fmaak_f32 v187, v187, v183, 0x3fb5f0e3
	v_fmaak_f32 v184, v184, v180, 0xbe91a98e
	v_fmaak_f32 v185, v185, v181, 0xbe91a98e
	v_fmaak_f32 v186, v186, v182, 0xbe91a98e
	v_fmaak_f32 v187, v187, v183, 0xbe91a98e
	v_fmaak_f32 v184, v184, v180, 0x3e827906
	v_fmaak_f32 v185, v185, v181, 0x3e827906
	v_fmaak_f32 v186, v186, v182, 0x3e827906
	v_fmaak_f32 v187, v187, v183, 0x3e827906
	v_mul_f32_e32 v180, v180, v184
	v_mul_f32_e32 v181, v181, v185
	v_mul_f32_e32 v182, v182, v186
	v_mul_f32_e32 v183, v183, v187
	v_mul_f32_e64 v184, |v176|, |v176|
	v_mul_f32_e64 v185, |v177|, |v177|
	v_mul_f32_e64 v186, |v178|, |v178|
	v_mul_f32_e64 v187, |v179|, |v179|
	v_mul_f32_e32 v184, 0xbfb8aa3b, v184
	v_mul_f32_e32 v185, 0xbfb8aa3b, v185
	v_mul_f32_e32 v186, 0xbfb8aa3b, v186
	v_mul_f32_e32 v187, 0xbfb8aa3b, v187
	v_exp_f32_e32 v184, v184
	v_exp_f32_e32 v185, v185
	v_exp_f32_e32 v186, v186
	v_exp_f32_e32 v187, v187
	v_fma_f32 v180, -v184, v180, 1.0
	v_fma_f32 v181, -v185, v181, 1.0
; __device__ __forceinline__ unsigned pack2(float a, float b) { const f32x2_t v = {a, b}; const bf16x2_t r = __builtin_convertvector(v, bf16x2_t); return __builtin_bit_cast(unsigned, r); }
; __device__ __forceinline__ float erf_fast(float x) {
;   const float ax = fabsf(x);
;   const float t = __builtin_amdgcn_rcpf(fmaf(0.3275911f, ax, 1.f));
;   float y = fmaf(1.061405429f, t, -1.453152027f);
;   y = fmaf(y, t, 1.421413741f);
;   y = fmaf(y, t, -0.284496736f);
;   y = fmaf(y, t, 0.254829592f);
;   y = 1.f - y * t * __expf(-ax * ax);
;   return copysignf(y, x);
; }
; __device__ __forceinline__ void ph_proj(const Params& p, int l, char* shm) {
;     ...
;     gemm_tile8(p.H + (size_t)brow * DM, DM, W + (size_t)pn * 256 * DM, DM, DM, shm, [&](int r, int c, f32x4 v) {
;       if (pn == 34) {
;         *(f32x4*)(p.KW + (size_t)(brow + r) * 256 + c) = v;
;       } else {
;         float y[4];
; #pragma unroll
;         for (int j = 0; j < 4; ++j) {
;           float xv = v[j];
;           if (act == 1) xv = xv * __builtin_amdgcn_rcpf(1.f + __expf(-xv));
;           else if (act == 2) xv = 0.5f * xv * (1.f + erf_fast(xv * 0.70710678118654752f));
;           y[j] = xv;
;         }
;         *(uint2*)(p.P + (size_t)(brow + r) * NP + pn * 256 + c) = uint2{pack2(y[0], y[1]), pack2(y[2], y[3])};
;       }
;     });
	v_fma_f32 v182, -v186, v182, 1.0
	v_fma_f32 v183, -v187, v183, 1.0
	v_bfi_b32 v176, s10, v180, v176
	v_bfi_b32 v177, s10, v181, v177
	v_bfi_b32 v178, s10, v182, v178
	v_bfi_b32 v179, s10, v183, v179
	v_add_f32_e32 v176, 1.0, v176
	v_add_f32_e32 v177, 1.0, v177
	v_add_f32_e32 v178, 1.0, v178
	v_add_f32_e32 v179, 1.0, v179
	v_mul_f32_e32 v188, v188, v176
	v_mul_f32_e32 v189, v189, v177
	v_mul_f32_e32 v190, v190, v178
	v_mul_f32_e32 v191, v191, v179
	v_cvt_pk_bf16_f32 v150, v188, v189
	v_cvt_pk_bf16_f32 v151, v190, v191
	s_nop 1
	v_permlane16_swap_b32_e32 v144, v146
	v_permlane16_swap_b32_e32 v145, v147
	global_store_dwordx4 v[166:167], v[144:147], off offset:256 nt
	v_mul_f32_e32 v176, 0x3f3504f3, v54
	v_mul_f32_e32 v177, 0x3f3504f3, v55
	v_mul_f32_e32 v178, 0x3f3504f3, v56
	v_mul_f32_e32 v179, 0x3f3504f3, v57
	v_fma_f32 v180, |v176|, s9, 1.0
	v_fma_f32 v181, |v177|, s9, 1.0
	v_fma_f32 v182, |v178|, s9, 1.0
	v_fma_f32 v183, |v179|, s9, 1.0
	v_rcp_f32_e32 v180, v180
	v_rcp_f32_e32 v181, v181
	v_rcp_f32_e32 v182, v182
	v_rcp_f32_e32 v183, v183
	v_mul_f32_e32 v188, 0.5, v54
	v_mul_f32_e32 v189, 0.5, v55
	v_mul_f32_e32 v190, 0.5, v56
	v_mul_f32_e32 v191, 0.5, v57
	v_fmamk_f32 v184, v180, 0x3f87dc22, v206
	v_fmamk_f32 v185, v181, 0x3f87dc22, v206
	v_fmamk_f32 v186, v182, 0x3f87dc22, v206
	v_fmamk_f32 v187, v183, 0x3f87dc22, v206
	v_fmaak_f32 v184, v184, v180, 0x3fb5f0e3
	v_fmaak_f32 v185, v185, v181, 0x3fb5f0e3
	v_fmaak_f32 v186, v186, v182, 0x3fb5f0e3
	v_fmaak_f32 v187, v187, v183, 0x3fb5f0e3
	v_fmaak_f32 v184, v184, v180, 0xbe91a98e
	v_fmaak_f32 v185, v185, v181, 0xbe91a98e
	v_fmaak_f32 v186, v186, v182, 0xbe91a98e
	v_fmaak_f32 v187, v187, v183, 0xbe91a98e
	v_fmaak_f32 v184, v184, v180, 0x3e827906
	v_fmaak_f32 v185, v185, v181, 0x3e827906
	v_fmaak_f32 v186, v186, v182, 0x3e827906
	v_fmaak_f32 v187, v187, v183, 0x3e827906
	v_mul_f32_e32 v180, v180, v184
	v_mul_f32_e32 v181, v181, v185
	v_mul_f32_e32 v182, v182, v186
	v_mul_f32_e32 v183, v183, v187
	v_mul_f32_e64 v184, |v176|, |v176|
	v_mul_f32_e64 v185, |v177|, |v177|
	v_mul_f32_e64 v186, |v178|, |v178|
	v_mul_f32_e64 v187, |v179|, |v179|
	v_mul_f32_e32 v184, 0xbfb8aa3b, v184
	v_mul_f32_e32 v185, 0xbfb8aa3b, v185
	v_mul_f32_e32 v186, 0xbfb8aa3b, v186
	v_mul_f32_e32 v187, 0xbfb8aa3b, v187
	v_exp_f32_e32 v184, v184
	v_exp_f32_e32 v185, v185
	v_exp_f32_e32 v186, v186
	v_exp_f32_e32 v187, v187
	v_fma_f32 v180, -v184, v180, 1.0
	v_fma_f32 v181, -v185, v181, 1.0
	v_fma_f32 v182, -v186, v182, 1.0
	v_fma_f32 v183, -v187, v183, 1.0
	v_bfi_b32 v176, s10, v180, v176
	v_bfi_b32 v177, s10, v181, v177
	v_bfi_b32 v178, s10, v182, v178
	v_bfi_b32 v179, s10, v183, v179
	v_add_f32_e32 v176, 1.0, v176
	v_add_f32_e32 v177, 1.0, v177
	v_add_f32_e32 v178, 1.0, v178
	v_add_f32_e32 v179, 1.0, v179
	v_mul_f32_e32 v188, v188, v176
	v_mul_f32_e32 v189, v189, v177
	v_mul_f32_e32 v190, v190, v178
	v_mul_f32_e32 v191, v191, v179
	v_cvt_pk_bf16_f32 v140, v188, v189
	v_cvt_pk_bf16_f32 v141, v190, v191
	v_mul_f32_e32 v176, 0x3f3504f3, v50
	v_mul_f32_e32 v177, 0x3f3504f3, v51
	v_mul_f32_e32 v178, 0x3f3504f3, v52
	v_mul_f32_e32 v179, 0x3f3504f3, v53
	v_fma_f32 v180, |v176|, s9, 1.0
	v_fma_f32 v181, |v177|, s9, 1.0
	v_fma_f32 v182, |v178|, s9, 1.0
	v_fma_f32 v183, |v179|, s9, 1.0
	v_rcp_f32_e32 v180, v180
	v_rcp_f32_e32 v181, v181
	v_rcp_f32_e32 v182, v182
	v_rcp_f32_e32 v183, v183
	v_mul_f32_e32 v188, 0.5, v50
	v_mul_f32_e32 v189, 0.5, v51
	v_mul_f32_e32 v190, 0.5, v52
	v_mul_f32_e32 v191, 0.5, v53
	v_fmamk_f32 v184, v180, 0x3f87dc22, v206
	v_fmamk_f32 v185, v181, 0x3f87dc22, v206
	v_fmamk_f32 v186, v182, 0x3f87dc22, v206
	v_fmamk_f32 v187, v183, 0x3f87dc22, v206
	v_fmaak_f32 v184, v184, v180, 0x3fb5f0e3
	v_fmaak_f32 v185, v185, v181, 0x3fb5f0e3
	v_fmaak_f32 v186, v186, v182, 0x3fb5f0e3
	v_fmaak_f32 v187, v187, v183, 0x3fb5f0e3
	v_fmaak_f32 v184, v184, v180, 0xbe91a98e
	v_fmaak_f32 v185, v185, v181, 0xbe91a98e
	v_fmaak_f32 v186, v186, v182, 0xbe91a98e
	v_fmaak_f32 v187, v187, v183, 0xbe91a98e
	v_fmaak_f32 v184, v184, v180, 0x3e827906
	v_fmaak_f32 v185, v185, v181, 0x3e827906
	v_fmaak_f32 v186, v186, v182, 0x3e827906
	v_fmaak_f32 v187, v187, v183, 0x3e827906
	v_mul_f32_e32 v180, v180, v184
	v_mul_f32_e32 v181, v181, v185
	v_mul_f32_e32 v182, v182, v186
	v_mul_f32_e32 v183, v183, v187
	v_mul_f32_e64 v184, |v176|, |v176|
	v_mul_f32_e64 v185, |v177|, |v177|
	v_mul_f32_e64 v186, |v178|, |v178|
	v_mul_f32_e64 v187, |v179|, |v179|
	v_mul_f32_e32 v184, 0xbfb8aa3b, v184
	v_mul_f32_e32 v185, 0xbfb8aa3b, v185
	v_mul_f32_e32 v186, 0xbfb8aa3b, v186
	v_mul_f32_e32 v187, 0xbfb8aa3b, v187
	v_exp_f32_e32 v184, v184
	v_exp_f32_e32 v185, v185
	v_exp_f32_e32 v186, v186
	v_exp_f32_e32 v187, v187
	v_fma_f32 v180, -v184, v180, 1.0
	v_fma_f32 v181, -v185, v181, 1.0
	v_fma_f32 v182, -v186, v182, 1.0
	v_fma_f32 v183, -v187, v183, 1.0
	v_bfi_b32 v176, s10, v180, v176
	v_bfi_b32 v177, s10, v181, v177
	v_bfi_b32 v178, s10, v182, v178
	v_bfi_b32 v179, s10, v183, v179
	v_add_f32_e32 v176, 1.0, v176
	v_add_f32_e32 v177, 1.0, v177
	v_add_f32_e32 v178, 1.0, v178
	v_add_f32_e32 v179, 1.0, v179
	v_mul_f32_e32 v188, v188, v176
	v_mul_f32_e32 v189, v189, v177
	v_mul_f32_e32 v190, v190, v178
	v_mul_f32_e32 v191, v191, v179
	v_cvt_pk_bf16_f32 v142, v188, v189
	v_cvt_pk_bf16_f32 v143, v190, v191
	s_nop 1
	v_permlane16_swap_b32_e32 v148, v150
	v_permlane16_swap_b32_e32 v149, v151
	global_store_dwordx4 v[168:169], v[148:151], off nt
	v_mul_f32_e32 v176, 0x3f3504f3, v46
	v_mul_f32_e32 v177, 0x3f3504f3, v47
	v_mul_f32_e32 v178, 0x3f3504f3, v48
	v_mul_f32_e32 v179, 0x3f3504f3, v49
	v_fma_f32 v180, |v176|, s9, 1.0
	v_fma_f32 v181, |v177|, s9, 1.0
	v_fma_f32 v182, |v178|, s9, 1.0
; __device__ __forceinline__ unsigned pack2(float a, float b) { const f32x2_t v = {a, b}; const bf16x2_t r = __builtin_convertvector(v, bf16x2_t); return __builtin_bit_cast(unsigned, r); }
; __device__ __forceinline__ float erf_fast(float x) {
;   const float ax = fabsf(x);
;   const float t = __builtin_amdgcn_rcpf(fmaf(0.3275911f, ax, 1.f));
;   float y = fmaf(1.061405429f, t, -1.453152027f);
;   y = fmaf(y, t, 1.421413741f);
;   y = fmaf(y, t, -0.284496736f);
;   y = fmaf(y, t, 0.254829592f);
;   y = 1.f - y * t * __expf(-ax * ax);
;   return copysignf(y, x);
; }
; __device__ __forceinline__ void ph_proj(const Params& p, int l, char* shm) {
;     ...
;     gemm_tile8(p.H + (size_t)brow * DM, DM, W + (size_t)pn * 256 * DM, DM, DM, shm, [&](int r, int c, f32x4 v) {
;       if (pn == 34) {
;         *(f32x4*)(p.KW + (size_t)(brow + r) * 256 + c) = v;
;       } else {
;         float y[4];
; #pragma unroll
;         for (int j = 0; j < 4; ++j) {
;           float xv = v[j];
;           if (act == 1) xv = xv * __builtin_amdgcn_rcpf(1.f + __expf(-xv));
;           else if (act == 2) xv = 0.5f * xv * (1.f + erf_fast(xv * 0.70710678118654752f));
;           y[j] = xv;
;         }
;         *(uint2*)(p.P + (size_t)(brow + r) * NP + pn * 256 + c) = uint2{pack2(y[0], y[1]), pack2(y[2], y[3])};
;       }
;     });
	v_fma_f32 v183, |v179|, s9, 1.0
	v_rcp_f32_e32 v180, v180
	v_rcp_f32_e32 v181, v181
	v_rcp_f32_e32 v182, v182
	v_rcp_f32_e32 v183, v183
	v_mul_f32_e32 v188, 0.5, v46
	v_mul_f32_e32 v189, 0.5, v47
	v_mul_f32_e32 v190, 0.5, v48
	v_mul_f32_e32 v191, 0.5, v49
	v_fmamk_f32 v184, v180, 0x3f87dc22, v206
	v_fmamk_f32 v185, v181, 0x3f87dc22, v206
	v_fmamk_f32 v186, v182, 0x3f87dc22, v206
	v_fmamk_f32 v187, v183, 0x3f87dc22, v206
	v_fmaak_f32 v184, v184, v180, 0x3fb5f0e3
	v_fmaak_f32 v185, v185, v181, 0x3fb5f0e3
	v_fmaak_f32 v186, v186, v182, 0x3fb5f0e3
	v_fmaak_f32 v187, v187, v183, 0x3fb5f0e3
	v_fmaak_f32 v184, v184, v180, 0xbe91a98e
	v_fmaak_f32 v185, v185, v181, 0xbe91a98e
	v_fmaak_f32 v186, v186, v182, 0xbe91a98e
	v_fmaak_f32 v187, v187, v183, 0xbe91a98e
	v_fmaak_f32 v184, v184, v180, 0x3e827906
	v_fmaak_f32 v185, v185, v181, 0x3e827906
	v_fmaak_f32 v186, v186, v182, 0x3e827906
	v_fmaak_f32 v187, v187, v183, 0x3e827906
	v_mul_f32_e32 v180, v180, v184
	v_mul_f32_e32 v181, v181, v185
	v_mul_f32_e32 v182, v182, v186
	v_mul_f32_e32 v183, v183, v187
	v_mul_f32_e64 v184, |v176|, |v176|
	v_mul_f32_e64 v185, |v177|, |v177|
	v_mul_f32_e64 v186, |v178|, |v178|
	v_mul_f32_e64 v187, |v179|, |v179|
	v_mul_f32_e32 v184, 0xbfb8aa3b, v184
	v_mul_f32_e32 v185, 0xbfb8aa3b, v185
	v_mul_f32_e32 v186, 0xbfb8aa3b, v186
	v_mul_f32_e32 v187, 0xbfb8aa3b, v187
	v_exp_f32_e32 v184, v184
	v_exp_f32_e32 v185, v185
	v_exp_f32_e32 v186, v186
	v_exp_f32_e32 v187, v187
	v_fma_f32 v180, -v184, v180, 1.0
	v_fma_f32 v181, -v185, v181, 1.0
	v_fma_f32 v182, -v186, v182, 1.0
	v_fma_f32 v183, -v187, v183, 1.0
	v_bfi_b32 v176, s10, v180, v176
	v_bfi_b32 v177, s10, v181, v177
	v_bfi_b32 v178, s10, v182, v178
	v_bfi_b32 v179, s10, v183, v179
	v_add_f32_e32 v176, 1.0, v176
	v_add_f32_e32 v177, 1.0, v177
	v_add_f32_e32 v178, 1.0, v178
	v_add_f32_e32 v179, 1.0, v179
	v_mul_f32_e32 v188, v188, v176
	v_mul_f32_e32 v189, v189, v177
	v_mul_f32_e32 v190, v190, v178
	v_mul_f32_e32 v191, v191, v179
	v_cvt_pk_bf16_f32 v144, v188, v189
	v_cvt_pk_bf16_f32 v145, v190, v191
	v_mul_f32_e32 v176, 0x3f3504f3, v42
	v_mul_f32_e32 v177, 0x3f3504f3, v43
	v_mul_f32_e32 v178, 0x3f3504f3, v44
	v_mul_f32_e32 v179, 0x3f3504f3, v45
	v_fma_f32 v180, |v176|, s9, 1.0
	v_fma_f32 v181, |v177|, s9, 1.0
	v_fma_f32 v182, |v178|, s9, 1.0
	v_fma_f32 v183, |v179|, s9, 1.0
	v_rcp_f32_e32 v180, v180
	v_rcp_f32_e32 v181, v181
	v_rcp_f32_e32 v182, v182
	v_rcp_f32_e32 v183, v183
	v_mul_f32_e32 v188, 0.5, v42
	v_mul_f32_e32 v189, 0.5, v43
	v_mul_f32_e32 v190, 0.5, v44
	v_mul_f32_e32 v191, 0.5, v45
	v_fmamk_f32 v184, v180, 0x3f87dc22, v206
	v_fmamk_f32 v185, v181, 0x3f87dc22, v206
	v_fmamk_f32 v186, v182, 0x3f87dc22, v206
	v_fmamk_f32 v187, v183, 0x3f87dc22, v206
	v_fmaak_f32 v184, v184, v180, 0x3fb5f0e3
	v_fmaak_f32 v185, v185, v181, 0x3fb5f0e3
	v_fmaak_f32 v186, v186, v182, 0x3fb5f0e3
	v_fmaak_f32 v187, v187, v183, 0x3fb5f0e3
	v_fmaak_f32 v184, v184, v180, 0xbe91a98e
	v_fmaak_f32 v185, v185, v181, 0xbe91a98e
	v_fmaak_f32 v186, v186, v182, 0xbe91a98e
	v_fmaak_f32 v187, v187, v183, 0xbe91a98e
	v_fmaak_f32 v184, v184, v180, 0x3e827906
	v_fmaak_f32 v185, v185, v181, 0x3e827906
	v_fmaak_f32 v186, v186, v182, 0x3e827906
	v_fmaak_f32 v187, v187, v183, 0x3e827906
	v_mul_f32_e32 v180, v180, v184
	v_mul_f32_e32 v181, v181, v185
	v_mul_f32_e32 v182, v182, v186
	v_mul_f32_e32 v183, v183, v187
	v_mul_f32_e64 v184, |v176|, |v176|
	v_mul_f32_e64 v185, |v177|, |v177|
	v_mul_f32_e64 v186, |v178|, |v178|
	v_mul_f32_e64 v187, |v179|, |v179|
	v_mul_f32_e32 v184, 0xbfb8aa3b, v184
	v_mul_f32_e32 v185, 0xbfb8aa3b, v185
	v_mul_f32_e32 v186, 0xbfb8aa3b, v186
	v_mul_f32_e32 v187, 0xbfb8aa3b, v187
	v_exp_f32_e32 v184, v184
	v_exp_f32_e32 v185, v185
	v_exp_f32_e32 v186, v186
	v_exp_f32_e32 v187, v187
	v_fma_f32 v180, -v184, v180, 1.0
	v_fma_f32 v181, -v185, v181, 1.0
	v_fma_f32 v182, -v186, v182, 1.0
	v_fma_f32 v183, -v187, v183, 1.0
	v_bfi_b32 v176, s10, v180, v176
	v_bfi_b32 v177, s10, v181, v177
	v_bfi_b32 v178, s10, v182, v178
	v_bfi_b32 v179, s10, v183, v179
	v_add_f32_e32 v176, 1.0, v176
	v_add_f32_e32 v177, 1.0, v177
	v_add_f32_e32 v178, 1.0, v178
	v_add_f32_e32 v179, 1.0, v179
	v_mul_f32_e32 v188, v188, v176
	v_mul_f32_e32 v189, v189, v177
	v_mul_f32_e32 v190, v190, v178
	v_mul_f32_e32 v191, v191, v179
	v_cvt_pk_bf16_f32 v146, v188, v189
	v_cvt_pk_bf16_f32 v147, v190, v191
	s_nop 1
	v_permlane16_swap_b32_e32 v140, v142
	v_permlane16_swap_b32_e32 v141, v143
	global_store_dwordx4 v[170:171], v[140:143], off nt
	v_mul_f32_e32 v176, 0x3f3504f3, v38
	v_mul_f32_e32 v177, 0x3f3504f3, v39
	v_mul_f32_e32 v178, 0x3f3504f3, v40
	v_mul_f32_e32 v179, 0x3f3504f3, v41
	v_fma_f32 v180, |v176|, s9, 1.0
	v_fma_f32 v181, |v177|, s9, 1.0
	v_fma_f32 v182, |v178|, s9, 1.0
	v_fma_f32 v183, |v179|, s9, 1.0
	v_rcp_f32_e32 v180, v180
	v_rcp_f32_e32 v181, v181
	v_rcp_f32_e32 v182, v182
	v_rcp_f32_e32 v183, v183
	v_mul_f32_e32 v188, 0.5, v38
	v_mul_f32_e32 v189, 0.5, v39
	v_mul_f32_e32 v190, 0.5, v40
	v_mul_f32_e32 v191, 0.5, v41
	v_fmamk_f32 v184, v180, 0x3f87dc22, v206
	v_fmamk_f32 v185, v181, 0x3f87dc22, v206
	v_fmamk_f32 v186, v182, 0x3f87dc22, v206
	v_fmamk_f32 v187, v183, 0x3f87dc22, v206
	v_fmaak_f32 v184, v184, v180, 0x3fb5f0e3
	v_fmaak_f32 v185, v185, v181, 0x3fb5f0e3
	v_fmaak_f32 v186, v186, v182, 0x3fb5f0e3
	v_fmaak_f32 v187, v187, v183, 0x3fb5f0e3
	v_fmaak_f32 v184, v184, v180, 0xbe91a98e
	v_fmaak_f32 v185, v185, v181, 0xbe91a98e
	v_fmaak_f32 v186, v186, v182, 0xbe91a98e
	v_fmaak_f32 v187, v187, v183, 0xbe91a98e
	v_fmaak_f32 v184, v184, v180, 0x3e827906
	v_fmaak_f32 v185, v185, v181, 0x3e827906
	v_fmaak_f32 v186, v186, v182, 0x3e827906
	v_fmaak_f32 v187, v187, v183, 0x3e827906
; __device__ __forceinline__ unsigned pack2(float a, float b) { const f32x2_t v = {a, b}; const bf16x2_t r = __builtin_convertvector(v, bf16x2_t); return __builtin_bit_cast(unsigned, r); }
; __device__ __forceinline__ float erf_fast(float x) {
;   const float ax = fabsf(x);
;   const float t = __builtin_amdgcn_rcpf(fmaf(0.3275911f, ax, 1.f));
;   float y = fmaf(1.061405429f, t, -1.453152027f);
;   y = fmaf(y, t, 1.421413741f);
;   y = fmaf(y, t, -0.284496736f);
;   y = fmaf(y, t, 0.254829592f);
;   y = 1.f - y * t * __expf(-ax * ax);
;   return copysignf(y, x);
; }
; __device__ __forceinline__ void ph_proj(const Params& p, int l, char* shm) {
;     ...
;     gemm_tile8(p.H + (size_t)brow * DM, DM, W + (size_t)pn * 256 * DM, DM, DM, shm, [&](int r, int c, f32x4 v) {
;       if (pn == 34) {
;         *(f32x4*)(p.KW + (size_t)(brow + r) * 256 + c) = v;
;       } else {
;         float y[4];
; #pragma unroll
;         for (int j = 0; j < 4; ++j) {
;           float xv = v[j];
;           if (act == 1) xv = xv * __builtin_amdgcn_rcpf(1.f + __expf(-xv));
;           else if (act == 2) xv = 0.5f * xv * (1.f + erf_fast(xv * 0.70710678118654752f));
;           y[j] = xv;
;         }
;         *(uint2*)(p.P + (size_t)(brow + r) * NP + pn * 256 + c) = uint2{pack2(y[0], y[1]), pack2(y[2], y[3])};
;       }
;     });
	v_mul_f32_e32 v180, v180, v184
	v_mul_f32_e32 v181, v181, v185
	v_mul_f32_e32 v182, v182, v186
	v_mul_f32_e32 v183, v183, v187
	v_mul_f32_e64 v184, |v176|, |v176|
	v_mul_f32_e64 v185, |v177|, |v177|
	v_mul_f32_e64 v186, |v178|, |v178|
	v_mul_f32_e64 v187, |v179|, |v179|
	v_mul_f32_e32 v184, 0xbfb8aa3b, v184
	v_mul_f32_e32 v185, 0xbfb8aa3b, v185
	v_mul_f32_e32 v186, 0xbfb8aa3b, v186
	v_mul_f32_e32 v187, 0xbfb8aa3b, v187
	v_exp_f32_e32 v184, v184
	v_exp_f32_e32 v185, v185
	v_exp_f32_e32 v186, v186
	v_exp_f32_e32 v187, v187
	v_fma_f32 v180, -v184, v180, 1.0
	v_fma_f32 v181, -v185, v181, 1.0
	v_fma_f32 v182, -v186, v182, 1.0
	v_fma_f32 v183, -v187, v183, 1.0
	v_bfi_b32 v176, s10, v180, v176
	v_bfi_b32 v177, s10, v181, v177
	v_bfi_b32 v178, s10, v182, v178
	v_bfi_b32 v179, s10, v183, v179
	v_add_f32_e32 v176, 1.0, v176
	v_add_f32_e32 v177, 1.0, v177
	v_add_f32_e32 v178, 1.0, v178
	v_add_f32_e32 v179, 1.0, v179
	v_mul_f32_e32 v188, v188, v176
	v_mul_f32_e32 v189, v189, v177
	v_mul_f32_e32 v190, v190, v178
	v_mul_f32_e32 v191, v191, v179
	v_cvt_pk_bf16_f32 v148, v188, v189
	v_cvt_pk_bf16_f32 v149, v190, v191
	v_mul_f32_e32 v176, 0x3f3504f3, v34
	v_mul_f32_e32 v177, 0x3f3504f3, v35
	v_mul_f32_e32 v178, 0x3f3504f3, v36
	v_mul_f32_e32 v179, 0x3f3504f3, v37
	v_fma_f32 v180, |v176|, s9, 1.0
	v_fma_f32 v181, |v177|, s9, 1.0
	v_fma_f32 v182, |v178|, s9, 1.0
	v_fma_f32 v183, |v179|, s9, 1.0
	v_rcp_f32_e32 v180, v180
	v_rcp_f32_e32 v181, v181
	v_rcp_f32_e32 v182, v182
	v_rcp_f32_e32 v183, v183
	v_mul_f32_e32 v188, 0.5, v34
	v_mul_f32_e32 v189, 0.5, v35
	v_mul_f32_e32 v190, 0.5, v36
	v_mul_f32_e32 v191, 0.5, v37
	v_fmamk_f32 v184, v180, 0x3f87dc22, v206
	v_fmamk_f32 v185, v181, 0x3f87dc22, v206
	v_fmamk_f32 v186, v182, 0x3f87dc22, v206
	v_fmamk_f32 v187, v183, 0x3f87dc22, v206
	v_fmaak_f32 v184, v184, v180, 0x3fb5f0e3
	v_fmaak_f32 v185, v185, v181, 0x3fb5f0e3
	v_fmaak_f32 v186, v186, v182, 0x3fb5f0e3
	v_fmaak_f32 v187, v187, v183, 0x3fb5f0e3
	v_fmaak_f32 v184, v184, v180, 0xbe91a98e
	v_fmaak_f32 v185, v185, v181, 0xbe91a98e
	v_fmaak_f32 v186, v186, v182, 0xbe91a98e
	v_fmaak_f32 v187, v187, v183, 0xbe91a98e
	v_fmaak_f32 v184, v184, v180, 0x3e827906
	v_fmaak_f32 v185, v185, v181, 0x3e827906
	v_fmaak_f32 v186, v186, v182, 0x3e827906
	v_fmaak_f32 v187, v187, v183, 0x3e827906
	v_mul_f32_e32 v180, v180, v184
	v_mul_f32_e32 v181, v181, v185
	v_mul_f32_e32 v182, v182, v186
	v_mul_f32_e32 v183, v183, v187
	v_mul_f32_e64 v184, |v176|, |v176|
	v_mul_f32_e64 v185, |v177|, |v177|
	v_mul_f32_e64 v186, |v178|, |v178|
	v_mul_f32_e64 v187, |v179|, |v179|
	v_mul_f32_e32 v184, 0xbfb8aa3b, v184
	v_mul_f32_e32 v185, 0xbfb8aa3b, v185
	v_mul_f32_e32 v186, 0xbfb8aa3b, v186
	v_mul_f32_e32 v187, 0xbfb8aa3b, v187
	v_exp_f32_e32 v184, v184
	v_exp_f32_e32 v185, v185
	v_exp_f32_e32 v186, v186
	v_exp_f32_e32 v187, v187
	v_fma_f32 v180, -v184, v180, 1.0
	v_fma_f32 v181, -v185, v181, 1.0
	v_fma_f32 v182, -v186, v182, 1.0
	v_fma_f32 v183, -v187, v183, 1.0
	v_bfi_b32 v176, s10, v180, v176
	v_bfi_b32 v177, s10, v181, v177
	v_bfi_b32 v178, s10, v182, v178
	v_bfi_b32 v179, s10, v183, v179
	v_add_f32_e32 v176, 1.0, v176
	v_add_f32_e32 v177, 1.0, v177
	v_add_f32_e32 v178, 1.0, v178
	v_add_f32_e32 v179, 1.0, v179
	v_mul_f32_e32 v188, v188, v176
	v_mul_f32_e32 v189, v189, v177
	v_mul_f32_e32 v190, v190, v178
	v_mul_f32_e32 v191, v191, v179
	v_cvt_pk_bf16_f32 v150, v188, v189
	v_cvt_pk_bf16_f32 v151, v190, v191
	s_nop 1
	v_permlane16_swap_b32_e32 v144, v146
	v_permlane16_swap_b32_e32 v145, v147
	global_store_dwordx4 v[172:173], v[144:147], off nt
	v_mul_f32_e32 v176, 0x3f3504f3, v28
	v_mul_f32_e32 v177, 0x3f3504f3, v29
	v_mul_f32_e32 v178, 0x3f3504f3, v30
	v_mul_f32_e32 v179, 0x3f3504f3, v31
	v_fma_f32 v180, |v176|, s9, 1.0
	v_fma_f32 v181, |v177|, s9, 1.0
	v_fma_f32 v182, |v178|, s9, 1.0
	v_fma_f32 v183, |v179|, s9, 1.0
	v_rcp_f32_e32 v180, v180
	v_rcp_f32_e32 v181, v181
	v_rcp_f32_e32 v182, v182
	v_rcp_f32_e32 v183, v183
	v_mul_f32_e32 v188, 0.5, v28
	v_mul_f32_e32 v189, 0.5, v29
	v_mul_f32_e32 v190, 0.5, v30
	v_mul_f32_e32 v191, 0.5, v31
	v_fmamk_f32 v184, v180, 0x3f87dc22, v206
	v_fmamk_f32 v185, v181, 0x3f87dc22, v206
	v_fmamk_f32 v186, v182, 0x3f87dc22, v206
	v_fmamk_f32 v187, v183, 0x3f87dc22, v206
	v_fmaak_f32 v184, v184, v180, 0x3fb5f0e3
	v_fmaak_f32 v185, v185, v181, 0x3fb5f0e3
	v_fmaak_f32 v186, v186, v182, 0x3fb5f0e3
	v_fmaak_f32 v187, v187, v183, 0x3fb5f0e3
	v_fmaak_f32 v184, v184, v180, 0xbe91a98e
	v_fmaak_f32 v185, v185, v181, 0xbe91a98e
	v_fmaak_f32 v186, v186, v182, 0xbe91a98e
	v_fmaak_f32 v187, v187, v183, 0xbe91a98e
	v_fmaak_f32 v184, v184, v180, 0x3e827906
	v_fmaak_f32 v185, v185, v181, 0x3e827906
	v_fmaak_f32 v186, v186, v182, 0x3e827906
	v_fmaak_f32 v187, v187, v183, 0x3e827906
	v_mul_f32_e32 v180, v180, v184
	v_mul_f32_e32 v181, v181, v185
	v_mul_f32_e32 v182, v182, v186
	v_mul_f32_e32 v183, v183, v187
	v_mul_f32_e64 v184, |v176|, |v176|
	v_mul_f32_e64 v185, |v177|, |v177|
	v_mul_f32_e64 v186, |v178|, |v178|
	v_mul_f32_e64 v187, |v179|, |v179|
	v_mul_f32_e32 v184, 0xbfb8aa3b, v184
	v_mul_f32_e32 v185, 0xbfb8aa3b, v185
	v_mul_f32_e32 v186, 0xbfb8aa3b, v186
	v_mul_f32_e32 v187, 0xbfb8aa3b, v187
	v_exp_f32_e32 v184, v184
	v_exp_f32_e32 v185, v185
	v_exp_f32_e32 v186, v186
	v_exp_f32_e32 v187, v187
	v_fma_f32 v180, -v184, v180, 1.0
	v_fma_f32 v181, -v185, v181, 1.0
	v_fma_f32 v182, -v186, v182, 1.0
	v_fma_f32 v183, -v187, v183, 1.0
	v_bfi_b32 v176, s10, v180, v176
	v_bfi_b32 v177, s10, v181, v177
	v_bfi_b32 v178, s10, v182, v178
	v_bfi_b32 v179, s10, v183, v179
	v_add_f32_e32 v176, 1.0, v176
	v_add_f32_e32 v177, 1.0, v177
	v_add_f32_e32 v178, 1.0, v178
	v_add_f32_e32 v179, 1.0, v179
; __device__ __forceinline__ unsigned pack2(float a, float b) { const f32x2_t v = {a, b}; const bf16x2_t r = __builtin_convertvector(v, bf16x2_t); return __builtin_bit_cast(unsigned, r); }
; __device__ __forceinline__ float erf_fast(float x) {
;   const float ax = fabsf(x);
;   const float t = __builtin_amdgcn_rcpf(fmaf(0.3275911f, ax, 1.f));
;   float y = fmaf(1.061405429f, t, -1.453152027f);
;   y = fmaf(y, t, 1.421413741f);
;   y = fmaf(y, t, -0.284496736f);
;   y = fmaf(y, t, 0.254829592f);
;   y = 1.f - y * t * __expf(-ax * ax);
;   return copysignf(y, x);
; }
; __device__ __forceinline__ void ph_proj(const Params& p, int l, char* shm) {
;     ...
;     gemm_tile8(p.H + (size_t)brow * DM, DM, W + (size_t)pn * 256 * DM, DM, DM, shm, [&](int r, int c, f32x4 v) {
;       if (pn == 34) {
;         *(f32x4*)(p.KW + (size_t)(brow + r) * 256 + c) = v;
;       } else {
;         float y[4];
; #pragma unroll
;         for (int j = 0; j < 4; ++j) {
;           float xv = v[j];
;           if (act == 1) xv = xv * __builtin_amdgcn_rcpf(1.f + __expf(-xv));
;           else if (act == 2) xv = 0.5f * xv * (1.f + erf_fast(xv * 0.70710678118654752f));
;           y[j] = xv;
;         }
;         *(uint2*)(p.P + (size_t)(brow + r) * NP + pn * 256 + c) = uint2{pack2(y[0], y[1]), pack2(y[2], y[3])};
;       }
;     });
	v_mul_f32_e32 v188, v188, v176
	v_mul_f32_e32 v189, v189, v177
	v_mul_f32_e32 v190, v190, v178
	v_mul_f32_e32 v191, v191, v179
	v_cvt_pk_bf16_f32 v140, v188, v189
	v_cvt_pk_bf16_f32 v141, v190, v191
	v_mul_f32_e32 v176, 0x3f3504f3, v24
	v_mul_f32_e32 v177, 0x3f3504f3, v25
	v_mul_f32_e32 v178, 0x3f3504f3, v26
	v_mul_f32_e32 v179, 0x3f3504f3, v27
	v_fma_f32 v180, |v176|, s9, 1.0
	v_fma_f32 v181, |v177|, s9, 1.0
	v_fma_f32 v182, |v178|, s9, 1.0
	v_fma_f32 v183, |v179|, s9, 1.0
	v_rcp_f32_e32 v180, v180
	v_rcp_f32_e32 v181, v181
	v_rcp_f32_e32 v182, v182
	v_rcp_f32_e32 v183, v183
	v_mul_f32_e32 v188, 0.5, v24
	v_mul_f32_e32 v189, 0.5, v25
	v_mul_f32_e32 v190, 0.5, v26
	v_mul_f32_e32 v191, 0.5, v27
	v_fmamk_f32 v184, v180, 0x3f87dc22, v206
	v_fmamk_f32 v185, v181, 0x3f87dc22, v206
	v_fmamk_f32 v186, v182, 0x3f87dc22, v206
	v_fmamk_f32 v187, v183, 0x3f87dc22, v206
	v_fmaak_f32 v184, v184, v180, 0x3fb5f0e3
	v_fmaak_f32 v185, v185, v181, 0x3fb5f0e3
	v_fmaak_f32 v186, v186, v182, 0x3fb5f0e3
	v_fmaak_f32 v187, v187, v183, 0x3fb5f0e3
	v_fmaak_f32 v184, v184, v180, 0xbe91a98e
	v_fmaak_f32 v185, v185, v181, 0xbe91a98e
	v_fmaak_f32 v186, v186, v182, 0xbe91a98e
	v_fmaak_f32 v187, v187, v183, 0xbe91a98e
	v_fmaak_f32 v184, v184, v180, 0x3e827906
	v_fmaak_f32 v185, v185, v181, 0x3e827906
	v_fmaak_f32 v186, v186, v182, 0x3e827906
	v_fmaak_f32 v187, v187, v183, 0x3e827906
	v_mul_f32_e32 v180, v180, v184
	v_mul_f32_e32 v181, v181, v185
	v_mul_f32_e32 v182, v182, v186
	v_mul_f32_e32 v183, v183, v187
	v_mul_f32_e64 v184, |v176|, |v176|
	v_mul_f32_e64 v185, |v177|, |v177|
	v_mul_f32_e64 v186, |v178|, |v178|
	v_mul_f32_e64 v187, |v179|, |v179|
	v_mul_f32_e32 v184, 0xbfb8aa3b, v184
	v_mul_f32_e32 v185, 0xbfb8aa3b, v185
	v_mul_f32_e32 v186, 0xbfb8aa3b, v186
	v_mul_f32_e32 v187, 0xbfb8aa3b, v187
	v_exp_f32_e32 v184, v184
	v_exp_f32_e32 v185, v185
	v_exp_f32_e32 v186, v186
	v_exp_f32_e32 v187, v187
	v_fma_f32 v180, -v184, v180, 1.0
	v_fma_f32 v181, -v185, v181, 1.0
	v_fma_f32 v182, -v186, v182, 1.0
	v_fma_f32 v183, -v187, v183, 1.0
	v_bfi_b32 v176, s10, v180, v176
	v_bfi_b32 v177, s10, v181, v177
	v_bfi_b32 v178, s10, v182, v178
	v_bfi_b32 v179, s10, v183, v179
	v_add_f32_e32 v176, 1.0, v176
	v_add_f32_e32 v177, 1.0, v177
	v_add_f32_e32 v178, 1.0, v178
	v_add_f32_e32 v179, 1.0, v179
	v_mul_f32_e32 v188, v188, v176
	v_mul_f32_e32 v189, v189, v177
	v_mul_f32_e32 v190, v190, v178
	v_mul_f32_e32 v191, v191, v179
	v_cvt_pk_bf16_f32 v142, v188, v189
	v_cvt_pk_bf16_f32 v143, v190, v191
	s_nop 1
	v_permlane16_swap_b32_e32 v148, v150
	v_permlane16_swap_b32_e32 v149, v151
	global_store_dwordx4 v[174:175], v[148:151], off nt
	v_mul_f32_e32 v176, 0x3f3504f3, v20
	v_mul_f32_e32 v177, 0x3f3504f3, v21
	v_mul_f32_e32 v178, 0x3f3504f3, v22
	v_mul_f32_e32 v179, 0x3f3504f3, v23
	v_fma_f32 v180, |v176|, s9, 1.0
	v_fma_f32 v181, |v177|, s9, 1.0
	v_fma_f32 v182, |v178|, s9, 1.0
	v_fma_f32 v183, |v179|, s9, 1.0
	v_rcp_f32_e32 v180, v180
	v_rcp_f32_e32 v181, v181
	v_rcp_f32_e32 v182, v182
	v_rcp_f32_e32 v183, v183
	v_mul_f32_e32 v188, 0.5, v20
	v_mul_f32_e32 v189, 0.5, v21
	v_mul_f32_e32 v190, 0.5, v22
	v_mul_f32_e32 v191, 0.5, v23
	v_fmamk_f32 v184, v180, 0x3f87dc22, v206
	v_fmamk_f32 v185, v181, 0x3f87dc22, v206
	v_fmamk_f32 v186, v182, 0x3f87dc22, v206
	v_fmamk_f32 v187, v183, 0x3f87dc22, v206
	v_fmaak_f32 v184, v184, v180, 0x3fb5f0e3
	v_fmaak_f32 v185, v185, v181, 0x3fb5f0e3
	v_fmaak_f32 v186, v186, v182, 0x3fb5f0e3
	v_fmaak_f32 v187, v187, v183, 0x3fb5f0e3
	v_fmaak_f32 v184, v184, v180, 0xbe91a98e
	v_fmaak_f32 v185, v185, v181, 0xbe91a98e
	v_fmaak_f32 v186, v186, v182, 0xbe91a98e
	v_fmaak_f32 v187, v187, v183, 0xbe91a98e
	v_fmaak_f32 v184, v184, v180, 0x3e827906
	v_fmaak_f32 v185, v185, v181, 0x3e827906
	v_fmaak_f32 v186, v186, v182, 0x3e827906
	v_fmaak_f32 v187, v187, v183, 0x3e827906
	v_mul_f32_e32 v180, v180, v184
	v_mul_f32_e32 v181, v181, v185
	v_mul_f32_e32 v182, v182, v186
	v_mul_f32_e32 v183, v183, v187
	v_mul_f32_e64 v184, |v176|, |v176|
	v_mul_f32_e64 v185, |v177|, |v177|
	v_mul_f32_e64 v186, |v178|, |v178|
	v_mul_f32_e64 v187, |v179|, |v179|
	v_mul_f32_e32 v184, 0xbfb8aa3b, v184
	v_mul_f32_e32 v185, 0xbfb8aa3b, v185
	v_mul_f32_e32 v186, 0xbfb8aa3b, v186
	v_mul_f32_e32 v187, 0xbfb8aa3b, v187
	v_exp_f32_e32 v184, v184
	v_exp_f32_e32 v185, v185
	v_exp_f32_e32 v186, v186
	v_exp_f32_e32 v187, v187
	v_fma_f32 v180, -v184, v180, 1.0
	v_fma_f32 v181, -v185, v181, 1.0
	v_fma_f32 v182, -v186, v182, 1.0
	v_fma_f32 v183, -v187, v183, 1.0
	v_bfi_b32 v176, s10, v180, v176
	v_bfi_b32 v177, s10, v181, v177
	v_bfi_b32 v178, s10, v182, v178
	v_bfi_b32 v179, s10, v183, v179
	v_add_f32_e32 v176, 1.0, v176
	v_add_f32_e32 v177, 1.0, v177
	v_add_f32_e32 v178, 1.0, v178
	v_add_f32_e32 v179, 1.0, v179
	v_mul_f32_e32 v188, v188, v176
	v_mul_f32_e32 v189, v189, v177
	v_mul_f32_e32 v190, v190, v178
	v_mul_f32_e32 v191, v191, v179
	v_cvt_pk_bf16_f32 v144, v188, v189
	v_cvt_pk_bf16_f32 v145, v190, v191
	v_mul_f32_e32 v176, 0x3f3504f3, v16
	v_mul_f32_e32 v177, 0x3f3504f3, v17
	v_mul_f32_e32 v178, 0x3f3504f3, v18
	v_mul_f32_e32 v179, 0x3f3504f3, v19
	v_fma_f32 v180, |v176|, s9, 1.0
	v_fma_f32 v181, |v177|, s9, 1.0
	v_fma_f32 v182, |v178|, s9, 1.0
	v_fma_f32 v183, |v179|, s9, 1.0
	v_rcp_f32_e32 v180, v180
	v_rcp_f32_e32 v181, v181
	v_rcp_f32_e32 v182, v182
	v_rcp_f32_e32 v183, v183
	v_mul_f32_e32 v188, 0.5, v16
	v_mul_f32_e32 v189, 0.5, v17
	v_mul_f32_e32 v190, 0.5, v18
	v_mul_f32_e32 v191, 0.5, v19
	v_fmamk_f32 v184, v180, 0x3f87dc22, v206
	v_fmamk_f32 v185, v181, 0x3f87dc22, v206
	v_fmamk_f32 v186, v182, 0x3f87dc22, v206
	v_fmamk_f32 v187, v183, 0x3f87dc22, v206
	v_fmaak_f32 v184, v184, v180, 0x3fb5f0e3
; __device__ __forceinline__ unsigned pack2(float a, float b) { const f32x2_t v = {a, b}; const bf16x2_t r = __builtin_convertvector(v, bf16x2_t); return __builtin_bit_cast(unsigned, r); }
; __device__ __forceinline__ float erf_fast(float x) {
;   const float ax = fabsf(x);
;   const float t = __builtin_amdgcn_rcpf(fmaf(0.3275911f, ax, 1.f));
;   float y = fmaf(1.061405429f, t, -1.453152027f);
;   y = fmaf(y, t, 1.421413741f);
;   y = fmaf(y, t, -0.284496736f);
;   y = fmaf(y, t, 0.254829592f);
;   y = 1.f - y * t * __expf(-ax * ax);
;   return copysignf(y, x);
; }
; __device__ __forceinline__ void ph_proj(const Params& p, int l, char* shm) {
;     ...
;     gemm_tile8(p.H + (size_t)brow * DM, DM, W + (size_t)pn * 256 * DM, DM, DM, shm, [&](int r, int c, f32x4 v) {
;       if (pn == 34) {
;         *(f32x4*)(p.KW + (size_t)(brow + r) * 256 + c) = v;
;       } else {
;         float y[4];
; #pragma unroll
;         for (int j = 0; j < 4; ++j) {
;           float xv = v[j];
;           if (act == 1) xv = xv * __builtin_amdgcn_rcpf(1.f + __expf(-xv));
;           else if (act == 2) xv = 0.5f * xv * (1.f + erf_fast(xv * 0.70710678118654752f));
;           y[j] = xv;
;         }
;         *(uint2*)(p.P + (size_t)(brow + r) * NP + pn * 256 + c) = uint2{pack2(y[0], y[1]), pack2(y[2], y[3])};
;       }
;     });
	v_fmaak_f32 v185, v185, v181, 0x3fb5f0e3
	v_fmaak_f32 v186, v186, v182, 0x3fb5f0e3
	v_fmaak_f32 v187, v187, v183, 0x3fb5f0e3
	v_fmaak_f32 v184, v184, v180, 0xbe91a98e
	v_fmaak_f32 v185, v185, v181, 0xbe91a98e
	v_fmaak_f32 v186, v186, v182, 0xbe91a98e
	v_fmaak_f32 v187, v187, v183, 0xbe91a98e
	v_fmaak_f32 v184, v184, v180, 0x3e827906
	v_fmaak_f32 v185, v185, v181, 0x3e827906
	v_fmaak_f32 v186, v186, v182, 0x3e827906
	v_fmaak_f32 v187, v187, v183, 0x3e827906
	v_mul_f32_e32 v180, v180, v184
	v_mul_f32_e32 v181, v181, v185
	v_mul_f32_e32 v182, v182, v186
	v_mul_f32_e32 v183, v183, v187
	v_mul_f32_e64 v184, |v176|, |v176|
	v_mul_f32_e64 v185, |v177|, |v177|
	v_mul_f32_e64 v186, |v178|, |v178|
	v_mul_f32_e64 v187, |v179|, |v179|
	v_mul_f32_e32 v184, 0xbfb8aa3b, v184
	v_mul_f32_e32 v185, 0xbfb8aa3b, v185
	v_mul_f32_e32 v186, 0xbfb8aa3b, v186
	v_mul_f32_e32 v187, 0xbfb8aa3b, v187
	v_exp_f32_e32 v184, v184
	v_exp_f32_e32 v185, v185
	v_exp_f32_e32 v186, v186
	v_exp_f32_e32 v187, v187
	v_fma_f32 v180, -v184, v180, 1.0
	v_fma_f32 v181, -v185, v181, 1.0
	v_fma_f32 v182, -v186, v182, 1.0
	v_fma_f32 v183, -v187, v183, 1.0
	v_bfi_b32 v176, s10, v180, v176
	v_bfi_b32 v177, s10, v181, v177
	v_bfi_b32 v178, s10, v182, v178
	v_bfi_b32 v179, s10, v183, v179
	v_add_f32_e32 v176, 1.0, v176
	v_add_f32_e32 v177, 1.0, v177
	v_add_f32_e32 v178, 1.0, v178
	v_add_f32_e32 v179, 1.0, v179
	v_mul_f32_e32 v188, v188, v176
	v_mul_f32_e32 v189, v189, v177
	v_mul_f32_e32 v190, v190, v178
	v_mul_f32_e32 v191, v191, v179
	v_cvt_pk_bf16_f32 v146, v188, v189
	v_cvt_pk_bf16_f32 v147, v190, v191
	s_nop 1
	v_permlane16_swap_b32_e32 v140, v142
	v_permlane16_swap_b32_e32 v141, v143
	global_store_dwordx4 v[168:169], v[140:143], off offset:256 nt
	v_mul_f32_e32 v176, 0x3f3504f3, v12
	v_mul_f32_e32 v177, 0x3f3504f3, v13
	v_mul_f32_e32 v178, 0x3f3504f3, v14
	v_mul_f32_e32 v179, 0x3f3504f3, v15
	v_fma_f32 v180, |v176|, s9, 1.0
	v_fma_f32 v181, |v177|, s9, 1.0
	v_fma_f32 v182, |v178|, s9, 1.0
	v_fma_f32 v183, |v179|, s9, 1.0
	v_rcp_f32_e32 v180, v180
	v_rcp_f32_e32 v181, v181
	v_rcp_f32_e32 v182, v182
	v_rcp_f32_e32 v183, v183
	v_mul_f32_e32 v188, 0.5, v12
	v_mul_f32_e32 v189, 0.5, v13
	v_mul_f32_e32 v190, 0.5, v14
	v_mul_f32_e32 v191, 0.5, v15
	v_fmamk_f32 v184, v180, 0x3f87dc22, v206
	v_fmamk_f32 v185, v181, 0x3f87dc22, v206
	v_fmamk_f32 v186, v182, 0x3f87dc22, v206
	v_fmamk_f32 v187, v183, 0x3f87dc22, v206
	v_fmaak_f32 v184, v184, v180, 0x3fb5f0e3
	v_fmaak_f32 v185, v185, v181, 0x3fb5f0e3
	v_fmaak_f32 v186, v186, v182, 0x3fb5f0e3
	v_fmaak_f32 v187, v187, v183, 0x3fb5f0e3
	v_fmaak_f32 v184, v184, v180, 0xbe91a98e
	v_fmaak_f32 v185, v185, v181, 0xbe91a98e
	v_fmaak_f32 v186, v186, v182, 0xbe91a98e
	v_fmaak_f32 v187, v187, v183, 0xbe91a98e
	v_fmaak_f32 v184, v184, v180, 0x3e827906
	v_fmaak_f32 v185, v185, v181, 0x3e827906
	v_fmaak_f32 v186, v186, v182, 0x3e827906
	v_fmaak_f32 v187, v187, v183, 0x3e827906
	v_mul_f32_e32 v180, v180, v184
	v_mul_f32_e32 v181, v181, v185
	v_mul_f32_e32 v182, v182, v186
	v_mul_f32_e32 v183, v183, v187
	v_mul_f32_e64 v184, |v176|, |v176|
	v_mul_f32_e64 v185, |v177|, |v177|
	v_mul_f32_e64 v186, |v178|, |v178|
	v_mul_f32_e64 v187, |v179|, |v179|
	v_mul_f32_e32 v184, 0xbfb8aa3b, v184
	v_mul_f32_e32 v185, 0xbfb8aa3b, v185
	v_mul_f32_e32 v186, 0xbfb8aa3b, v186
	v_mul_f32_e32 v187, 0xbfb8aa3b, v187
	v_exp_f32_e32 v184, v184
	v_exp_f32_e32 v185, v185
	v_exp_f32_e32 v186, v186
	v_exp_f32_e32 v187, v187
	v_fma_f32 v180, -v184, v180, 1.0
	v_fma_f32 v181, -v185, v181, 1.0
	v_fma_f32 v182, -v186, v182, 1.0
	v_fma_f32 v183, -v187, v183, 1.0
	v_bfi_b32 v176, s10, v180, v176
	v_bfi_b32 v177, s10, v181, v177
	v_bfi_b32 v178, s10, v182, v178
	v_bfi_b32 v179, s10, v183, v179
	v_add_f32_e32 v176, 1.0, v176
	v_add_f32_e32 v177, 1.0, v177
	v_add_f32_e32 v178, 1.0, v178
	v_add_f32_e32 v179, 1.0, v179
	v_mul_f32_e32 v188, v188, v176
	v_mul_f32_e32 v189, v189, v177
	v_mul_f32_e32 v190, v190, v178
	v_mul_f32_e32 v191, v191, v179
	v_cvt_pk_bf16_f32 v148, v188, v189
	v_cvt_pk_bf16_f32 v149, v190, v191
	v_mul_f32_e32 v176, 0x3f3504f3, v8
	v_mul_f32_e32 v177, 0x3f3504f3, v9
	v_mul_f32_e32 v178, 0x3f3504f3, v10
	v_mul_f32_e32 v179, 0x3f3504f3, v11
	v_fma_f32 v180, |v176|, s9, 1.0
	v_fma_f32 v181, |v177|, s9, 1.0
	v_fma_f32 v182, |v178|, s9, 1.0
	v_fma_f32 v183, |v179|, s9, 1.0
	v_rcp_f32_e32 v180, v180
	v_rcp_f32_e32 v181, v181
	v_rcp_f32_e32 v182, v182
	v_rcp_f32_e32 v183, v183
	v_mul_f32_e32 v188, 0.5, v8
	v_mul_f32_e32 v189, 0.5, v9
	v_mul_f32_e32 v190, 0.5, v10
	v_mul_f32_e32 v191, 0.5, v11
	v_fmamk_f32 v184, v180, 0x3f87dc22, v206
	v_fmamk_f32 v185, v181, 0x3f87dc22, v206
	v_fmamk_f32 v186, v182, 0x3f87dc22, v206
	v_fmamk_f32 v187, v183, 0x3f87dc22, v206
	v_fmaak_f32 v184, v184, v180, 0x3fb5f0e3
	v_fmaak_f32 v185, v185, v181, 0x3fb5f0e3
	v_fmaak_f32 v186, v186, v182, 0x3fb5f0e3
	v_fmaak_f32 v187, v187, v183, 0x3fb5f0e3
	v_fmaak_f32 v184, v184, v180, 0xbe91a98e
	v_fmaak_f32 v185, v185, v181, 0xbe91a98e
	v_fmaak_f32 v186, v186, v182, 0xbe91a98e
	v_fmaak_f32 v187, v187, v183, 0xbe91a98e
	v_fmaak_f32 v184, v184, v180, 0x3e827906
	v_fmaak_f32 v185, v185, v181, 0x3e827906
	v_fmaak_f32 v186, v186, v182, 0x3e827906
	v_fmaak_f32 v187, v187, v183, 0x3e827906
	v_mul_f32_e32 v180, v180, v184
	v_mul_f32_e32 v181, v181, v185
	v_mul_f32_e32 v182, v182, v186
	v_mul_f32_e32 v183, v183, v187
	v_mul_f32_e64 v184, |v176|, |v176|
	v_mul_f32_e64 v185, |v177|, |v177|
	v_mul_f32_e64 v186, |v178|, |v178|
	v_mul_f32_e64 v187, |v179|, |v179|
	v_mul_f32_e32 v184, 0xbfb8aa3b, v184
	v_mul_f32_e32 v185, 0xbfb8aa3b, v185
	v_mul_f32_e32 v186, 0xbfb8aa3b, v186
	v_mul_f32_e32 v187, 0xbfb8aa3b, v187
	v_exp_f32_e32 v184, v184
; __device__ __forceinline__ unsigned pack2(float a, float b) { const f32x2_t v = {a, b}; const bf16x2_t r = __builtin_convertvector(v, bf16x2_t); return __builtin_bit_cast(unsigned, r); }
; __device__ __forceinline__ float erf_fast(float x) {
;   const float ax = fabsf(x);
;   const float t = __builtin_amdgcn_rcpf(fmaf(0.3275911f, ax, 1.f));
;   float y = fmaf(1.061405429f, t, -1.453152027f);
;   y = fmaf(y, t, 1.421413741f);
;   y = fmaf(y, t, -0.284496736f);
;   y = fmaf(y, t, 0.254829592f);
;   y = 1.f - y * t * __expf(-ax * ax);
;   return copysignf(y, x);
; }
; __device__ __forceinline__ void ph_proj(const Params& p, int l, char* shm) {
;     ...
;     gemm_tile8(p.H + (size_t)brow * DM, DM, W + (size_t)pn * 256 * DM, DM, DM, shm, [&](int r, int c, f32x4 v) {
;       if (pn == 34) {
;         *(f32x4*)(p.KW + (size_t)(brow + r) * 256 + c) = v;
;       } else {
;         float y[4];
; #pragma unroll
;         for (int j = 0; j < 4; ++j) {
;           float xv = v[j];
;           if (act == 1) xv = xv * __builtin_amdgcn_rcpf(1.f + __expf(-xv));
;           else if (act == 2) xv = 0.5f * xv * (1.f + erf_fast(xv * 0.70710678118654752f));
;           y[j] = xv;
;         }
;         *(uint2*)(p.P + (size_t)(brow + r) * NP + pn * 256 + c) = uint2{pack2(y[0], y[1]), pack2(y[2], y[3])};
;       }
;     });
	v_exp_f32_e32 v185, v185
	v_exp_f32_e32 v186, v186
	v_exp_f32_e32 v187, v187
	v_fma_f32 v180, -v184, v180, 1.0
	v_fma_f32 v181, -v185, v181, 1.0
	v_fma_f32 v182, -v186, v182, 1.0
	v_fma_f32 v183, -v187, v183, 1.0
	v_bfi_b32 v176, s10, v180, v176
	v_bfi_b32 v177, s10, v181, v177
	v_bfi_b32 v178, s10, v182, v178
	v_bfi_b32 v179, s10, v183, v179
	v_add_f32_e32 v176, 1.0, v176
	v_add_f32_e32 v177, 1.0, v177
	v_add_f32_e32 v178, 1.0, v178
	v_add_f32_e32 v179, 1.0, v179
	v_mul_f32_e32 v188, v188, v176
	v_mul_f32_e32 v189, v189, v177
	v_mul_f32_e32 v190, v190, v178
	v_mul_f32_e32 v191, v191, v179
	v_cvt_pk_bf16_f32 v150, v188, v189
	v_cvt_pk_bf16_f32 v151, v190, v191
	s_nop 1
	v_permlane16_swap_b32_e32 v144, v146
	v_permlane16_swap_b32_e32 v145, v147
	global_store_dwordx4 v[170:171], v[144:147], off offset:256 nt
	v_mul_f32_e32 v176, 0x3f3504f3, v4
	v_mul_f32_e32 v177, 0x3f3504f3, v5
	v_mul_f32_e32 v178, 0x3f3504f3, v6
	v_mul_f32_e32 v179, 0x3f3504f3, v7
	v_fma_f32 v180, |v176|, s9, 1.0
	v_fma_f32 v181, |v177|, s9, 1.0
	v_fma_f32 v182, |v178|, s9, 1.0
	v_fma_f32 v183, |v179|, s9, 1.0
	v_rcp_f32_e32 v180, v180
	v_rcp_f32_e32 v181, v181
	v_rcp_f32_e32 v182, v182
	v_rcp_f32_e32 v183, v183
	v_mul_f32_e32 v188, 0.5, v4
	v_mul_f32_e32 v189, 0.5, v5
	v_mul_f32_e32 v190, 0.5, v6
	v_mul_f32_e32 v191, 0.5, v7
	v_fmamk_f32 v184, v180, 0x3f87dc22, v206
	v_fmamk_f32 v185, v181, 0x3f87dc22, v206
	v_fmamk_f32 v186, v182, 0x3f87dc22, v206
	v_fmamk_f32 v187, v183, 0x3f87dc22, v206
	v_fmaak_f32 v184, v184, v180, 0x3fb5f0e3
	v_fmaak_f32 v185, v185, v181, 0x3fb5f0e3
	v_fmaak_f32 v186, v186, v182, 0x3fb5f0e3
	v_fmaak_f32 v187, v187, v183, 0x3fb5f0e3
	v_fmaak_f32 v184, v184, v180, 0xbe91a98e
	v_fmaak_f32 v185, v185, v181, 0xbe91a98e
	v_fmaak_f32 v186, v186, v182, 0xbe91a98e
	v_fmaak_f32 v187, v187, v183, 0xbe91a98e
	v_fmaak_f32 v184, v184, v180, 0x3e827906
	v_fmaak_f32 v185, v185, v181, 0x3e827906
	v_fmaak_f32 v186, v186, v182, 0x3e827906
	v_fmaak_f32 v187, v187, v183, 0x3e827906
	v_mul_f32_e32 v180, v180, v184
	v_mul_f32_e32 v181, v181, v185
	v_mul_f32_e32 v182, v182, v186
	v_mul_f32_e32 v183, v183, v187
	v_mul_f32_e64 v184, |v176|, |v176|
	v_mul_f32_e64 v185, |v177|, |v177|
	v_mul_f32_e64 v186, |v178|, |v178|
	v_mul_f32_e64 v187, |v179|, |v179|
	v_mul_f32_e32 v184, 0xbfb8aa3b, v184
	v_mul_f32_e32 v185, 0xbfb8aa3b, v185
	v_mul_f32_e32 v186, 0xbfb8aa3b, v186
	v_mul_f32_e32 v187, 0xbfb8aa3b, v187
	v_exp_f32_e32 v184, v184
	v_exp_f32_e32 v185, v185
	v_exp_f32_e32 v186, v186
	v_exp_f32_e32 v187, v187
	v_fma_f32 v180, -v184, v180, 1.0
	v_fma_f32 v181, -v185, v181, 1.0
	v_fma_f32 v182, -v186, v182, 1.0
	v_fma_f32 v183, -v187, v183, 1.0
	v_bfi_b32 v176, s10, v180, v176
	v_bfi_b32 v177, s10, v181, v177
	v_bfi_b32 v178, s10, v182, v178
	v_bfi_b32 v179, s10, v183, v179
	v_add_f32_e32 v176, 1.0, v176
	v_add_f32_e32 v177, 1.0, v177
	v_add_f32_e32 v178, 1.0, v178
	v_add_f32_e32 v179, 1.0, v179
	v_mul_f32_e32 v188, v188, v176
	v_mul_f32_e32 v189, v189, v177
	v_mul_f32_e32 v190, v190, v178
	v_mul_f32_e32 v191, v191, v179
	v_cvt_pk_bf16_f32 v140, v188, v189
	v_cvt_pk_bf16_f32 v141, v190, v191
	v_mul_f32_e32 v176, 0x3f3504f3, v0
	v_mul_f32_e32 v177, 0x3f3504f3, v1
	v_mul_f32_e32 v178, 0x3f3504f3, v2
	v_mul_f32_e32 v179, 0x3f3504f3, v3
	v_fma_f32 v180, |v176|, s9, 1.0
	v_fma_f32 v181, |v177|, s9, 1.0
	v_fma_f32 v182, |v178|, s9, 1.0
	v_fma_f32 v183, |v179|, s9, 1.0
	v_rcp_f32_e32 v180, v180
	v_rcp_f32_e32 v181, v181
	v_rcp_f32_e32 v182, v182
	v_rcp_f32_e32 v183, v183
	v_mul_f32_e32 v188, 0.5, v0
	v_mul_f32_e32 v189, 0.5, v1
	v_mul_f32_e32 v190, 0.5, v2
	v_mul_f32_e32 v191, 0.5, v3
	v_fmamk_f32 v184, v180, 0x3f87dc22, v206
	v_fmamk_f32 v185, v181, 0x3f87dc22, v206
	v_fmamk_f32 v186, v182, 0x3f87dc22, v206
	v_fmamk_f32 v187, v183, 0x3f87dc22, v206
	v_fmaak_f32 v184, v184, v180, 0x3fb5f0e3
	v_fmaak_f32 v185, v185, v181, 0x3fb5f0e3
	v_fmaak_f32 v186, v186, v182, 0x3fb5f0e3
	v_fmaak_f32 v187, v187, v183, 0x3fb5f0e3
	v_fmaak_f32 v184, v184, v180, 0xbe91a98e
	v_fmaak_f32 v185, v185, v181, 0xbe91a98e
	v_fmaak_f32 v186, v186, v182, 0xbe91a98e
	v_fmaak_f32 v187, v187, v183, 0xbe91a98e
	v_fmaak_f32 v184, v184, v180, 0x3e827906
	v_fmaak_f32 v185, v185, v181, 0x3e827906
	v_fmaak_f32 v186, v186, v182, 0x3e827906
	v_fmaak_f32 v187, v187, v183, 0x3e827906
	v_mul_f32_e32 v180, v180, v184
	v_mul_f32_e32 v181, v181, v185
	v_mul_f32_e32 v182, v182, v186
	v_mul_f32_e32 v183, v183, v187
	v_mul_f32_e64 v184, |v176|, |v176|
	v_mul_f32_e64 v185, |v177|, |v177|
	v_mul_f32_e64 v186, |v178|, |v178|
	v_mul_f32_e64 v187, |v179|, |v179|
	v_mul_f32_e32 v184, 0xbfb8aa3b, v184
	v_mul_f32_e32 v185, 0xbfb8aa3b, v185
	v_mul_f32_e32 v186, 0xbfb8aa3b, v186
	v_mul_f32_e32 v187, 0xbfb8aa3b, v187
	v_exp_f32_e32 v184, v184
	v_exp_f32_e32 v185, v185
	v_exp_f32_e32 v186, v186
	v_exp_f32_e32 v187, v187
	v_fma_f32 v180, -v184, v180, 1.0
	v_fma_f32 v181, -v185, v181, 1.0
	v_fma_f32 v182, -v186, v182, 1.0
	v_fma_f32 v183, -v187, v183, 1.0
	v_bfi_b32 v176, s10, v180, v176
	v_bfi_b32 v177, s10, v181, v177
	v_bfi_b32 v178, s10, v182, v178
	v_bfi_b32 v179, s10, v183, v179
	v_add_f32_e32 v176, 1.0, v176
	v_add_f32_e32 v177, 1.0, v177
	v_add_f32_e32 v178, 1.0, v178
	v_add_f32_e32 v179, 1.0, v179
	v_mul_f32_e32 v188, v188, v176
	v_mul_f32_e32 v189, v189, v177
	v_mul_f32_e32 v190, v190, v178
	v_mul_f32_e32 v191, v191, v179
	v_cvt_pk_bf16_f32 v142, v188, v189
	v_cvt_pk_bf16_f32 v143, v190, v191
	s_nop 1
	v_permlane16_swap_b32_e32 v148, v150
	v_permlane16_swap_b32_e32 v149, v151
	global_store_dwordx4 v[172:173], v[148:151], off offset:256 nt
	s_nop 1
	v_permlane16_swap_b32_e32 v140, v142
	v_permlane16_swap_b32_e32 v141, v143
	global_store_dwordx4 v[174:175], v[140:143], off offset:256 nt
	s_branch .LBB0_958
